# GEMM K-step: first fragment reads hoisted above DMA address computation, gemm24 loop also DMA-interleaved
# baseline (speedup 1.0000x reference)
; #define MFMA(a, b, c) __builtin_amdgcn_mfma_f32_32x32x16_bf16((a), (b), (c), 0, 0, 0)
;     ...
;   for (int s = 0; s < S; ++s) {
;     G_DMA(s + 1, cur ^ BUFB);
;     {
;       const char* Ab = smem + cur + fA;
;       const char* Bb = smem + cur + fB;
;       __builtin_amdgcn_sched_barrier(0);
; #pragma unroll
;       for (int kk = 0; kk < 4; ++kk) {
;         const int ko = (((kk * 2 + hh) ^ fsw) << 4);
;         bf16x8 af[2], wf[4];
;         af[0] = *(const bf16x8*)(Ab + ko); af[1] = *(const bf16x8*)(Ab + 4096 + ko);
; #pragma unroll
;         for (int ni = 0; ni < 4; ++ni) wf[ni] = *(const bf16x8*)(Bb + ni * 4096 + ko);
; #pragma unroll
;         for (int mi = 0; mi < 2; ++mi)
; #pragma unroll
;           for (int ni = 0; ni < 4; ++ni) acc[mi][ni] = MFMA(wf[ni], af[mi], acc[mi][ni]);
;         if (kk == 1) __builtin_amdgcn_sched_barrier(0);
;       }
;       __builtin_amdgcn_sched_barrier(0);
;     }
;     asm volatile("s_waitcnt vmcnt(0)" ::: "memory");
.LBB0_211:
	v_add3_u32 v244, s8, v144, v147
	v_add3_u32 v245, s8, v149, v147
	v_add_u32_e32 v187, v245, v148
	v_add_u32_e32 v208, v244, v148
	ds_read_b128 v[188:191], v187 offset:32768
	ds_read_b128 v[204:207], v208
	ds_read_b128 v[192:195], v187 offset:36864
	ds_read_b128 v[196:199], v187 offset:40960
	ds_read_b128 v[200:203], v187 offset:45056
	ds_read_b128 v[216:219], v208 offset:4096
	v_add_u32_e32 v209, v245, v145
	v_add_u32_e32 v215, v244, v145
	ds_read_b128 v[220:223], v209 offset:32768
	ds_read_b128 v[236:239], v215
	ds_read_b128 v[224:227], v209 offset:36864
	ds_read_b128 v[228:231], v209 offset:40960
	ds_read_b128 v[232:235], v209 offset:45056
	ds_read_b128 v[240:243], v215 offset:4096
	s_lshl_b32 s9, s7, 16
	s_and_b32 s9, s9, 0x200000
	s_add_i32 s9, s93, s9
	s_lshl_b32 s9, s9, 1
	s_and_b32 s28, s9, 0x700000
	s_xor_b32 s9, s8, 0x10000
	v_add_u32_e32 v128, s9, v150
	v_lshl_add_u64 v[160:161], v[136:137], 0, s[40:41]
	v_readfirstlane_b32 s22, v128
	v_add_u32_e32 v164, 0x2000, v128
	v_lshl_add_u64 v[162:163], v[160:161], 0, s[24:25]
	s_mov_b32 m0, s22
	v_readfirstlane_b32 s22, v164
	v_add_u32_e32 v164, 0x4000, v128
	global_load_lds_dwordx4 v[162:163], off
	s_waitcnt lgkmcnt(10)
	v_mfma_f32_32x32x16_bf16 v[112:127], v[188:191], v[204:207], v[112:127]
	s_waitcnt lgkmcnt(9)
	v_mfma_f32_32x32x16_bf16 v[96:111], v[192:195], v[204:207], v[96:111]
	v_lshl_add_u64 v[162:163], v[160:161], 0, s[42:43]
	s_mov_b32 m0, s22
	v_readfirstlane_b32 s22, v164
	global_load_lds_dwordx4 v[162:163], off
	s_waitcnt lgkmcnt(8)
	v_mfma_f32_32x32x16_bf16 v[80:95], v[196:199], v[204:207], v[80:95]
	s_waitcnt lgkmcnt(7)
	v_mfma_f32_32x32x16_bf16 v[64:79], v[200:203], v[204:207], v[64:79]
	v_lshl_add_u64 v[162:163], v[160:161], 0, s[44:45]
	s_mov_b32 m0, s22
	v_lshl_add_u64 v[158:159], v[138:139], 0, s[28:29]
	global_load_lds_dwordx4 v[162:163], off
	s_waitcnt lgkmcnt(6)
	v_mfma_f32_32x32x16_bf16 v[48:63], v[188:191], v[216:219], v[48:63]
	v_mfma_f32_32x32x16_bf16 v[32:47], v[192:195], v[216:219], v[32:47]
	v_add_u32_e32 v162, 0x6000, v128
	v_lshl_add_u64 v[160:161], v[160:161], 0, s[46:47]
	v_readfirstlane_b32 s22, v162
	v_add_u32_e32 v162, 0x8000, v128
	s_mov_b32 m0, s22
	v_lshl_add_u64 v[158:159], v[158:159], 0, s[40:41]
	v_readfirstlane_b32 s22, v162
	v_add_u32_e32 v162, 0xa000, v128
	global_load_lds_dwordx4 v[160:161], off
	v_mfma_f32_32x32x16_bf16 v[16:31], v[196:199], v[216:219], v[16:31]
	v_mfma_f32_32x32x16_bf16 v[0:15], v[200:203], v[216:219], v[0:15]
	v_lshl_add_u64 v[160:161], v[158:159], 0, s[48:49]
	s_mov_b32 m0, s22
	v_readfirstlane_b32 s22, v162
	v_add_u32_e32 v162, 0xc000, v128
	global_load_lds_dwordx4 v[160:161], off
	v_add_u32_e32 v187, v245, v141
	v_add_u32_e32 v208, v244, v141
	ds_read_b128 v[188:191], v187 offset:32768
	ds_read_b128 v[204:207], v208
	ds_read_b128 v[192:195], v187 offset:36864
	ds_read_b128 v[196:199], v187 offset:40960
	ds_read_b128 v[200:203], v187 offset:45056
	ds_read_b128 v[216:219], v208 offset:4096
	s_waitcnt lgkmcnt(10)
	v_mfma_f32_32x32x16_bf16 v[112:127], v[220:223], v[236:239], v[112:127]
	s_waitcnt lgkmcnt(9)
	v_mfma_f32_32x32x16_bf16 v[96:111], v[224:227], v[236:239], v[96:111]
	v_lshl_add_u64 v[160:161], v[158:159], 0, s[50:51]
	s_mov_b32 m0, s22
	v_readfirstlane_b32 s22, v162
	v_add_u32_e32 v128, 0xe000, v128
	global_load_lds_dwordx4 v[160:161], off
	s_waitcnt lgkmcnt(8)
	v_mfma_f32_32x32x16_bf16 v[80:95], v[228:231], v[236:239], v[80:95]
	s_waitcnt lgkmcnt(7)
	v_mfma_f32_32x32x16_bf16 v[64:79], v[232:235], v[236:239], v[64:79]
	v_lshl_add_u64 v[160:161], v[158:159], 0, s[52:53]
	s_mov_b32 m0, s22
	v_readfirstlane_b32 s22, v128
	global_load_lds_dwordx4 v[160:161], off
	s_waitcnt lgkmcnt(6)
	v_mfma_f32_32x32x16_bf16 v[48:63], v[220:223], v[240:243], v[48:63]
	v_mfma_f32_32x32x16_bf16 v[32:47], v[224:227], v[240:243], v[32:47]
	v_lshl_add_u64 v[158:159], v[158:159], 0, s[54:55]
	s_mov_b32 m0, s22
	s_add_i32 s8, s8, 0
	global_load_lds_dwordx4 v[158:159], off
	v_mfma_f32_32x32x16_bf16 v[16:31], v[228:231], v[240:243], v[16:31]
	v_mfma_f32_32x32x16_bf16 v[0:15], v[232:235], v[240:243], v[0:15]
	v_add_u32_e32 v209, v245, v140
	v_add_u32_e32 v215, v244, v140
	ds_read_b128 v[220:223], v209 offset:32768
	ds_read_b128 v[236:239], v215
	ds_read_b128 v[224:227], v209 offset:36864
	ds_read_b128 v[228:231], v209 offset:40960
	ds_read_b128 v[232:235], v209 offset:45056
	ds_read_b128 v[240:243], v215 offset:4096
	s_waitcnt lgkmcnt(10)
	v_mfma_f32_32x32x16_bf16 v[112:127], v[188:191], v[204:207], v[112:127]
	s_waitcnt lgkmcnt(9)
	v_mfma_f32_32x32x16_bf16 v[96:111], v[192:195], v[204:207], v[96:111]
	s_waitcnt lgkmcnt(8)
	v_mfma_f32_32x32x16_bf16 v[80:95], v[196:199], v[204:207], v[80:95]
	s_waitcnt lgkmcnt(7)
	v_mfma_f32_32x32x16_bf16 v[64:79], v[200:203], v[204:207], v[64:79]
	s_waitcnt lgkmcnt(6)
	v_mfma_f32_32x32x16_bf16 v[48:63], v[188:191], v[216:219], v[48:63]
	v_mfma_f32_32x32x16_bf16 v[32:47], v[192:195], v[216:219], v[32:47]
	v_mfma_f32_32x32x16_bf16 v[16:31], v[196:199], v[216:219], v[16:31]
	v_mfma_f32_32x32x16_bf16 v[0:15], v[200:203], v[216:219], v[0:15]
	s_waitcnt lgkmcnt(4)
	v_mfma_f32_32x32x16_bf16 v[112:127], v[220:223], v[236:239], v[112:127]
	s_waitcnt lgkmcnt(3)
	v_mfma_f32_32x32x16_bf16 v[96:111], v[224:227], v[236:239], v[96:111]
	s_waitcnt lgkmcnt(2)
	v_mfma_f32_32x32x16_bf16 v[80:95], v[228:231], v[236:239], v[80:95]
	s_waitcnt lgkmcnt(1)
	v_mfma_f32_32x32x16_bf16 v[64:79], v[232:235], v[236:239], v[64:79]
	s_waitcnt lgkmcnt(0)
	v_mfma_f32_32x32x16_bf16 v[48:63], v[220:223], v[240:243], v[48:63]
	v_mfma_f32_32x32x16_bf16 v[32:47], v[224:227], v[240:243], v[32:47]
	v_mfma_f32_32x32x16_bf16 v[16:31], v[228:231], v[240:243], v[16:31]
	v_mfma_f32_32x32x16_bf16 v[0:15], v[232:235], v[240:243], v[0:15]
	s_waitcnt vmcnt(0)
	s_waitcnt lgkmcnt(0)
	s_barrier
; #define MFMA(a, b, c) __builtin_amdgcn_mfma_f32_32x32x16_bf16((a), (b), (c), 0, 0, 0)
;     ...
;   for (int s = 0; s < S; ++s) {
;     G_DMA(s + 1, cur ^ BUFB);
;     {
;       const char* Ab = smem + cur + fA;
;       const char* Bb = smem + cur + fB;
;       __builtin_amdgcn_sched_barrier(0);
; #pragma unroll
;       for (int kk = 0; kk < 4; ++kk) {
;         const int ko = (((kk * 2 + hh) ^ fsw) << 4);
;         bf16x8 af[2], wf[4];
;         af[0] = *(const bf16x8*)(Ab + ko); af[1] = *(const bf16x8*)(Ab + 4096 + ko);
; #pragma unroll
;         for (int ni = 0; ni < 4; ++ni) wf[ni] = *(const bf16x8*)(Bb + ni * 4096 + ko);
; #pragma unroll
;         for (int mi = 0; mi < 2; ++mi)
; #pragma unroll
;           for (int ni = 0; ni < 4; ++ni) acc[mi][ni] = MFMA(wf[ni], af[mi], acc[mi][ni]);
;         if (kk == 1) __builtin_amdgcn_sched_barrier(0);
;       }
;       __builtin_amdgcn_sched_barrier(0);
;     }
;     asm volatile("s_waitcnt vmcnt(0)" ::: "memory");
	s_add_u32 s40, s40, 0x80
	s_addc_u32 s41, s41, 0
	s_add_i32 s7, s7, 1
	s_cmpk_eq_i32 s40, 0xf80
	s_mov_b32 s8, s9
	s_cbranch_scc0 .LBB0_211
	s_mov_b64 s[8:9], 0xf80
	v_readfirstlane_b32 s7, v150
	v_lshl_add_u64 v[136:137], v[132:133], 0, s[8:9]
	s_mov_b32 m0, s7
	s_mov_b64 s[22:23], 0x40f80
	v_readfirstlane_b32 s7, v151
	global_load_lds_dwordx4 v[136:137], off
	v_lshl_add_u64 v[136:137], v[132:133], 0, s[22:23]
	s_mov_b32 m0, s7
	s_mov_b64 s[24:25], 0x80f80
	v_readfirstlane_b32 s7, v152
	global_load_lds_dwordx4 v[136:137], off
	v_lshl_add_u64 v[136:137], v[132:133], 0, s[24:25]
	s_mov_b32 m0, s7
	s_mov_b64 s[40:41], 0xc0f80
	v_readfirstlane_b32 s7, v153
	global_load_lds_dwordx4 v[136:137], off
	v_lshl_add_u64 v[132:133], v[132:133], 0, s[40:41]
	s_mov_b32 m0, s7
	v_readfirstlane_b32 s7, v154
	global_load_lds_dwordx4 v[132:133], off
	v_lshl_add_u64 v[132:133], v[134:135], 0, s[8:9]
	s_mov_b32 m0, s7
	v_readfirstlane_b32 s7, v155
	global_load_lds_dwordx4 v[132:133], off
	v_lshl_add_u64 v[132:133], v[134:135], 0, s[22:23]
	s_mov_b32 m0, s7
	v_readfirstlane_b32 s7, v156
	global_load_lds_dwordx4 v[132:133], off
	v_lshl_add_u64 v[132:133], v[134:135], 0, s[24:25]
	s_mov_b32 m0, s7
	v_readfirstlane_b32 s7, v157
	global_load_lds_dwordx4 v[132:133], off
	v_lshl_add_u64 v[132:133], v[134:135], 0, s[40:41]
	s_mov_b32 m0, s7
	s_add_i32 s28, s6, -1
	global_load_lds_dwordx4 v[132:133], off
	s_lshl_b64 s[8:9], s[28:29], 25
	v_readlane_b32 s22, v253, 39
	v_readlane_b32 s23, v253, 40
	s_add_u32 s40, s22, s8
	v_lshlrev_b32_e32 v132, 6, v146
	s_addc_u32 s41, s23, s9
	v_readlane_b32 s8, v253, 27
	v_ashrrev_i32_e32 v133, 31, v132
	v_readlane_b32 s9, v253, 28
	s_add_i32 s7, 0, 0x10000
	v_lshlrev_b32_e32 v128, 3, v142
	v_lshl_add_u64 v[162:163], v[132:133], 0, s[8:9]
	v_lshlrev_b32_e32 v132, 4, v142
	v_mov_b32_e32 v133, v129
	v_or_b32_e32 v162, v162, v143
	v_lshl_add_u64 v[132:133], s[40:41], 0, v[132:133]
	v_add3_u32 v138, s7, v144, v147
	v_add3_u32 v139, s7, v149, v147
	v_add_u32_e32 v187, v139, v148
	v_add_u32_e32 v208, v138, v148
	ds_read_b128 v[134:137], v187 offset:32768
	ds_read_b128 v[146:149], v208
	ds_read_b128 v[150:153], v187 offset:36864
	ds_read_b128 v[154:157], v187 offset:40960
	ds_read_b128 v[158:161], v187 offset:45056
	ds_read_b128 v[188:191], v208 offset:4096
	v_add_u32_e32 v209, v139, v145
	v_add_u32_e32 v215, v138, v145
	ds_read_b128 v[192:195], v209 offset:32768
	ds_read_b128 v[216:219], v215
	ds_read_b128 v[196:199], v209 offset:36864
	ds_read_b128 v[200:203], v209 offset:40960
	ds_read_b128 v[204:207], v209 offset:45056
	ds_read_b128 v[220:223], v215 offset:4096
	s_waitcnt lgkmcnt(10)
	v_mfma_f32_32x32x16_bf16 v[112:127], v[134:137], v[146:149], v[112:127]
	s_waitcnt lgkmcnt(9)
	v_mfma_f32_32x32x16_bf16 v[96:111], v[150:153], v[146:149], v[96:111]
	s_waitcnt lgkmcnt(8)
	v_mfma_f32_32x32x16_bf16 v[80:95], v[154:157], v[146:149], v[80:95]
	s_waitcnt lgkmcnt(7)
	v_mfma_f32_32x32x16_bf16 v[64:79], v[158:161], v[146:149], v[64:79]
	s_waitcnt lgkmcnt(6)
	v_mfma_f32_32x32x16_bf16 v[48:63], v[134:137], v[188:191], v[48:63]
	v_mfma_f32_32x32x16_bf16 v[32:47], v[150:153], v[188:191], v[32:47]
	v_mfma_f32_32x32x16_bf16 v[16:31], v[154:157], v[188:191], v[16:31]
	v_mfma_f32_32x32x16_bf16 v[0:15], v[158:161], v[188:191], v[0:15]
	v_add_u32_e32 v187, v139, v141
	v_add_u32_e32 v208, v138, v141
	ds_read_b128 v[134:137], v187 offset:32768
	ds_read_b128 v[146:149], v208
	ds_read_b128 v[150:153], v187 offset:36864
	ds_read_b128 v[154:157], v187 offset:40960
	ds_read_b128 v[158:161], v187 offset:45056
	ds_read_b128 v[188:191], v208 offset:4096
	s_waitcnt lgkmcnt(10)
	v_mfma_f32_32x32x16_bf16 v[112:127], v[192:195], v[216:219], v[112:127]
	s_waitcnt lgkmcnt(9)
	v_mfma_f32_32x32x16_bf16 v[96:111], v[196:199], v[216:219], v[96:111]
	s_waitcnt lgkmcnt(8)
	v_mfma_f32_32x32x16_bf16 v[80:95], v[200:203], v[216:219], v[80:95]
	s_waitcnt lgkmcnt(7)
	v_mfma_f32_32x32x16_bf16 v[64:79], v[204:207], v[216:219], v[64:79]
	s_waitcnt lgkmcnt(6)
	v_mfma_f32_32x32x16_bf16 v[48:63], v[192:195], v[220:223], v[48:63]
	v_mfma_f32_32x32x16_bf16 v[32:47], v[196:199], v[220:223], v[32:47]
	v_mfma_f32_32x32x16_bf16 v[16:31], v[200:203], v[220:223], v[16:31]
	v_mfma_f32_32x32x16_bf16 v[0:15], v[204:207], v[220:223], v[0:15]
	v_add_u32_e32 v209, v139, v140
	v_add_u32_e32 v215, v138, v140
	ds_read_b128 v[192:195], v209 offset:32768
	ds_read_b128 v[216:219], v215
	ds_read_b128 v[196:199], v209 offset:36864
	ds_read_b128 v[200:203], v209 offset:40960
	ds_read_b128 v[204:207], v209 offset:45056
	ds_read_b128 v[220:223], v215 offset:4096
	s_waitcnt lgkmcnt(10)
	v_mfma_f32_32x32x16_bf16 v[112:127], v[134:137], v[146:149], v[112:127]
	s_waitcnt lgkmcnt(9)
	v_mfma_f32_32x32x16_bf16 v[96:111], v[150:153], v[146:149], v[96:111]
	s_waitcnt lgkmcnt(8)
	v_mfma_f32_32x32x16_bf16 v[80:95], v[154:157], v[146:149], v[80:95]
	s_waitcnt lgkmcnt(7)
	v_mfma_f32_32x32x16_bf16 v[64:79], v[158:161], v[146:149], v[64:79]
	s_waitcnt lgkmcnt(6)
	v_mfma_f32_32x32x16_bf16 v[48:63], v[134:137], v[188:191], v[48:63]
	v_mfma_f32_32x32x16_bf16 v[32:47], v[150:153], v[188:191], v[32:47]
	v_mfma_f32_32x32x16_bf16 v[16:31], v[154:157], v[188:191], v[16:31]
	v_mfma_f32_32x32x16_bf16 v[0:15], v[158:161], v[188:191], v[0:15]
	s_waitcnt lgkmcnt(4)
	v_mfma_f32_32x32x16_bf16 v[112:127], v[192:195], v[216:219], v[112:127]
	s_waitcnt lgkmcnt(3)
	v_mfma_f32_32x32x16_bf16 v[96:111], v[196:199], v[216:219], v[96:111]
	s_waitcnt lgkmcnt(2)
	v_mfma_f32_32x32x16_bf16 v[80:95], v[200:203], v[216:219], v[80:95]
	s_waitcnt lgkmcnt(1)
	v_mfma_f32_32x32x16_bf16 v[64:79], v[204:207], v[216:219], v[64:79]
	s_waitcnt lgkmcnt(0)
; DI unsigned pack2(float a, float b) { f32x2_t v = {a, b}; return __builtin_bit_cast(unsigned, __builtin_convertvector(v, bf16x2_t)); }
; DI float lo2f(unsigned v) { return __uint_as_float(v << 16); }
; DI float hi2f(unsigned v) { return __uint_as_float(v & 0xffff0000u); }
;     ...
;             } else if (MODE == 1) {
; #pragma unroll
;               for (int gp = 0; gp < 2; ++gp) {
;                 const int g0 = 2 * gp;
;                 const int nb_ = nt * 256 + wn * 128 + ni * 32 + 8 * g0;
;                 const uint2 ra = *(const uint2*)(res + m * 1024 + nb_ + 4 * hh), rb = *(const uint2*)(res + m * 1024 + nb_ + 8 + 4 * hh);
;                 uint2 pa, pb;
;                 pa.x = pack2(alpha * lo2f(ra.x) + acc[mi][ni][4 * g0], alpha * hi2f(ra.x) + acc[mi][ni][4 * g0 + 1]);
;                 pa.y = pack2(alpha * lo2f(ra.y) + acc[mi][ni][4 * g0 + 2], alpha * hi2f(ra.y) + acc[mi][ni][4 * g0 + 3]);
;                 pb.x = pack2(alpha * lo2f(rb.x) + acc[mi][ni][4 * g0 + 4], alpha * hi2f(rb.x) + acc[mi][ni][4 * g0 + 5]);
;                 pb.y = pack2(alpha * lo2f(rb.y) + acc[mi][ni][4 * g0 + 6], alpha * hi2f(rb.y) + acc[mi][ni][4 * g0 + 7]);
;                 { auto rx = __builtin_amdgcn_permlane32_swap(pa.x, pb.x, false, false); pa.x = rx[0]; pb.x = rx[1]; }
;                 { auto ry = __builtin_amdgcn_permlane32_swap(pa.y, pb.y, false, false); pa.y = ry[0]; pb.y = ry[1]; }
;                 *(uint4*)(outp + m * 1024 + nb_ + 8 * hh) = make_uint4(pa.x, pa.y, pb.x, pb.y);
;               }
	v_mfma_f32_32x32x16_bf16 v[48:63], v[192:195], v[220:223], v[48:63]
	v_mfma_f32_32x32x16_bf16 v[32:47], v[196:199], v[220:223], v[32:47]
	v_mfma_f32_32x32x16_bf16 v[16:31], v[200:203], v[220:223], v[16:31]
	v_mfma_f32_32x32x16_bf16 v[0:15], v[204:207], v[220:223], v[0:15]
	s_waitcnt vmcnt(0)
	v_lshlrev_b64 v[136:137], 11, v[162:163]
	v_lshl_add_u64 v[138:139], s[40:41], 0, v[136:137]
	v_lshl_add_u64 v[144:145], v[132:133], 0, v[136:137]
	v_readlane_b32 s7, v251, 32
	s_lshl_b32 s7, s7, 1
	v_mov_b32_e32 v135, v129
	v_lshl_or_b32 v134, v131, 8, s7
	v_lshl_add_u64 v[138:139], v[138:139], 0, v[134:135]
	v_lshl_add_u64 v[138:139], v[138:139], 0, v[128:129]
	global_load_dwordx2 v[140:141], v[138:139], off
	global_load_dwordx2 v[142:143], v[138:139], off offset:16
	s_mov_b32 s8, 0x3fd744fd
	s_waitcnt vmcnt(0)
	v_lshlrev_b32_e32 v146, 16, v140
	v_and_b32_e32 v147, 0xffff0000, v140
	v_pk_fma_f32 v[112:113], v[146:147], s[8:9], v[112:113] op_sel_hi:[1,0,1]
	s_nop 0
	v_cvt_pk_bf16_f32 v140, v112, v113
	v_lshlrev_b32_e32 v112, 16, v141
	v_and_b32_e32 v113, 0xffff0000, v141
	v_pk_fma_f32 v[112:113], v[112:113], s[8:9], v[114:115] op_sel_hi:[1,0,1]
	s_nop 0
	v_cvt_pk_bf16_f32 v141, v112, v113
	v_lshlrev_b32_e32 v112, 16, v142
	v_and_b32_e32 v113, 0xffff0000, v142
	v_pk_fma_f32 v[112:113], v[112:113], s[8:9], v[116:117] op_sel_hi:[1,0,1]
	s_nop 0
	v_cvt_pk_bf16_f32 v142, v112, v113
	v_lshlrev_b32_e32 v112, 16, v143
	v_and_b32_e32 v113, 0xffff0000, v143
	v_pk_fma_f32 v[112:113], v[112:113], s[8:9], v[118:119] op_sel_hi:[1,0,1]
	v_permlane32_swap_b32_e32 v140, v142
	v_cvt_pk_bf16_f32 v143, v112, v113
	s_nop 1
	v_permlane32_swap_b32_e32 v141, v143
	v_lshl_add_u64 v[112:113], v[144:145], 0, v[134:135]
	global_store_dwordx4 v[112:113], v[140:143], off
	global_load_dwordx2 v[114:115], v[138:139], off offset:32
	global_load_dwordx2 v[116:117], v[138:139], off offset:48
	s_waitcnt vmcnt(1)
	v_lshlrev_b32_e32 v118, 16, v114
	v_and_b32_e32 v119, 0xffff0000, v114
	v_pk_fma_f32 v[118:119], v[118:119], s[8:9], v[120:121] op_sel_hi:[1,0,1]
	s_nop 0
	v_cvt_pk_bf16_f32 v114, v118, v119
	v_lshlrev_b32_e32 v118, 16, v115
	v_and_b32_e32 v119, 0xffff0000, v115
	v_pk_fma_f32 v[118:119], v[118:119], s[8:9], v[122:123] op_sel_hi:[1,0,1]
	s_nop 0
	v_cvt_pk_bf16_f32 v115, v118, v119
	s_waitcnt vmcnt(0)
	v_lshlrev_b32_e32 v118, 16, v116
	v_and_b32_e32 v119, 0xffff0000, v116
	v_pk_fma_f32 v[118:119], v[118:119], s[8:9], v[124:125] op_sel_hi:[1,0,1]
	s_nop 0
	v_cvt_pk_bf16_f32 v116, v118, v119
	v_lshlrev_b32_e32 v118, 16, v117
	v_and_b32_e32 v119, 0xffff0000, v117
	v_pk_fma_f32 v[118:119], v[118:119], s[8:9], v[126:127] op_sel_hi:[1,0,1]
	v_permlane32_swap_b32_e32 v114, v116
	v_cvt_pk_bf16_f32 v117, v118, v119
	s_nop 1
	v_permlane32_swap_b32_e32 v115, v117
	global_store_dwordx4 v[112:113], v[114:117], off offset:32
	global_load_dwordx2 v[114:115], v[138:139], off offset:64
	s_nop 0
	global_load_dwordx2 v[116:117], v[138:139], off offset:80
	s_waitcnt vmcnt(1)
	v_lshlrev_b32_e32 v118, 16, v114
	v_and_b32_e32 v119, 0xffff0000, v114
	v_lshlrev_b32_e32 v114, 16, v115
	v_and_b32_e32 v115, 0xffff0000, v115
	v_pk_fma_f32 v[96:97], v[118:119], s[8:9], v[96:97] op_sel_hi:[1,0,1]
	v_pk_fma_f32 v[98:99], v[114:115], s[8:9], v[98:99] op_sel_hi:[1,0,1]
	v_cvt_pk_bf16_f32 v96, v96, v97
	v_cvt_pk_bf16_f32 v97, v98, v99
	s_waitcnt vmcnt(0)
	v_lshlrev_b32_e32 v98, 16, v116
	v_and_b32_e32 v99, 0xffff0000, v116
	v_pk_fma_f32 v[98:99], v[98:99], s[8:9], v[100:101] op_sel_hi:[1,0,1]
	v_lshlrev_b32_e32 v100, 16, v117
	v_and_b32_e32 v101, 0xffff0000, v117
	v_pk_fma_f32 v[100:101], v[100:101], s[8:9], v[102:103] op_sel_hi:[1,0,1]
	v_cvt_pk_bf16_f32 v98, v98, v99
	v_cvt_pk_bf16_f32 v99, v100, v101
	s_nop 0
	v_permlane32_swap_b32_e32 v96, v98
	v_permlane32_swap_b32_e32 v97, v99
	global_store_dwordx4 v[112:113], v[96:99], off offset:64
	global_load_dwordx2 v[96:97], v[138:139], off offset:96
	s_nop 0
	global_load_dwordx2 v[98:99], v[138:139], off offset:112
	s_waitcnt vmcnt(1)
	v_lshlrev_b32_e32 v100, 16, v96
	v_and_b32_e32 v101, 0xffff0000, v96
	v_pk_fma_f32 v[100:101], v[100:101], s[8:9], v[104:105] op_sel_hi:[1,0,1]
	s_nop 0
	v_cvt_pk_bf16_f32 v96, v100, v101
	v_lshlrev_b32_e32 v100, 16, v97
	v_and_b32_e32 v101, 0xffff0000, v97
	v_pk_fma_f32 v[100:101], v[100:101], s[8:9], v[106:107] op_sel_hi:[1,0,1]
	s_nop 0
	v_cvt_pk_bf16_f32 v97, v100, v101
	s_waitcnt vmcnt(0)
	v_lshlrev_b32_e32 v100, 16, v98
	v_and_b32_e32 v101, 0xffff0000, v98
	v_pk_fma_f32 v[100:101], v[100:101], s[8:9], v[108:109] op_sel_hi:[1,0,1]
	s_nop 0
	v_cvt_pk_bf16_f32 v98, v100, v101
	v_lshlrev_b32_e32 v100, 16, v99
	v_and_b32_e32 v101, 0xffff0000, v99
	v_pk_fma_f32 v[100:101], v[100:101], s[8:9], v[110:111] op_sel_hi:[1,0,1]
	v_permlane32_swap_b32_e32 v96, v98
	v_cvt_pk_bf16_f32 v99, v100, v101
	s_nop 1
	v_permlane32_swap_b32_e32 v97, v99
	global_store_dwordx4 v[112:113], v[96:99], off offset:96
	global_load_dwordx2 v[96:97], v[138:139], off offset:128
	s_nop 0
	global_load_dwordx2 v[98:99], v[138:139], off offset:144
	s_waitcnt vmcnt(1)
	v_lshlrev_b32_e32 v100, 16, v96
	v_and_b32_e32 v101, 0xffff0000, v96
	v_lshlrev_b32_e32 v96, 16, v97
	v_and_b32_e32 v97, 0xffff0000, v97
	v_pk_fma_f32 v[80:81], v[100:101], s[8:9], v[80:81] op_sel_hi:[1,0,1]
	v_pk_fma_f32 v[82:83], v[96:97], s[8:9], v[82:83] op_sel_hi:[1,0,1]
	v_cvt_pk_bf16_f32 v80, v80, v81
	v_cvt_pk_bf16_f32 v81, v82, v83
	s_waitcnt vmcnt(0)
; DI unsigned pack2(float a, float b) { f32x2_t v = {a, b}; return __builtin_bit_cast(unsigned, __builtin_convertvector(v, bf16x2_t)); }
; DI float lo2f(unsigned v) { return __uint_as_float(v << 16); }
; DI float hi2f(unsigned v) { return __uint_as_float(v & 0xffff0000u); }
;     ...
;             } else if (MODE == 1) {
; #pragma unroll
;               for (int gp = 0; gp < 2; ++gp) {
;                 const int g0 = 2 * gp;
;                 const int nb_ = nt * 256 + wn * 128 + ni * 32 + 8 * g0;
;                 const uint2 ra = *(const uint2*)(res + m * 1024 + nb_ + 4 * hh), rb = *(const uint2*)(res + m * 1024 + nb_ + 8 + 4 * hh);
;                 uint2 pa, pb;
;                 pa.x = pack2(alpha * lo2f(ra.x) + acc[mi][ni][4 * g0], alpha * hi2f(ra.x) + acc[mi][ni][4 * g0 + 1]);
;                 pa.y = pack2(alpha * lo2f(ra.y) + acc[mi][ni][4 * g0 + 2], alpha * hi2f(ra.y) + acc[mi][ni][4 * g0 + 3]);
;                 pb.x = pack2(alpha * lo2f(rb.x) + acc[mi][ni][4 * g0 + 4], alpha * hi2f(rb.x) + acc[mi][ni][4 * g0 + 5]);
;                 pb.y = pack2(alpha * lo2f(rb.y) + acc[mi][ni][4 * g0 + 6], alpha * hi2f(rb.y) + acc[mi][ni][4 * g0 + 7]);
;                 { auto rx = __builtin_amdgcn_permlane32_swap(pa.x, pb.x, false, false); pa.x = rx[0]; pb.x = rx[1]; }
;                 { auto ry = __builtin_amdgcn_permlane32_swap(pa.y, pb.y, false, false); pa.y = ry[0]; pb.y = ry[1]; }
;                 *(uint4*)(outp + m * 1024 + nb_ + 8 * hh) = make_uint4(pa.x, pa.y, pb.x, pb.y);
;               }
	v_lshlrev_b32_e32 v82, 16, v98
	v_and_b32_e32 v83, 0xffff0000, v98
	v_pk_fma_f32 v[82:83], v[82:83], s[8:9], v[84:85] op_sel_hi:[1,0,1]
	v_lshlrev_b32_e32 v84, 16, v99
	v_and_b32_e32 v85, 0xffff0000, v99
	v_pk_fma_f32 v[84:85], v[84:85], s[8:9], v[86:87] op_sel_hi:[1,0,1]
	v_cvt_pk_bf16_f32 v82, v82, v83
	v_cvt_pk_bf16_f32 v83, v84, v85
	s_nop 0
	v_permlane32_swap_b32_e32 v80, v82
	v_permlane32_swap_b32_e32 v81, v83
	global_store_dwordx4 v[112:113], v[80:83], off offset:128
	global_load_dwordx2 v[80:81], v[138:139], off offset:160
	s_nop 0
	global_load_dwordx2 v[82:83], v[138:139], off offset:176
	s_waitcnt vmcnt(1)
	v_lshlrev_b32_e32 v84, 16, v80
	v_and_b32_e32 v85, 0xffff0000, v80
	v_pk_fma_f32 v[84:85], v[84:85], s[8:9], v[88:89] op_sel_hi:[1,0,1]
	s_nop 0
	v_cvt_pk_bf16_f32 v80, v84, v85
	v_lshlrev_b32_e32 v84, 16, v81
	v_and_b32_e32 v85, 0xffff0000, v81
	v_pk_fma_f32 v[84:85], v[84:85], s[8:9], v[90:91] op_sel_hi:[1,0,1]
	s_nop 0
	v_cvt_pk_bf16_f32 v81, v84, v85
	s_waitcnt vmcnt(0)
	v_lshlrev_b32_e32 v84, 16, v82
	v_and_b32_e32 v85, 0xffff0000, v82
	v_pk_fma_f32 v[84:85], v[84:85], s[8:9], v[92:93] op_sel_hi:[1,0,1]
	s_nop 0
	v_cvt_pk_bf16_f32 v82, v84, v85
	v_lshlrev_b32_e32 v84, 16, v83
	v_and_b32_e32 v85, 0xffff0000, v83
	v_pk_fma_f32 v[84:85], v[84:85], s[8:9], v[94:95] op_sel_hi:[1,0,1]
	v_permlane32_swap_b32_e32 v80, v82
	v_cvt_pk_bf16_f32 v83, v84, v85
	s_nop 1
	v_permlane32_swap_b32_e32 v81, v83
	global_store_dwordx4 v[112:113], v[80:83], off offset:160
	global_load_dwordx2 v[80:81], v[138:139], off offset:192
	s_nop 0
	global_load_dwordx2 v[82:83], v[138:139], off offset:208
	v_or_b32_e32 v136, 0x10000, v136
	s_waitcnt vmcnt(1)
	v_lshlrev_b32_e32 v84, 16, v80
	v_and_b32_e32 v85, 0xffff0000, v80
	v_lshlrev_b32_e32 v80, 16, v81
	v_and_b32_e32 v81, 0xffff0000, v81
	v_pk_fma_f32 v[64:65], v[84:85], s[8:9], v[64:65] op_sel_hi:[1,0,1]
	v_pk_fma_f32 v[66:67], v[80:81], s[8:9], v[66:67] op_sel_hi:[1,0,1]
	v_cvt_pk_bf16_f32 v64, v64, v65
	v_cvt_pk_bf16_f32 v65, v66, v67
	s_waitcnt vmcnt(0)
	v_lshlrev_b32_e32 v66, 16, v82
	v_and_b32_e32 v67, 0xffff0000, v82
	v_pk_fma_f32 v[66:67], v[66:67], s[8:9], v[68:69] op_sel_hi:[1,0,1]
	v_lshlrev_b32_e32 v68, 16, v83
	v_and_b32_e32 v69, 0xffff0000, v83
	v_pk_fma_f32 v[68:69], v[68:69], s[8:9], v[70:71] op_sel_hi:[1,0,1]
	v_cvt_pk_bf16_f32 v66, v66, v67
	v_cvt_pk_bf16_f32 v67, v68, v69
	s_nop 0
	v_permlane32_swap_b32_e32 v64, v66
	v_permlane32_swap_b32_e32 v65, v67
	global_store_dwordx4 v[112:113], v[64:67], off offset:192
	global_load_dwordx2 v[64:65], v[138:139], off offset:224
	s_nop 0
	global_load_dwordx2 v[66:67], v[138:139], off offset:240
	v_lshl_add_u64 v[70:71], v[132:133], 0, v[136:137]
	s_waitcnt vmcnt(1)
	v_lshlrev_b32_e32 v68, 16, v64
	v_and_b32_e32 v69, 0xffff0000, v64
	v_pk_fma_f32 v[68:69], v[68:69], s[8:9], v[72:73] op_sel_hi:[1,0,1]
	s_nop 0
	v_cvt_pk_bf16_f32 v64, v68, v69
	v_lshlrev_b32_e32 v68, 16, v65
	v_and_b32_e32 v69, 0xffff0000, v65
	v_pk_fma_f32 v[68:69], v[68:69], s[8:9], v[74:75] op_sel_hi:[1,0,1]
	s_nop 0
	v_cvt_pk_bf16_f32 v65, v68, v69
	s_waitcnt vmcnt(0)
	v_lshlrev_b32_e32 v68, 16, v66
	v_and_b32_e32 v69, 0xffff0000, v66
	v_pk_fma_f32 v[68:69], v[68:69], s[8:9], v[76:77] op_sel_hi:[1,0,1]
	s_nop 0
	v_cvt_pk_bf16_f32 v66, v68, v69
	v_lshlrev_b32_e32 v68, 16, v67
	v_and_b32_e32 v69, 0xffff0000, v67
	v_pk_fma_f32 v[68:69], v[68:69], s[8:9], v[78:79] op_sel_hi:[1,0,1]
	v_permlane32_swap_b32_e32 v64, v66
	v_cvt_pk_bf16_f32 v67, v68, v69
	s_nop 1
	v_permlane32_swap_b32_e32 v65, v67
	global_store_dwordx4 v[112:113], v[64:67], off offset:224
	s_nop 1
	v_lshl_add_u64 v[64:65], s[40:41], 0, v[136:137]
	v_lshl_add_u64 v[64:65], v[64:65], 0, v[134:135]
	v_lshl_add_u64 v[64:65], v[64:65], 0, v[128:129]
	global_load_dwordx2 v[66:67], v[64:65], off
	global_load_dwordx2 v[68:69], v[64:65], off offset:16
	s_waitcnt vmcnt(1)
	v_lshlrev_b32_e32 v72, 16, v66
	v_and_b32_e32 v73, 0xffff0000, v66
	v_pk_fma_f32 v[48:49], v[72:73], s[8:9], v[48:49] op_sel_hi:[1,0,1]
	s_nop 0
	v_cvt_pk_bf16_f32 v66, v48, v49
	v_lshlrev_b32_e32 v48, 16, v67
	v_and_b32_e32 v49, 0xffff0000, v67
	v_pk_fma_f32 v[48:49], v[48:49], s[8:9], v[50:51] op_sel_hi:[1,0,1]
	s_nop 0
	v_cvt_pk_bf16_f32 v67, v48, v49
	s_waitcnt vmcnt(0)
	v_lshlrev_b32_e32 v48, 16, v68
	v_and_b32_e32 v49, 0xffff0000, v68
	v_pk_fma_f32 v[48:49], v[48:49], s[8:9], v[52:53] op_sel_hi:[1,0,1]
	s_nop 0
	v_cvt_pk_bf16_f32 v68, v48, v49
	v_lshlrev_b32_e32 v48, 16, v69
	v_and_b32_e32 v49, 0xffff0000, v69
	v_pk_fma_f32 v[48:49], v[48:49], s[8:9], v[54:55] op_sel_hi:[1,0,1]
	v_permlane32_swap_b32_e32 v66, v68
	v_cvt_pk_bf16_f32 v69, v48, v49
	s_nop 1
	v_permlane32_swap_b32_e32 v67, v69
	v_lshl_add_u64 v[48:49], v[70:71], 0, v[134:135]
	global_store_dwordx4 v[48:49], v[66:69], off
	global_load_dwordx2 v[50:51], v[64:65], off offset:32
	global_load_dwordx2 v[52:53], v[64:65], off offset:48
	s_waitcnt vmcnt(1)
	v_lshlrev_b32_e32 v54, 16, v50
	v_and_b32_e32 v55, 0xffff0000, v50
	v_pk_fma_f32 v[54:55], v[54:55], s[8:9], v[56:57] op_sel_hi:[1,0,1]
	s_nop 0
	v_cvt_pk_bf16_f32 v50, v54, v55
	v_lshlrev_b32_e32 v54, 16, v51
	v_and_b32_e32 v55, 0xffff0000, v51
	v_pk_fma_f32 v[54:55], v[54:55], s[8:9], v[58:59] op_sel_hi:[1,0,1]
	s_nop 0
	v_cvt_pk_bf16_f32 v51, v54, v55
	s_waitcnt vmcnt(0)
	v_lshlrev_b32_e32 v54, 16, v52
	v_and_b32_e32 v55, 0xffff0000, v52
	v_pk_fma_f32 v[54:55], v[54:55], s[8:9], v[60:61] op_sel_hi:[1,0,1]
	s_nop 0
	v_cvt_pk_bf16_f32 v52, v54, v55
	v_lshlrev_b32_e32 v54, 16, v53
	v_and_b32_e32 v55, 0xffff0000, v53
	v_pk_fma_f32 v[54:55], v[54:55], s[8:9], v[62:63] op_sel_hi:[1,0,1]
	v_permlane32_swap_b32_e32 v50, v52
	v_cvt_pk_bf16_f32 v53, v54, v55
	s_nop 1
	v_permlane32_swap_b32_e32 v51, v53
	global_store_dwordx4 v[48:49], v[50:53], off offset:32
	global_load_dwordx2 v[50:51], v[64:65], off offset:64
	s_nop 0
	global_load_dwordx2 v[52:53], v[64:65], off offset:80
	s_waitcnt vmcnt(1)
; DI unsigned pack2(float a, float b) { f32x2_t v = {a, b}; return __builtin_bit_cast(unsigned, __builtin_convertvector(v, bf16x2_t)); }
; DI float lo2f(unsigned v) { return __uint_as_float(v << 16); }
; DI float hi2f(unsigned v) { return __uint_as_float(v & 0xffff0000u); }
;     ...
;             } else if (MODE == 1) {
; #pragma unroll
;               for (int gp = 0; gp < 2; ++gp) {
;                 const int g0 = 2 * gp;
;                 const int nb_ = nt * 256 + wn * 128 + ni * 32 + 8 * g0;
;                 const uint2 ra = *(const uint2*)(res + m * 1024 + nb_ + 4 * hh), rb = *(const uint2*)(res + m * 1024 + nb_ + 8 + 4 * hh);
;                 uint2 pa, pb;
;                 pa.x = pack2(alpha * lo2f(ra.x) + acc[mi][ni][4 * g0], alpha * hi2f(ra.x) + acc[mi][ni][4 * g0 + 1]);
;                 pa.y = pack2(alpha * lo2f(ra.y) + acc[mi][ni][4 * g0 + 2], alpha * hi2f(ra.y) + acc[mi][ni][4 * g0 + 3]);
;                 pb.x = pack2(alpha * lo2f(rb.x) + acc[mi][ni][4 * g0 + 4], alpha * hi2f(rb.x) + acc[mi][ni][4 * g0 + 5]);
;                 pb.y = pack2(alpha * lo2f(rb.y) + acc[mi][ni][4 * g0 + 6], alpha * hi2f(rb.y) + acc[mi][ni][4 * g0 + 7]);
;                 { auto rx = __builtin_amdgcn_permlane32_swap(pa.x, pb.x, false, false); pa.x = rx[0]; pb.x = rx[1]; }
;                 { auto ry = __builtin_amdgcn_permlane32_swap(pa.y, pb.y, false, false); pa.y = ry[0]; pb.y = ry[1]; }
;                 *(uint4*)(outp + m * 1024 + nb_ + 8 * hh) = make_uint4(pa.x, pa.y, pb.x, pb.y);
;               }
;     ...
;     asm volatile("s_waitcnt lgkmcnt(0)" ::: "memory"); __builtin_amdgcn_s_barrier(); asm volatile("" ::: "memory");
;     cur ^= BUFB;
;   }
;   asm volatile("s_waitcnt vmcnt(0)" ::: "memory");
;   __syncthreads();
	v_lshlrev_b32_e32 v54, 16, v50
	v_and_b32_e32 v55, 0xffff0000, v50
	v_lshlrev_b32_e32 v50, 16, v51
	v_and_b32_e32 v51, 0xffff0000, v51
	v_pk_fma_f32 v[32:33], v[54:55], s[8:9], v[32:33] op_sel_hi:[1,0,1]
	v_pk_fma_f32 v[34:35], v[50:51], s[8:9], v[34:35] op_sel_hi:[1,0,1]
	v_cvt_pk_bf16_f32 v32, v32, v33
	v_cvt_pk_bf16_f32 v33, v34, v35
	s_waitcnt vmcnt(0)
	v_lshlrev_b32_e32 v34, 16, v52
	v_and_b32_e32 v35, 0xffff0000, v52
	v_pk_fma_f32 v[34:35], v[34:35], s[8:9], v[36:37] op_sel_hi:[1,0,1]
	v_lshlrev_b32_e32 v36, 16, v53
	v_and_b32_e32 v37, 0xffff0000, v53
	v_pk_fma_f32 v[36:37], v[36:37], s[8:9], v[38:39] op_sel_hi:[1,0,1]
	v_cvt_pk_bf16_f32 v34, v34, v35
	v_cvt_pk_bf16_f32 v35, v36, v37
	s_nop 0
	v_permlane32_swap_b32_e32 v32, v34
	v_permlane32_swap_b32_e32 v33, v35
	global_store_dwordx4 v[48:49], v[32:35], off offset:64
	global_load_dwordx2 v[32:33], v[64:65], off offset:96
	s_nop 0
	global_load_dwordx2 v[34:35], v[64:65], off offset:112
	s_waitcnt vmcnt(1)
	v_lshlrev_b32_e32 v36, 16, v32
	v_and_b32_e32 v37, 0xffff0000, v32
	v_pk_fma_f32 v[36:37], v[36:37], s[8:9], v[40:41] op_sel_hi:[1,0,1]
	s_nop 0
	v_cvt_pk_bf16_f32 v32, v36, v37
	v_lshlrev_b32_e32 v36, 16, v33
	v_and_b32_e32 v37, 0xffff0000, v33
	v_pk_fma_f32 v[36:37], v[36:37], s[8:9], v[42:43] op_sel_hi:[1,0,1]
	s_nop 0
	v_cvt_pk_bf16_f32 v33, v36, v37
	s_waitcnt vmcnt(0)
	v_lshlrev_b32_e32 v36, 16, v34
	v_and_b32_e32 v37, 0xffff0000, v34
	v_pk_fma_f32 v[36:37], v[36:37], s[8:9], v[44:45] op_sel_hi:[1,0,1]
	s_nop 0
	v_cvt_pk_bf16_f32 v34, v36, v37
	v_lshlrev_b32_e32 v36, 16, v35
	v_and_b32_e32 v37, 0xffff0000, v35
	v_pk_fma_f32 v[36:37], v[36:37], s[8:9], v[46:47] op_sel_hi:[1,0,1]
	v_permlane32_swap_b32_e32 v32, v34
	v_cvt_pk_bf16_f32 v35, v36, v37
	s_nop 1
	v_permlane32_swap_b32_e32 v33, v35
	global_store_dwordx4 v[48:49], v[32:35], off offset:96
	global_load_dwordx2 v[32:33], v[64:65], off offset:128
	s_nop 0
	global_load_dwordx2 v[34:35], v[64:65], off offset:144
	s_waitcnt vmcnt(1)
	v_lshlrev_b32_e32 v36, 16, v32
	v_and_b32_e32 v37, 0xffff0000, v32
	v_lshlrev_b32_e32 v32, 16, v33
	v_and_b32_e32 v33, 0xffff0000, v33
	v_pk_fma_f32 v[16:17], v[36:37], s[8:9], v[16:17] op_sel_hi:[1,0,1]
	v_pk_fma_f32 v[18:19], v[32:33], s[8:9], v[18:19] op_sel_hi:[1,0,1]
	v_cvt_pk_bf16_f32 v16, v16, v17
	v_cvt_pk_bf16_f32 v17, v18, v19
	s_waitcnt vmcnt(0)
	v_lshlrev_b32_e32 v18, 16, v34
	v_and_b32_e32 v19, 0xffff0000, v34
	v_pk_fma_f32 v[18:19], v[18:19], s[8:9], v[20:21] op_sel_hi:[1,0,1]
	v_lshlrev_b32_e32 v20, 16, v35
	v_and_b32_e32 v21, 0xffff0000, v35
	v_pk_fma_f32 v[20:21], v[20:21], s[8:9], v[22:23] op_sel_hi:[1,0,1]
	v_cvt_pk_bf16_f32 v18, v18, v19
	v_cvt_pk_bf16_f32 v19, v20, v21
	s_nop 0
	v_permlane32_swap_b32_e32 v16, v18
	v_permlane32_swap_b32_e32 v17, v19
	global_store_dwordx4 v[48:49], v[16:19], off offset:128
	global_load_dwordx2 v[16:17], v[64:65], off offset:160
	s_nop 0
	global_load_dwordx2 v[18:19], v[64:65], off offset:176
	s_waitcnt vmcnt(1)
	v_lshlrev_b32_e32 v20, 16, v16
	v_and_b32_e32 v21, 0xffff0000, v16
	v_pk_fma_f32 v[20:21], v[20:21], s[8:9], v[24:25] op_sel_hi:[1,0,1]
	s_nop 0
	v_cvt_pk_bf16_f32 v16, v20, v21
	v_lshlrev_b32_e32 v20, 16, v17
	v_and_b32_e32 v21, 0xffff0000, v17
	v_pk_fma_f32 v[20:21], v[20:21], s[8:9], v[26:27] op_sel_hi:[1,0,1]
	s_nop 0
	v_cvt_pk_bf16_f32 v17, v20, v21
	s_waitcnt vmcnt(0)
	v_lshlrev_b32_e32 v20, 16, v18
	v_and_b32_e32 v21, 0xffff0000, v18
	v_pk_fma_f32 v[20:21], v[20:21], s[8:9], v[28:29] op_sel_hi:[1,0,1]
	s_nop 0
	v_cvt_pk_bf16_f32 v18, v20, v21
	v_lshlrev_b32_e32 v20, 16, v19
	v_and_b32_e32 v21, 0xffff0000, v19
	v_pk_fma_f32 v[20:21], v[20:21], s[8:9], v[30:31] op_sel_hi:[1,0,1]
	v_permlane32_swap_b32_e32 v16, v18
	v_cvt_pk_bf16_f32 v19, v20, v21
	s_nop 1
	v_permlane32_swap_b32_e32 v17, v19
	global_store_dwordx4 v[48:49], v[16:19], off offset:160
	global_load_dwordx2 v[16:17], v[64:65], off offset:192
	s_nop 0
	global_load_dwordx2 v[18:19], v[64:65], off offset:208
	s_waitcnt vmcnt(1)
	v_lshlrev_b32_e32 v20, 16, v16
	v_and_b32_e32 v21, 0xffff0000, v16
	v_lshlrev_b32_e32 v16, 16, v17
	v_and_b32_e32 v17, 0xffff0000, v17
	v_pk_fma_f32 v[0:1], v[20:21], s[8:9], v[0:1] op_sel_hi:[1,0,1]
	v_pk_fma_f32 v[2:3], v[16:17], s[8:9], v[2:3] op_sel_hi:[1,0,1]
	v_cvt_pk_bf16_f32 v0, v0, v1
	v_cvt_pk_bf16_f32 v1, v2, v3
	s_waitcnt vmcnt(0)
	v_lshlrev_b32_e32 v2, 16, v18
	v_and_b32_e32 v3, 0xffff0000, v18
	v_pk_fma_f32 v[2:3], v[2:3], s[8:9], v[4:5] op_sel_hi:[1,0,1]
	v_lshlrev_b32_e32 v4, 16, v19
	v_and_b32_e32 v5, 0xffff0000, v19
	v_pk_fma_f32 v[4:5], v[4:5], s[8:9], v[6:7] op_sel_hi:[1,0,1]
	v_cvt_pk_bf16_f32 v2, v2, v3
	v_cvt_pk_bf16_f32 v3, v4, v5
	s_nop 0
	v_permlane32_swap_b32_e32 v0, v2
	v_permlane32_swap_b32_e32 v1, v3
	global_store_dwordx4 v[48:49], v[0:3], off offset:192
	global_load_dwordx2 v[0:1], v[64:65], off offset:224
	s_nop 0
	global_load_dwordx2 v[2:3], v[64:65], off offset:240
	s_waitcnt vmcnt(1)
	v_lshlrev_b32_e32 v4, 16, v0
	v_and_b32_e32 v5, 0xffff0000, v0
	v_pk_fma_f32 v[4:5], v[4:5], s[8:9], v[8:9] op_sel_hi:[1,0,1]
	s_nop 0
	v_cvt_pk_bf16_f32 v0, v4, v5
	v_lshlrev_b32_e32 v4, 16, v1
	v_and_b32_e32 v5, 0xffff0000, v1
	v_pk_fma_f32 v[4:5], v[4:5], s[8:9], v[10:11] op_sel_hi:[1,0,1]
	s_nop 0
	v_cvt_pk_bf16_f32 v1, v4, v5
	s_waitcnt vmcnt(0)
	v_lshlrev_b32_e32 v4, 16, v2
	v_and_b32_e32 v5, 0xffff0000, v2
	v_pk_fma_f32 v[4:5], v[4:5], s[8:9], v[12:13] op_sel_hi:[1,0,1]
	s_nop 0
	v_cvt_pk_bf16_f32 v2, v4, v5
	v_lshlrev_b32_e32 v4, 16, v3
	v_and_b32_e32 v5, 0xffff0000, v3
	v_pk_fma_f32 v[4:5], v[4:5], s[8:9], v[14:15] op_sel_hi:[1,0,1]
	v_permlane32_swap_b32_e32 v0, v2
	v_cvt_pk_bf16_f32 v3, v4, v5
	s_nop 1
	v_permlane32_swap_b32_e32 v1, v3
	global_store_dwordx4 v[48:49], v[0:3], off offset:224
	s_waitcnt lgkmcnt(0)
	s_barrier
	s_waitcnt vmcnt(0)
	s_barrier

; #define MFMA(a, b, c) __builtin_amdgcn_mfma_f32_32x32x16_bf16((a), (b), (c), 0, 0, 0)
;     ...
;   for (int s = 0; s < S; ++s) {
;     G_DMA(s + 1, cur ^ BUFB);
;     {
;       const char* Ab = smem + cur + fA;
;       const char* Bb = smem + cur + fB;
;       __builtin_amdgcn_sched_barrier(0);
; #pragma unroll
;       for (int kk = 0; kk < 4; ++kk) {
;         const int ko = (((kk * 2 + hh) ^ fsw) << 4);
;         bf16x8 af[2], wf[4];
;         af[0] = *(const bf16x8*)(Ab + ko); af[1] = *(const bf16x8*)(Ab + 4096 + ko);
; #pragma unroll
;         for (int ni = 0; ni < 4; ++ni) wf[ni] = *(const bf16x8*)(Bb + ni * 4096 + ko);
; #pragma unroll
;         for (int mi = 0; mi < 2; ++mi)
; #pragma unroll
;           for (int ni = 0; ni < 4; ++ni) acc[mi][ni] = MFMA(wf[ni], af[mi], acc[mi][ni]);
;         if (kk == 1) __builtin_amdgcn_sched_barrier(0);
;       }
;       __builtin_amdgcn_sched_barrier(0);
;     }
;     asm volatile("s_waitcnt vmcnt(0)" ::: "memory");
.LBB0_218:
	v_add3_u32 v244, s25, v131, v140
	v_add3_u32 v245, s25, v141, v140
	v_add_u32_e32 v187, v245, v144
	v_add_u32_e32 v208, v244, v144
	ds_read_b128 v[188:191], v187 offset:32768
	ds_read_b128 v[204:207], v208
	ds_read_b128 v[192:195], v187 offset:36864
	ds_read_b128 v[196:199], v187 offset:40960
	ds_read_b128 v[200:203], v187 offset:45056
	ds_read_b128 v[216:219], v208 offset:4096
	v_add_u32_e32 v209, v245, v145
	v_add_u32_e32 v215, v244, v145
	ds_read_b128 v[220:223], v209 offset:32768
	ds_read_b128 v[236:239], v215
	ds_read_b128 v[224:227], v209 offset:36864
	ds_read_b128 v[228:231], v209 offset:40960
	ds_read_b128 v[232:235], v209 offset:45056
	ds_read_b128 v[240:243], v215 offset:4096
	s_add_i32 s46, s8, 1
	s_cmp_lt_u32 s46, s58
	s_cselect_b32 s22, s46, s59
	s_lshl_b32 s23, s22, 1
	s_andn2_b32 s23, s23, 31
	s_add_i32 s23, s23, s33
	s_lshr_b32 s23, s23, 3
	s_mov_b32 s9, s25
	s_and_b32 s25, s23, 4
	s_or_b32 s25, s25, s45
	s_and_b32 s23, s23, 0xfffff8
	s_or_b32 s28, s23, s74
	s_lshl_b32 s23, s25, 19
	s_add_u32 s23, s7, s23
	s_addc_u32 s25, s24, 0
	s_lshl_b32 s22, s22, 7
	s_and_b32 s44, s22, 0x780
	s_add_u32 s22, s23, s44
	s_addc_u32 s23, s25, 0
	s_lshl_b32 s40, s28, 8
	s_ashr_i32 s41, s40, 31
	s_lshl_b64 s[40:41], s[40:41], 11
	s_add_u32 s28, s62, s40
	s_addc_u32 s40, s63, s41
	s_xor_b32 s25, s9, 0x10000
	v_add_u32_e32 v128, s25, v142
	v_lshl_add_u64 v[136:137], s[22:23], 0, v[132:133]
	v_readfirstlane_b32 s22, v128
	v_add_u32_e32 v148, 0x2000, v128
	s_mov_b32 m0, s22
	s_mov_b64 s[50:51], 0x20000
	v_readfirstlane_b32 s22, v148
	v_add_u32_e32 v148, 0x4000, v128
	global_load_lds_dwordx4 v[136:137], off
	s_waitcnt lgkmcnt(10)
	v_mfma_f32_32x32x16_bf16 v[112:127], v[188:191], v[204:207], v[112:127]
	s_waitcnt lgkmcnt(9)
	v_mfma_f32_32x32x16_bf16 v[96:111], v[192:195], v[204:207], v[96:111]
	v_lshl_add_u64 v[138:139], v[136:137], 0, s[50:51]
	s_mov_b32 m0, s22
	s_mov_b64 s[48:49], 0x40000
	v_readfirstlane_b32 s22, v148
	global_load_lds_dwordx4 v[138:139], off
	s_waitcnt lgkmcnt(8)
	v_mfma_f32_32x32x16_bf16 v[80:95], v[196:199], v[204:207], v[80:95]
	s_waitcnt lgkmcnt(7)
	v_mfma_f32_32x32x16_bf16 v[64:79], v[200:203], v[204:207], v[64:79]
	v_lshl_add_u64 v[138:139], v[136:137], 0, s[48:49]
	s_mov_b32 m0, s22
	s_mov_b64 s[52:53], 0x60000
	global_load_lds_dwordx4 v[138:139], off
	s_waitcnt lgkmcnt(6)
	v_mfma_f32_32x32x16_bf16 v[48:63], v[188:191], v[216:219], v[48:63]
	v_mfma_f32_32x32x16_bf16 v[32:47], v[192:195], v[216:219], v[32:47]
	v_add_u32_e32 v138, 0x6000, v128
	v_lshl_add_u64 v[136:137], v[136:137], 0, s[52:53]
	v_readfirstlane_b32 s22, v138
	s_mov_b32 m0, s22
	s_add_u32 s22, s28, s44
	s_addc_u32 s23, s40, 0
	v_add_u32_e32 v138, 0x8000, v128
	global_load_lds_dwordx4 v[136:137], off
	v_mfma_f32_32x32x16_bf16 v[16:31], v[196:199], v[216:219], v[16:31]
	v_mfma_f32_32x32x16_bf16 v[0:15], v[200:203], v[216:219], v[0:15]
	v_lshl_add_u64 v[136:137], s[22:23], 0, v[132:133]
	v_readfirstlane_b32 s22, v138
	v_add_u32_e32 v148, 0xa000, v128
	s_mov_b32 m0, s22
	v_readfirstlane_b32 s22, v148
	v_add_u32_e32 v148, 0xc000, v128
	global_load_lds_dwordx4 v[136:137], off
	v_add_u32_e32 v187, v245, v146
	v_add_u32_e32 v208, v244, v146
	ds_read_b128 v[188:191], v187 offset:32768
	ds_read_b128 v[204:207], v208
	ds_read_b128 v[192:195], v187 offset:36864
	ds_read_b128 v[196:199], v187 offset:40960
	ds_read_b128 v[200:203], v187 offset:45056
	ds_read_b128 v[216:219], v208 offset:4096
	s_waitcnt lgkmcnt(10)
	v_mfma_f32_32x32x16_bf16 v[112:127], v[220:223], v[236:239], v[112:127]
	s_waitcnt lgkmcnt(9)
	v_mfma_f32_32x32x16_bf16 v[96:111], v[224:227], v[236:239], v[96:111]
	v_lshl_add_u64 v[138:139], v[136:137], 0, s[50:51]
	s_mov_b32 m0, s22
	v_readfirstlane_b32 s22, v148
	v_add_u32_e32 v128, 0xe000, v128
	global_load_lds_dwordx4 v[138:139], off
	s_waitcnt lgkmcnt(8)
	v_mfma_f32_32x32x16_bf16 v[80:95], v[228:231], v[236:239], v[80:95]
	s_waitcnt lgkmcnt(7)
	v_mfma_f32_32x32x16_bf16 v[64:79], v[232:235], v[236:239], v[64:79]
	v_lshl_add_u64 v[138:139], v[136:137], 0, s[48:49]
	s_mov_b32 m0, s22
	v_readfirstlane_b32 s22, v128
	global_load_lds_dwordx4 v[138:139], off
	s_waitcnt lgkmcnt(6)
	v_mfma_f32_32x32x16_bf16 v[48:63], v[220:223], v[240:243], v[48:63]
	v_mfma_f32_32x32x16_bf16 v[32:47], v[224:227], v[240:243], v[32:47]
	v_lshl_add_u64 v[136:137], v[136:137], 0, s[52:53]
	s_mov_b32 m0, s22
	s_add_i32 s9, s9, 0
	global_load_lds_dwordx4 v[136:137], off
	v_mfma_f32_32x32x16_bf16 v[16:31], v[228:231], v[240:243], v[16:31]
	v_mfma_f32_32x32x16_bf16 v[0:15], v[232:235], v[240:243], v[0:15]
	v_add_u32_e32 v209, v245, v147
	v_add_u32_e32 v215, v244, v147
	ds_read_b128 v[220:223], v209 offset:32768
	ds_read_b128 v[236:239], v215
	ds_read_b128 v[224:227], v209 offset:36864
	ds_read_b128 v[228:231], v209 offset:40960
	ds_read_b128 v[232:235], v209 offset:45056
	ds_read_b128 v[240:243], v215 offset:4096
	s_waitcnt lgkmcnt(10)
	v_mfma_f32_32x32x16_bf16 v[112:127], v[188:191], v[204:207], v[112:127]
	s_waitcnt lgkmcnt(9)
	v_mfma_f32_32x32x16_bf16 v[96:111], v[192:195], v[204:207], v[96:111]
	s_waitcnt lgkmcnt(8)
	v_mfma_f32_32x32x16_bf16 v[80:95], v[196:199], v[204:207], v[80:95]
	s_waitcnt lgkmcnt(7)
	v_mfma_f32_32x32x16_bf16 v[64:79], v[200:203], v[204:207], v[64:79]
	s_waitcnt lgkmcnt(6)
	v_mfma_f32_32x32x16_bf16 v[48:63], v[188:191], v[216:219], v[48:63]
	v_mfma_f32_32x32x16_bf16 v[32:47], v[192:195], v[216:219], v[32:47]
	v_mfma_f32_32x32x16_bf16 v[16:31], v[196:199], v[216:219], v[16:31]
	v_mfma_f32_32x32x16_bf16 v[0:15], v[200:203], v[216:219], v[0:15]
	s_waitcnt lgkmcnt(4)
	v_mfma_f32_32x32x16_bf16 v[112:127], v[220:223], v[236:239], v[112:127]
	s_waitcnt lgkmcnt(3)
	v_mfma_f32_32x32x16_bf16 v[96:111], v[224:227], v[236:239], v[96:111]
	s_waitcnt lgkmcnt(2)
	v_mfma_f32_32x32x16_bf16 v[80:95], v[228:231], v[236:239], v[80:95]
	s_waitcnt lgkmcnt(1)
	v_mfma_f32_32x32x16_bf16 v[64:79], v[232:235], v[236:239], v[64:79]
	s_waitcnt lgkmcnt(0)
	v_mfma_f32_32x32x16_bf16 v[48:63], v[220:223], v[240:243], v[48:63]
	v_mfma_f32_32x32x16_bf16 v[32:47], v[224:227], v[240:243], v[32:47]
	v_mfma_f32_32x32x16_bf16 v[16:31], v[228:231], v[240:243], v[16:31]
	v_mfma_f32_32x32x16_bf16 v[0:15], v[232:235], v[240:243], v[0:15]
	s_waitcnt vmcnt(0)
	s_and_b32 s9, s8, 15
	s_cmp_lg_u32 s9, 15
	s_cbranch_scc1 .LBB0_217
; DI unsigned pack2(float a, float b) { f32x2_t v = {a, b}; return __builtin_bit_cast(unsigned, __builtin_convertvector(v, bf16x2_t)); }
; #define G_TILEMAP(q, MT, NT) do { if (sq) { const int grp_ = (q) >> 5, i_ = (q) & 31; \
;       MT = xcd * mpx + (grp_ & (mpx / 4 - 1)) * 4 + (i_ & 3); NT = (grp_ >> (LMPX - 2)) * 8 + (i_ >> 2); } \
;     else { MT = xcd * mpx + ((q) & (mpx - 1)); NT = (q) >> LMPX; } } while (0)
;     ...
;     if ((s & (nk - 1)) == nk - 1) {
;       const int q = slot + (s >> lnk) * nslots;
;       int mt, nt; G_TILEMAP(q, mt, nt);
;       if (dostore) {
; #pragma unroll
;         for (int mi = 0; mi < 2; ++mi) {
;           const size_t m = (size_t)mt * 256 + wm * 64 + mi * 32 + r;
; #pragma unroll
;           for (int ni = 0; ni < 4; ++ni) {
;             __builtin_amdgcn_sched_barrier(0);
;             if (MODE == 0) {
; #pragma unroll
;               for (int gp = 0; gp < 2; ++gp) {
;                 const int g0 = 2 * gp;
;                 uint2 pa, pb;
;                 pa.x = pack2(acc[mi][ni][4 * g0], acc[mi][ni][4 * g0 + 1]); pa.y = pack2(acc[mi][ni][4 * g0 + 2], acc[mi][ni][4 * g0 + 3]);
;                 pb.x = pack2(acc[mi][ni][4 * g0 + 4], acc[mi][ni][4 * g0 + 5]); pb.y = pack2(acc[mi][ni][4 * g0 + 6], acc[mi][ni][4 * g0 + 7]);
;                 { auto rx = __builtin_amdgcn_permlane32_swap(pa.x, pb.x, false, false); pa.x = rx[0]; pb.x = rx[1]; }
;                 { auto ry = __builtin_amdgcn_permlane32_swap(pa.y, pb.y, false, false); pa.y = ry[0]; pb.y = ry[1]; }
;                 const int col = nt * 256 + wn * 128 + ni * 32 + 8 * g0 + 8 * hh;
;                 const uint4 v4 = make_uint4(pa.x, pa.y, pb.x, pb.y);
;                 if (outp != nullptr && nt >= 32) *(uint4*)(outp + m * 2048 + (col - 8192)) = v4;
;                 else if (col < nvalid) *(uint4*)(C + m * ldc + col) = v4;
	s_lshl_b32 s8, s8, 1
	s_and_b32 s8, s8, 0x7fffffe0
	s_add_i32 s8, s8, s33
	s_lshr_b32 s9, s8, 3
	s_and_b32 s22, s9, 4
	s_or_b32 s22, s22, s45
	s_and_b32 s9, s9, 0xfffff8
	s_or_b32 s9, s9, s74
	s_lshl_b32 s28, s22, 8
	v_lshl_add_u64 v[136:137], v[134:135], 0, s[28:29]
	s_lshl_b32 s28, s9, 8
	s_cmpk_lt_u32 s8, 0x100
	s_cselect_b64 s[8:9], -1, 0
	s_xor_b64 s[22:23], s[56:57], -1
	v_lshlrev_b64 v[138:139], 14, v[136:137]
	v_or_b32_e32 v128, s28, v143
	s_mov_b64 s[40:41], -1
	s_or_b64 s[44:45], s[22:23], s[8:9]
	v_lshl_add_u64 v[138:139], s[30:31], 0, v[138:139]
	v_cvt_pk_bf16_f32 v112, v112, v113
	v_cvt_pk_bf16_f32 v113, v114, v115
	v_cvt_pk_bf16_f32 v114, v116, v117
	v_cvt_pk_bf16_f32 v115, v118, v119
	s_nop 0
	v_permlane32_swap_b32_e32 v112, v114
	v_permlane32_swap_b32_e32 v113, v115
	s_and_b64 vcc, exec, s[44:45]
	s_cbranch_vccz .LBB0_223
	s_cmp_gt_u32 s28, 0x3fffffff
	s_cbranch_scc1 .LBB0_222
	v_lshl_add_u64 v[116:117], v[128:129], 1, v[138:139]
	global_store_dwordx4 v[116:117], v[112:115], off

; #define MFMA(a, b, c) __builtin_amdgcn_mfma_f32_32x32x16_bf16((a), (b), (c), 0, 0, 0)
;     ...
;   for (int s = 0; s < S; ++s) {
;     G_DMA(s + 1, cur ^ BUFB);
;     {
;       const char* Ab = smem + cur + fA;
;       const char* Bb = smem + cur + fB;
;       __builtin_amdgcn_sched_barrier(0);
; #pragma unroll
;       for (int kk = 0; kk < 4; ++kk) {
;         const int ko = (((kk * 2 + hh) ^ fsw) << 4);
;         bf16x8 af[2], wf[4];
;         af[0] = *(const bf16x8*)(Ab + ko); af[1] = *(const bf16x8*)(Ab + 4096 + ko);
; #pragma unroll
;         for (int ni = 0; ni < 4; ++ni) wf[ni] = *(const bf16x8*)(Bb + ni * 4096 + ko);
; #pragma unroll
;         for (int mi = 0; mi < 2; ++mi)
; #pragma unroll
;           for (int ni = 0; ni < 4; ++ni) acc[mi][ni] = MFMA(wf[ni], af[mi], acc[mi][ni]);
;         if (kk == 1) __builtin_amdgcn_sched_barrier(0);
;       }
;       __builtin_amdgcn_sched_barrier(0);
;     }
;     asm volatile("s_waitcnt vmcnt(0)" ::: "memory");
.LBB0_734:
	v_add3_u32 v187, s7, v144, v147
	v_add3_u32 v208, s7, v149, v147
	v_add_u32_e32 v182, v208, v148
	v_add_u32_e32 v183, v187, v148
	ds_read_b128 v[192:195], v182 offset:32768
	ds_read_b128 v[216:219], v183
	ds_read_b128 v[196:199], v182 offset:36864
	ds_read_b128 v[200:203], v182 offset:40960
	ds_read_b128 v[204:207], v182 offset:45056
	ds_read_b128 v[220:223], v183 offset:4096
	v_add_u32_e32 v184, v208, v145
	v_add_u32_e32 v185, v187, v145
	ds_read_b128 v[224:227], v184 offset:32768
	ds_read_b128 v[240:243], v185
	ds_read_b128 v[228:231], v184 offset:36864
	ds_read_b128 v[232:235], v184 offset:40960
	ds_read_b128 v[236:239], v184 offset:45056
	ds_read_b128 v[244:247], v185 offset:4096
	s_lshl_b32 s8, s6, 16
	s_and_b32 s8, s8, 0x200000
	s_add_i32 s8, s93, s8
	s_lshl_b32 s8, s8, 1
	s_and_b32 s28, s8, 0x700000
	s_xor_b32 s8, s7, 0x10000
	v_add_u32_e32 v128, s8, v150
	v_lshl_add_u64 v[160:161], v[136:137], 0, s[40:41]
	s_mov_b64 s[22:23], 0x17e00080
	v_readfirstlane_b32 s9, v128
	v_add_u32_e32 v164, 0x2000, v128
	v_lshl_add_u64 v[162:163], v[160:161], 0, s[22:23]
	s_mov_b32 m0, s9
	s_mov_b64 s[22:23], 0x17e40080
	v_readfirstlane_b32 s9, v164
	v_add_u32_e32 v164, 0x4000, v128
	global_load_lds_dwordx4 v[162:163], off
	s_waitcnt lgkmcnt(10)
	v_mfma_f32_32x32x16_bf16 v[112:127], v[192:195], v[216:219], v[112:127]
	s_waitcnt lgkmcnt(9)
	v_mfma_f32_32x32x16_bf16 v[96:111], v[196:199], v[216:219], v[96:111]
	v_lshl_add_u64 v[162:163], v[160:161], 0, s[22:23]
	s_mov_b32 m0, s9
	s_mov_b64 s[22:23], 0x17e80080
	v_readfirstlane_b32 s9, v164
	global_load_lds_dwordx4 v[162:163], off
	s_waitcnt lgkmcnt(8)
	v_mfma_f32_32x32x16_bf16 v[80:95], v[200:203], v[216:219], v[80:95]
	s_waitcnt lgkmcnt(7)
	v_mfma_f32_32x32x16_bf16 v[64:79], v[204:207], v[216:219], v[64:79]
	v_lshl_add_u64 v[162:163], v[160:161], 0, s[22:23]
	s_mov_b32 m0, s9
	v_lshl_add_u64 v[158:159], v[138:139], 0, s[28:29]
	global_load_lds_dwordx4 v[162:163], off
	s_waitcnt lgkmcnt(6)
	v_mfma_f32_32x32x16_bf16 v[48:63], v[192:195], v[220:223], v[48:63]
	v_mfma_f32_32x32x16_bf16 v[32:47], v[196:199], v[220:223], v[32:47]
	v_add_u32_e32 v162, 0x6000, v128
	s_mov_b64 s[22:23], 0x17ec0080
	v_readfirstlane_b32 s9, v162
	v_add_u32_e32 v162, 0x8000, v128
	v_lshl_add_u64 v[160:161], v[160:161], 0, s[22:23]
	s_mov_b32 m0, s9
	v_lshl_add_u64 v[158:159], v[158:159], 0, s[40:41]
	v_readfirstlane_b32 s9, v162
	v_add_u32_e32 v162, 0xa000, v128
	global_load_lds_dwordx4 v[160:161], off
	v_mfma_f32_32x32x16_bf16 v[16:31], v[200:203], v[220:223], v[16:31]
	v_mfma_f32_32x32x16_bf16 v[0:15], v[204:207], v[220:223], v[0:15]
	v_lshl_add_u64 v[160:161], v[158:159], 0, s[24:25]
	s_mov_b32 m0, s9
	v_readfirstlane_b32 s9, v162
	v_add_u32_e32 v162, 0xc000, v128
	global_load_lds_dwordx4 v[160:161], off
	v_add_u32_e32 v182, v208, v141
	v_add_u32_e32 v183, v187, v141
	ds_read_b128 v[192:195], v182 offset:32768
	ds_read_b128 v[216:219], v183
	ds_read_b128 v[196:199], v182 offset:36864
	ds_read_b128 v[200:203], v182 offset:40960
	ds_read_b128 v[204:207], v182 offset:45056
	ds_read_b128 v[220:223], v183 offset:4096
	s_waitcnt lgkmcnt(10)
	v_mfma_f32_32x32x16_bf16 v[112:127], v[224:227], v[240:243], v[112:127]
	s_waitcnt lgkmcnt(9)
	v_mfma_f32_32x32x16_bf16 v[96:111], v[228:231], v[240:243], v[96:111]
	v_lshl_add_u64 v[160:161], v[158:159], 0, s[42:43]
	s_mov_b32 m0, s9
	v_readfirstlane_b32 s9, v162
	v_add_u32_e32 v128, 0xe000, v128
	global_load_lds_dwordx4 v[160:161], off
	s_waitcnt lgkmcnt(8)
	v_mfma_f32_32x32x16_bf16 v[80:95], v[232:235], v[240:243], v[80:95]
	s_waitcnt lgkmcnt(7)
	v_mfma_f32_32x32x16_bf16 v[64:79], v[236:239], v[240:243], v[64:79]
	v_lshl_add_u64 v[160:161], v[158:159], 0, s[44:45]
	s_mov_b32 m0, s9
	v_readfirstlane_b32 s9, v128
	global_load_lds_dwordx4 v[160:161], off
	s_waitcnt lgkmcnt(6)
	v_mfma_f32_32x32x16_bf16 v[48:63], v[224:227], v[244:247], v[48:63]
	v_mfma_f32_32x32x16_bf16 v[32:47], v[228:231], v[244:247], v[32:47]
	v_lshl_add_u64 v[158:159], v[158:159], 0, s[46:47]
	s_mov_b32 m0, s9
	s_add_i32 s7, s7, 0
	global_load_lds_dwordx4 v[158:159], off
	v_mfma_f32_32x32x16_bf16 v[16:31], v[232:235], v[244:247], v[16:31]
	v_mfma_f32_32x32x16_bf16 v[0:15], v[236:239], v[244:247], v[0:15]
	v_add_u32_e32 v184, v208, v140
	v_add_u32_e32 v185, v187, v140
	ds_read_b128 v[224:227], v184 offset:32768
	ds_read_b128 v[240:243], v185
	ds_read_b128 v[228:231], v184 offset:36864
	ds_read_b128 v[232:235], v184 offset:40960
	ds_read_b128 v[236:239], v184 offset:45056
	ds_read_b128 v[244:247], v185 offset:4096
	s_waitcnt lgkmcnt(10)
	v_mfma_f32_32x32x16_bf16 v[112:127], v[192:195], v[216:219], v[112:127]
	s_waitcnt lgkmcnt(9)
	v_mfma_f32_32x32x16_bf16 v[96:111], v[196:199], v[216:219], v[96:111]
	s_waitcnt lgkmcnt(8)
	v_mfma_f32_32x32x16_bf16 v[80:95], v[200:203], v[216:219], v[80:95]
	s_waitcnt lgkmcnt(7)
	v_mfma_f32_32x32x16_bf16 v[64:79], v[204:207], v[216:219], v[64:79]
	s_waitcnt lgkmcnt(6)
	v_mfma_f32_32x32x16_bf16 v[48:63], v[192:195], v[220:223], v[48:63]
	v_mfma_f32_32x32x16_bf16 v[32:47], v[196:199], v[220:223], v[32:47]
	v_mfma_f32_32x32x16_bf16 v[16:31], v[200:203], v[220:223], v[16:31]
	v_mfma_f32_32x32x16_bf16 v[0:15], v[204:207], v[220:223], v[0:15]
	s_waitcnt lgkmcnt(4)
	v_mfma_f32_32x32x16_bf16 v[112:127], v[224:227], v[240:243], v[112:127]
	s_waitcnt lgkmcnt(3)
	v_mfma_f32_32x32x16_bf16 v[96:111], v[228:231], v[240:243], v[96:111]
	s_waitcnt lgkmcnt(2)
	v_mfma_f32_32x32x16_bf16 v[80:95], v[232:235], v[240:243], v[80:95]
	s_waitcnt lgkmcnt(1)
	v_mfma_f32_32x32x16_bf16 v[64:79], v[236:239], v[240:243], v[64:79]
	s_waitcnt lgkmcnt(0)
	v_mfma_f32_32x32x16_bf16 v[48:63], v[224:227], v[244:247], v[48:63]
	v_mfma_f32_32x32x16_bf16 v[32:47], v[228:231], v[244:247], v[32:47]
	v_mfma_f32_32x32x16_bf16 v[16:31], v[232:235], v[244:247], v[16:31]
	v_mfma_f32_32x32x16_bf16 v[0:15], v[236:239], v[244:247], v[0:15]
	s_waitcnt vmcnt(0)
	s_waitcnt lgkmcnt(0)
	s_barrier
; #define MFMA(a, b, c) __builtin_amdgcn_mfma_f32_32x32x16_bf16((a), (b), (c), 0, 0, 0)
;     ...
;   for (int s = 0; s < S; ++s) {
;     G_DMA(s + 1, cur ^ BUFB);
;     {
;       const char* Ab = smem + cur + fA;
;       const char* Bb = smem + cur + fB;
;       __builtin_amdgcn_sched_barrier(0);
; #pragma unroll
;       for (int kk = 0; kk < 4; ++kk) {
;         const int ko = (((kk * 2 + hh) ^ fsw) << 4);
;         bf16x8 af[2], wf[4];
;         af[0] = *(const bf16x8*)(Ab + ko); af[1] = *(const bf16x8*)(Ab + 4096 + ko);
; #pragma unroll
;         for (int ni = 0; ni < 4; ++ni) wf[ni] = *(const bf16x8*)(Bb + ni * 4096 + ko);
; #pragma unroll
;         for (int mi = 0; mi < 2; ++mi)
; #pragma unroll
;           for (int ni = 0; ni < 4; ++ni) acc[mi][ni] = MFMA(wf[ni], af[mi], acc[mi][ni]);
;         if (kk == 1) __builtin_amdgcn_sched_barrier(0);
;       }
;       __builtin_amdgcn_sched_barrier(0);
;     }
;     asm volatile("s_waitcnt vmcnt(0)" ::: "memory");
	s_add_u32 s40, s40, 0x80
	s_addc_u32 s41, s41, 0
	s_add_i32 s6, s6, 1
	s_cmpk_eq_i32 s40, 0xf80
	s_mov_b32 s7, s8
	s_cbranch_scc0 .LBB0_734
	s_mov_b64 s[8:9], 0xf80
	v_readfirstlane_b32 s6, v150
	v_lshl_add_u64 v[136:137], v[132:133], 0, s[8:9]
	s_mov_b32 m0, s6
	s_mov_b64 s[22:23], 0x40f80
	v_readfirstlane_b32 s6, v151
	global_load_lds_dwordx4 v[136:137], off
	v_lshl_add_u64 v[136:137], v[132:133], 0, s[22:23]
	s_mov_b32 m0, s6
	s_mov_b64 s[24:25], 0x80f80
	v_readfirstlane_b32 s6, v152
	global_load_lds_dwordx4 v[136:137], off
	v_lshl_add_u64 v[136:137], v[132:133], 0, s[24:25]
	s_mov_b32 m0, s6
	s_mov_b64 s[40:41], 0xc0f80
	v_readfirstlane_b32 s6, v153
	global_load_lds_dwordx4 v[136:137], off
	v_lshl_add_u64 v[132:133], v[132:133], 0, s[40:41]
	s_mov_b32 m0, s6
	v_readfirstlane_b32 s6, v154
	global_load_lds_dwordx4 v[132:133], off
	v_lshl_add_u64 v[132:133], v[134:135], 0, s[8:9]
	s_mov_b32 m0, s6
	v_readfirstlane_b32 s6, v155
	global_load_lds_dwordx4 v[132:133], off
	v_lshl_add_u64 v[132:133], v[134:135], 0, s[22:23]
	s_mov_b32 m0, s6
	v_readfirstlane_b32 s6, v156
	global_load_lds_dwordx4 v[132:133], off
	v_lshl_add_u64 v[132:133], v[134:135], 0, s[24:25]
	s_mov_b32 m0, s6
	v_readfirstlane_b32 s6, v157
	global_load_lds_dwordx4 v[132:133], off
	v_lshl_add_u64 v[132:133], v[134:135], 0, s[40:41]
	s_mov_b32 m0, s6
	s_add_i32 s28, s60, -1
	global_load_lds_dwordx4 v[132:133], off
	s_lshl_b64 s[6:7], s[28:29], 25
	v_readlane_b32 s8, v253, 39
	v_readlane_b32 s9, v253, 40
	s_add_u32 s40, s8, s6
	v_lshlrev_b32_e32 v132, 6, v146
	s_addc_u32 s41, s9, s7
	v_readlane_b32 s6, v253, 27
	v_ashrrev_i32_e32 v133, 31, v132
	v_readlane_b32 s7, v253, 28
	v_lshlrev_b32_e32 v128, 3, v142
	s_nop 0
	v_lshl_add_u64 v[162:163], v[132:133], 0, s[6:7]
	v_lshlrev_b32_e32 v132, 4, v142
	v_mov_b32_e32 v133, v129
	s_add_i32 s6, 0, 0x10000
	v_or_b32_e32 v162, v162, v143
	v_lshl_add_u64 v[132:133], s[40:41], 0, v[132:133]
	v_add3_u32 v138, s6, v144, v147
	v_add3_u32 v139, s6, v149, v147
	v_add_u32_e32 v182, v139, v148
	v_add_u32_e32 v183, v138, v148
	ds_read_b128 v[134:137], v182 offset:32768
	ds_read_b128 v[146:149], v183
	ds_read_b128 v[150:153], v182 offset:36864
	ds_read_b128 v[154:157], v182 offset:40960
	ds_read_b128 v[158:161], v182 offset:45056
	ds_read_b128 v[192:195], v183 offset:4096
	v_add_u32_e32 v184, v139, v145
	v_add_u32_e32 v185, v138, v145
	ds_read_b128 v[196:199], v184 offset:32768
	ds_read_b128 v[220:223], v185
	ds_read_b128 v[200:203], v184 offset:36864
	ds_read_b128 v[204:207], v184 offset:40960
	ds_read_b128 v[216:219], v184 offset:45056
	ds_read_b128 v[224:227], v185 offset:4096
	s_waitcnt lgkmcnt(10)
	v_mfma_f32_32x32x16_bf16 v[112:127], v[134:137], v[146:149], v[112:127]
	s_waitcnt lgkmcnt(9)
	v_mfma_f32_32x32x16_bf16 v[96:111], v[150:153], v[146:149], v[96:111]
	s_waitcnt lgkmcnt(8)
	v_mfma_f32_32x32x16_bf16 v[80:95], v[154:157], v[146:149], v[80:95]
	s_waitcnt lgkmcnt(7)
	v_mfma_f32_32x32x16_bf16 v[64:79], v[158:161], v[146:149], v[64:79]
	s_waitcnt lgkmcnt(6)
	v_mfma_f32_32x32x16_bf16 v[48:63], v[134:137], v[192:195], v[48:63]
	v_mfma_f32_32x32x16_bf16 v[32:47], v[150:153], v[192:195], v[32:47]
	v_mfma_f32_32x32x16_bf16 v[16:31], v[154:157], v[192:195], v[16:31]
	v_mfma_f32_32x32x16_bf16 v[0:15], v[158:161], v[192:195], v[0:15]
	v_add_u32_e32 v182, v139, v141
	v_add_u32_e32 v183, v138, v141
	ds_read_b128 v[134:137], v182 offset:32768
	ds_read_b128 v[146:149], v183
	ds_read_b128 v[150:153], v182 offset:36864
	ds_read_b128 v[154:157], v182 offset:40960
	ds_read_b128 v[158:161], v182 offset:45056
	ds_read_b128 v[192:195], v183 offset:4096
	s_waitcnt lgkmcnt(10)
	v_mfma_f32_32x32x16_bf16 v[112:127], v[196:199], v[220:223], v[112:127]
	s_waitcnt lgkmcnt(9)
	v_mfma_f32_32x32x16_bf16 v[96:111], v[200:203], v[220:223], v[96:111]
	s_waitcnt lgkmcnt(8)
	v_mfma_f32_32x32x16_bf16 v[80:95], v[204:207], v[220:223], v[80:95]
	s_waitcnt lgkmcnt(7)
	v_mfma_f32_32x32x16_bf16 v[64:79], v[216:219], v[220:223], v[64:79]
	s_waitcnt lgkmcnt(6)
	v_mfma_f32_32x32x16_bf16 v[48:63], v[196:199], v[224:227], v[48:63]
	v_mfma_f32_32x32x16_bf16 v[32:47], v[200:203], v[224:227], v[32:47]
	v_mfma_f32_32x32x16_bf16 v[16:31], v[204:207], v[224:227], v[16:31]
	v_mfma_f32_32x32x16_bf16 v[0:15], v[216:219], v[224:227], v[0:15]
	v_add_u32_e32 v184, v139, v140
	v_add_u32_e32 v185, v138, v140
	ds_read_b128 v[196:199], v184 offset:32768
	ds_read_b128 v[220:223], v185
	ds_read_b128 v[200:203], v184 offset:36864
	ds_read_b128 v[204:207], v184 offset:40960
	ds_read_b128 v[216:219], v184 offset:45056
	ds_read_b128 v[224:227], v185 offset:4096
	s_waitcnt lgkmcnt(10)
	v_mfma_f32_32x32x16_bf16 v[112:127], v[134:137], v[146:149], v[112:127]
	s_waitcnt lgkmcnt(9)
	v_mfma_f32_32x32x16_bf16 v[96:111], v[150:153], v[146:149], v[96:111]
	s_waitcnt lgkmcnt(8)
	v_mfma_f32_32x32x16_bf16 v[80:95], v[154:157], v[146:149], v[80:95]
	s_waitcnt lgkmcnt(7)
	v_mfma_f32_32x32x16_bf16 v[64:79], v[158:161], v[146:149], v[64:79]
	s_waitcnt lgkmcnt(6)
	v_mfma_f32_32x32x16_bf16 v[48:63], v[134:137], v[192:195], v[48:63]
	v_mfma_f32_32x32x16_bf16 v[32:47], v[150:153], v[192:195], v[32:47]
	v_mfma_f32_32x32x16_bf16 v[16:31], v[154:157], v[192:195], v[16:31]
	v_mfma_f32_32x32x16_bf16 v[0:15], v[158:161], v[192:195], v[0:15]
	s_waitcnt lgkmcnt(4)
	v_mfma_f32_32x32x16_bf16 v[112:127], v[196:199], v[220:223], v[112:127]
	s_waitcnt lgkmcnt(3)
	v_mfma_f32_32x32x16_bf16 v[96:111], v[200:203], v[220:223], v[96:111]
	s_waitcnt lgkmcnt(2)
	v_mfma_f32_32x32x16_bf16 v[80:95], v[204:207], v[220:223], v[80:95]
	s_waitcnt lgkmcnt(1)
	v_mfma_f32_32x32x16_bf16 v[64:79], v[216:219], v[220:223], v[64:79]
	s_waitcnt lgkmcnt(0)
;     ...
;           for (int ni = 0; ni < 4; ++ni) acc[mi][ni] = MFMA(wf[ni], af[mi], acc[mi][ni]);
;         if (kk == 1) __builtin_amdgcn_sched_barrier(0);
;       }
;       __builtin_amdgcn_sched_barrier(0);
;     }
;     asm volatile("s_waitcnt vmcnt(0)" ::: "memory");
;     if ((s & (nk - 1)) == nk - 1) {
;       const int q = slot + (s >> lnk) * nslots;
;       int mt, nt; G_TILEMAP(q, mt, nt);
;       if (dostore) {
; #pragma unroll
;         for (int mi = 0; mi < 2; ++mi) {
;           const size_t m = (size_t)mt * 256 + wm * 64 + mi * 32 + r;
; #pragma unroll
;           for (int ni = 0; ni < 4; ++ni) {
;             __builtin_amdgcn_sched_barrier(0);
;             if (MODE == 0) {
; #pragma unroll
;               for (int gp = 0; gp < 2; ++gp) {
;                 const int g0 = 2 * gp;
;                 uint2 pa, pb;
;                 pa.x = pack2(acc[mi][ni][4 * g0], acc[mi][ni][4 * g0 + 1]); pa.y = pack2(acc[mi][ni][4 * g0 + 2], acc[mi][ni][4 * g0 + 3]);
;                 pb.x = pack2(acc[mi][ni][4 * g0 + 4], acc[mi][ni][4 * g0 + 5]); pb.y = pack2(acc[mi][ni][4 * g0 + 6], acc[mi][ni][4 * g0 + 7]);
;                 { auto rx = __builtin_amdgcn_permlane32_swap(pa.x, pb.x, false, false); pa.x = rx[0]; pb.x = rx[1]; }
;                 { auto ry = __builtin_amdgcn_permlane32_swap(pa.y, pb.y, false, false); pa.y = ry[0]; pb.y = ry[1]; }
;                 const int col = nt * 256 + wn * 128 + ni * 32 + 8 * g0 + 8 * hh;
;                 const uint4 v4 = make_uint4(pa.x, pa.y, pb.x, pb.y);
;                 if (outp != nullptr && nt >= 32) *(uint4*)(outp + m * 2048 + (col - 8192)) = v4;
;                 else if (col < nvalid) *(uint4*)(C + m * ldc + col) = v4;
;               }
;             } else if (MODE == 1) {
; #pragma unroll
;               for (int gp = 0; gp < 2; ++gp) {
;                 const int g0 = 2 * gp;
;                 const int nb_ = nt * 256 + wn * 128 + ni * 32 + 8 * g0;
;                 const uint2 ra = *(const uint2*)(res + m * 1024 + nb_ + 4 * hh), rb = *(const uint2*)(res + m * 1024 + nb_ + 8 + 4 * hh);
;                 uint2 pa, pb;
;                 pa.x = pack2(alpha * lo2f(ra.x) + acc[mi][ni][4 * g0], alpha * hi2f(ra.x) + acc[mi][ni][4 * g0 + 1]);
;                 pa.y = pack2(alpha * lo2f(ra.y) + acc[mi][ni][4 * g0 + 2], alpha * hi2f(ra.y) + acc[mi][ni][4 * g0 + 3]);
	v_mfma_f32_32x32x16_bf16 v[48:63], v[196:199], v[224:227], v[48:63]
	v_mfma_f32_32x32x16_bf16 v[32:47], v[200:203], v[224:227], v[32:47]
	v_mfma_f32_32x32x16_bf16 v[16:31], v[204:207], v[224:227], v[16:31]
	v_mfma_f32_32x32x16_bf16 v[0:15], v[216:219], v[224:227], v[0:15]
	s_waitcnt vmcnt(0)
	v_lshlrev_b64 v[136:137], 11, v[162:163]
	v_lshl_add_u64 v[138:139], s[40:41], 0, v[136:137]
	v_lshl_add_u64 v[144:145], v[132:133], 0, v[136:137]
	v_readlane_b32 s6, v251, 32
	s_lshl_b32 s6, s6, 1
	v_mov_b32_e32 v135, v129
	v_lshl_or_b32 v134, v131, 8, s6
	v_lshl_add_u64 v[138:139], v[138:139], 0, v[134:135]
	v_lshl_add_u64 v[138:139], v[138:139], 0, v[128:129]
	global_load_dwordx2 v[140:141], v[138:139], off
	global_load_dwordx2 v[142:143], v[138:139], off offset:16
	s_mov_b32 s6, 0x3fd744fd
	s_waitcnt vmcnt(0)
	v_lshlrev_b32_e32 v146, 16, v140
	v_and_b32_e32 v147, 0xffff0000, v140
	v_pk_fma_f32 v[112:113], v[146:147], s[6:7], v[112:113] op_sel_hi:[1,0,1]
	s_nop 0
	v_cvt_pk_bf16_f32 v140, v112, v113
	v_lshlrev_b32_e32 v112, 16, v141
	v_and_b32_e32 v113, 0xffff0000, v141
	v_pk_fma_f32 v[112:113], v[112:113], s[6:7], v[114:115] op_sel_hi:[1,0,1]
	s_nop 0
	v_cvt_pk_bf16_f32 v141, v112, v113
	v_lshlrev_b32_e32 v112, 16, v142
	v_and_b32_e32 v113, 0xffff0000, v142
	v_pk_fma_f32 v[112:113], v[112:113], s[6:7], v[116:117] op_sel_hi:[1,0,1]
	s_nop 0
	v_cvt_pk_bf16_f32 v142, v112, v113
	v_lshlrev_b32_e32 v112, 16, v143
	v_and_b32_e32 v113, 0xffff0000, v143
	v_pk_fma_f32 v[112:113], v[112:113], s[6:7], v[118:119] op_sel_hi:[1,0,1]
	v_permlane32_swap_b32_e32 v140, v142
	v_cvt_pk_bf16_f32 v143, v112, v113
	s_nop 1
	v_permlane32_swap_b32_e32 v141, v143
	v_lshl_add_u64 v[112:113], v[144:145], 0, v[134:135]
	global_store_dwordx4 v[112:113], v[140:143], off
	global_load_dwordx2 v[114:115], v[138:139], off offset:32
	global_load_dwordx2 v[116:117], v[138:139], off offset:48
	s_waitcnt vmcnt(1)
	v_lshlrev_b32_e32 v118, 16, v114
	v_and_b32_e32 v119, 0xffff0000, v114
	v_pk_fma_f32 v[118:119], v[118:119], s[6:7], v[120:121] op_sel_hi:[1,0,1]
	s_nop 0
	v_cvt_pk_bf16_f32 v114, v118, v119
	v_lshlrev_b32_e32 v118, 16, v115
	v_and_b32_e32 v119, 0xffff0000, v115
	v_pk_fma_f32 v[118:119], v[118:119], s[6:7], v[122:123] op_sel_hi:[1,0,1]
	s_nop 0
	v_cvt_pk_bf16_f32 v115, v118, v119
	s_waitcnt vmcnt(0)
	v_lshlrev_b32_e32 v118, 16, v116
	v_and_b32_e32 v119, 0xffff0000, v116
	v_pk_fma_f32 v[118:119], v[118:119], s[6:7], v[124:125] op_sel_hi:[1,0,1]
	s_nop 0
	v_cvt_pk_bf16_f32 v116, v118, v119
	v_lshlrev_b32_e32 v118, 16, v117
	v_and_b32_e32 v119, 0xffff0000, v117
	v_pk_fma_f32 v[118:119], v[118:119], s[6:7], v[126:127] op_sel_hi:[1,0,1]
	v_permlane32_swap_b32_e32 v114, v116
	v_cvt_pk_bf16_f32 v117, v118, v119
	s_nop 1
	v_permlane32_swap_b32_e32 v115, v117
	global_store_dwordx4 v[112:113], v[114:117], off offset:32
	global_load_dwordx2 v[114:115], v[138:139], off offset:64
	s_nop 0
	global_load_dwordx2 v[116:117], v[138:139], off offset:80
	s_waitcnt vmcnt(1)
	v_lshlrev_b32_e32 v118, 16, v114
	v_and_b32_e32 v119, 0xffff0000, v114
	v_lshlrev_b32_e32 v114, 16, v115
	v_and_b32_e32 v115, 0xffff0000, v115
	v_pk_fma_f32 v[96:97], v[118:119], s[6:7], v[96:97] op_sel_hi:[1,0,1]
	v_pk_fma_f32 v[98:99], v[114:115], s[6:7], v[98:99] op_sel_hi:[1,0,1]
	v_cvt_pk_bf16_f32 v96, v96, v97
	v_cvt_pk_bf16_f32 v97, v98, v99
	s_waitcnt vmcnt(0)
	v_lshlrev_b32_e32 v98, 16, v116
	v_and_b32_e32 v99, 0xffff0000, v116
	v_pk_fma_f32 v[98:99], v[98:99], s[6:7], v[100:101] op_sel_hi:[1,0,1]
	v_lshlrev_b32_e32 v100, 16, v117
	v_and_b32_e32 v101, 0xffff0000, v117
	v_pk_fma_f32 v[100:101], v[100:101], s[6:7], v[102:103] op_sel_hi:[1,0,1]
	v_cvt_pk_bf16_f32 v98, v98, v99
	v_cvt_pk_bf16_f32 v99, v100, v101
	s_nop 0
	v_permlane32_swap_b32_e32 v96, v98
	v_permlane32_swap_b32_e32 v97, v99
	global_store_dwordx4 v[112:113], v[96:99], off offset:64
	global_load_dwordx2 v[96:97], v[138:139], off offset:96
	s_nop 0
	global_load_dwordx2 v[98:99], v[138:139], off offset:112
	s_waitcnt vmcnt(1)
	v_lshlrev_b32_e32 v100, 16, v96
	v_and_b32_e32 v101, 0xffff0000, v96
	v_pk_fma_f32 v[100:101], v[100:101], s[6:7], v[104:105] op_sel_hi:[1,0,1]
	s_nop 0
	v_cvt_pk_bf16_f32 v96, v100, v101
	v_lshlrev_b32_e32 v100, 16, v97
	v_and_b32_e32 v101, 0xffff0000, v97
	v_pk_fma_f32 v[100:101], v[100:101], s[6:7], v[106:107] op_sel_hi:[1,0,1]
	s_nop 0
	v_cvt_pk_bf16_f32 v97, v100, v101
	s_waitcnt vmcnt(0)
	v_lshlrev_b32_e32 v100, 16, v98
	v_and_b32_e32 v101, 0xffff0000, v98
	v_pk_fma_f32 v[100:101], v[100:101], s[6:7], v[108:109] op_sel_hi:[1,0,1]
	s_nop 0
	v_cvt_pk_bf16_f32 v98, v100, v101
	v_lshlrev_b32_e32 v100, 16, v99
	v_and_b32_e32 v101, 0xffff0000, v99
	v_pk_fma_f32 v[100:101], v[100:101], s[6:7], v[110:111] op_sel_hi:[1,0,1]
	v_permlane32_swap_b32_e32 v96, v98
	v_cvt_pk_bf16_f32 v99, v100, v101
	s_nop 1
	v_permlane32_swap_b32_e32 v97, v99
	global_store_dwordx4 v[112:113], v[96:99], off offset:96
	global_load_dwordx2 v[96:97], v[138:139], off offset:128
	s_nop 0
	global_load_dwordx2 v[98:99], v[138:139], off offset:144
	s_waitcnt vmcnt(1)
	v_lshlrev_b32_e32 v100, 16, v96
	v_and_b32_e32 v101, 0xffff0000, v96
	v_lshlrev_b32_e32 v96, 16, v97
	v_and_b32_e32 v97, 0xffff0000, v97
	v_pk_fma_f32 v[80:81], v[100:101], s[6:7], v[80:81] op_sel_hi:[1,0,1]
	v_pk_fma_f32 v[82:83], v[96:97], s[6:7], v[82:83] op_sel_hi:[1,0,1]
	v_cvt_pk_bf16_f32 v80, v80, v81
	v_cvt_pk_bf16_f32 v81, v82, v83
	s_waitcnt vmcnt(0)
;     ...
;         for (int mi = 0; mi < 2; ++mi) {
;           const size_t m = (size_t)mt * 256 + wm * 64 + mi * 32 + r;
; #pragma unroll
;           for (int ni = 0; ni < 4; ++ni) {
;             __builtin_amdgcn_sched_barrier(0);
;             if (MODE == 0) {
; #pragma unroll
;               for (int gp = 0; gp < 2; ++gp) {
;                 const int g0 = 2 * gp;
;                 uint2 pa, pb;
;                 pa.x = pack2(acc[mi][ni][4 * g0], acc[mi][ni][4 * g0 + 1]); pa.y = pack2(acc[mi][ni][4 * g0 + 2], acc[mi][ni][4 * g0 + 3]);
;                 pb.x = pack2(acc[mi][ni][4 * g0 + 4], acc[mi][ni][4 * g0 + 5]); pb.y = pack2(acc[mi][ni][4 * g0 + 6], acc[mi][ni][4 * g0 + 7]);
;                 { auto rx = __builtin_amdgcn_permlane32_swap(pa.x, pb.x, false, false); pa.x = rx[0]; pb.x = rx[1]; }
;                 { auto ry = __builtin_amdgcn_permlane32_swap(pa.y, pb.y, false, false); pa.y = ry[0]; pb.y = ry[1]; }
;                 const int col = nt * 256 + wn * 128 + ni * 32 + 8 * g0 + 8 * hh;
;                 const uint4 v4 = make_uint4(pa.x, pa.y, pb.x, pb.y);
;                 if (outp != nullptr && nt >= 32) *(uint4*)(outp + m * 2048 + (col - 8192)) = v4;
;                 else if (col < nvalid) *(uint4*)(C + m * ldc + col) = v4;
;               }
;             } else if (MODE == 1) {
; #pragma unroll
;               for (int gp = 0; gp < 2; ++gp) {
;                 const int g0 = 2 * gp;
;                 const int nb_ = nt * 256 + wn * 128 + ni * 32 + 8 * g0;
;                 const uint2 ra = *(const uint2*)(res + m * 1024 + nb_ + 4 * hh), rb = *(const uint2*)(res + m * 1024 + nb_ + 8 + 4 * hh);
;                 uint2 pa, pb;
;                 pa.x = pack2(alpha * lo2f(ra.x) + acc[mi][ni][4 * g0], alpha * hi2f(ra.x) + acc[mi][ni][4 * g0 + 1]);
;                 pa.y = pack2(alpha * lo2f(ra.y) + acc[mi][ni][4 * g0 + 2], alpha * hi2f(ra.y) + acc[mi][ni][4 * g0 + 3]);
;                 pb.x = pack2(alpha * lo2f(rb.x) + acc[mi][ni][4 * g0 + 4], alpha * hi2f(rb.x) + acc[mi][ni][4 * g0 + 5]);
;                 pb.y = pack2(alpha * lo2f(rb.y) + acc[mi][ni][4 * g0 + 6], alpha * hi2f(rb.y) + acc[mi][ni][4 * g0 + 7]);
;                 { auto rx = __builtin_amdgcn_permlane32_swap(pa.x, pb.x, false, false); pa.x = rx[0]; pb.x = rx[1]; }
;                 { auto ry = __builtin_amdgcn_permlane32_swap(pa.y, pb.y, false, false); pa.y = ry[0]; pb.y = ry[1]; }
	v_lshlrev_b32_e32 v82, 16, v98
	v_and_b32_e32 v83, 0xffff0000, v98
	v_pk_fma_f32 v[82:83], v[82:83], s[6:7], v[84:85] op_sel_hi:[1,0,1]
	v_lshlrev_b32_e32 v84, 16, v99
	v_and_b32_e32 v85, 0xffff0000, v99
	v_pk_fma_f32 v[84:85], v[84:85], s[6:7], v[86:87] op_sel_hi:[1,0,1]
	v_cvt_pk_bf16_f32 v82, v82, v83
	v_cvt_pk_bf16_f32 v83, v84, v85
	s_nop 0
	v_permlane32_swap_b32_e32 v80, v82
	v_permlane32_swap_b32_e32 v81, v83
	global_store_dwordx4 v[112:113], v[80:83], off offset:128
	global_load_dwordx2 v[80:81], v[138:139], off offset:160
	s_nop 0
	global_load_dwordx2 v[82:83], v[138:139], off offset:176
	s_waitcnt vmcnt(1)
	v_lshlrev_b32_e32 v84, 16, v80
	v_and_b32_e32 v85, 0xffff0000, v80
	v_pk_fma_f32 v[84:85], v[84:85], s[6:7], v[88:89] op_sel_hi:[1,0,1]
	s_nop 0
	v_cvt_pk_bf16_f32 v80, v84, v85
	v_lshlrev_b32_e32 v84, 16, v81
	v_and_b32_e32 v85, 0xffff0000, v81
	v_pk_fma_f32 v[84:85], v[84:85], s[6:7], v[90:91] op_sel_hi:[1,0,1]
	s_nop 0
	v_cvt_pk_bf16_f32 v81, v84, v85
	s_waitcnt vmcnt(0)
	v_lshlrev_b32_e32 v84, 16, v82
	v_and_b32_e32 v85, 0xffff0000, v82
	v_pk_fma_f32 v[84:85], v[84:85], s[6:7], v[92:93] op_sel_hi:[1,0,1]
	s_nop 0
	v_cvt_pk_bf16_f32 v82, v84, v85
	v_lshlrev_b32_e32 v84, 16, v83
	v_and_b32_e32 v85, 0xffff0000, v83
	v_pk_fma_f32 v[84:85], v[84:85], s[6:7], v[94:95] op_sel_hi:[1,0,1]
	v_permlane32_swap_b32_e32 v80, v82
	v_cvt_pk_bf16_f32 v83, v84, v85
	s_nop 1
	v_permlane32_swap_b32_e32 v81, v83
	global_store_dwordx4 v[112:113], v[80:83], off offset:160
	global_load_dwordx2 v[80:81], v[138:139], off offset:192
	s_nop 0
	global_load_dwordx2 v[82:83], v[138:139], off offset:208
	v_or_b32_e32 v136, 0x10000, v136
	s_waitcnt vmcnt(1)
	v_lshlrev_b32_e32 v84, 16, v80
	v_and_b32_e32 v85, 0xffff0000, v80
	v_lshlrev_b32_e32 v80, 16, v81
	v_and_b32_e32 v81, 0xffff0000, v81
	v_pk_fma_f32 v[64:65], v[84:85], s[6:7], v[64:65] op_sel_hi:[1,0,1]
	v_pk_fma_f32 v[66:67], v[80:81], s[6:7], v[66:67] op_sel_hi:[1,0,1]
	v_cvt_pk_bf16_f32 v64, v64, v65
	v_cvt_pk_bf16_f32 v65, v66, v67
	s_waitcnt vmcnt(0)
	v_lshlrev_b32_e32 v66, 16, v82
	v_and_b32_e32 v67, 0xffff0000, v82
	v_pk_fma_f32 v[66:67], v[66:67], s[6:7], v[68:69] op_sel_hi:[1,0,1]
	v_lshlrev_b32_e32 v68, 16, v83
	v_and_b32_e32 v69, 0xffff0000, v83
	v_pk_fma_f32 v[68:69], v[68:69], s[6:7], v[70:71] op_sel_hi:[1,0,1]
	v_cvt_pk_bf16_f32 v66, v66, v67
	v_cvt_pk_bf16_f32 v67, v68, v69
	s_nop 0
	v_permlane32_swap_b32_e32 v64, v66
	v_permlane32_swap_b32_e32 v65, v67
	global_store_dwordx4 v[112:113], v[64:67], off offset:192
	global_load_dwordx2 v[64:65], v[138:139], off offset:224
	s_nop 0
	global_load_dwordx2 v[66:67], v[138:139], off offset:240
	v_lshl_add_u64 v[70:71], v[132:133], 0, v[136:137]
	s_waitcnt vmcnt(1)
	v_lshlrev_b32_e32 v68, 16, v64
	v_and_b32_e32 v69, 0xffff0000, v64
	v_pk_fma_f32 v[68:69], v[68:69], s[6:7], v[72:73] op_sel_hi:[1,0,1]
	s_nop 0
	v_cvt_pk_bf16_f32 v64, v68, v69
	v_lshlrev_b32_e32 v68, 16, v65
	v_and_b32_e32 v69, 0xffff0000, v65
	v_pk_fma_f32 v[68:69], v[68:69], s[6:7], v[74:75] op_sel_hi:[1,0,1]
	s_nop 0
	v_cvt_pk_bf16_f32 v65, v68, v69
	s_waitcnt vmcnt(0)
	v_lshlrev_b32_e32 v68, 16, v66
	v_and_b32_e32 v69, 0xffff0000, v66
	v_pk_fma_f32 v[68:69], v[68:69], s[6:7], v[76:77] op_sel_hi:[1,0,1]
	s_nop 0
	v_cvt_pk_bf16_f32 v66, v68, v69
	v_lshlrev_b32_e32 v68, 16, v67
	v_and_b32_e32 v69, 0xffff0000, v67
	v_pk_fma_f32 v[68:69], v[68:69], s[6:7], v[78:79] op_sel_hi:[1,0,1]
	v_permlane32_swap_b32_e32 v64, v66
	v_cvt_pk_bf16_f32 v67, v68, v69
	s_nop 1
	v_permlane32_swap_b32_e32 v65, v67
	global_store_dwordx4 v[112:113], v[64:67], off offset:224
	s_nop 1
	v_lshl_add_u64 v[64:65], s[40:41], 0, v[136:137]
	v_lshl_add_u64 v[64:65], v[64:65], 0, v[134:135]
	v_lshl_add_u64 v[64:65], v[64:65], 0, v[128:129]
	global_load_dwordx2 v[66:67], v[64:65], off
	global_load_dwordx2 v[68:69], v[64:65], off offset:16
	s_waitcnt vmcnt(1)
	v_lshlrev_b32_e32 v72, 16, v66
	v_and_b32_e32 v73, 0xffff0000, v66
	v_pk_fma_f32 v[48:49], v[72:73], s[6:7], v[48:49] op_sel_hi:[1,0,1]
	s_nop 0
	v_cvt_pk_bf16_f32 v66, v48, v49
	v_lshlrev_b32_e32 v48, 16, v67
	v_and_b32_e32 v49, 0xffff0000, v67
	v_pk_fma_f32 v[48:49], v[48:49], s[6:7], v[50:51] op_sel_hi:[1,0,1]
	s_nop 0
	v_cvt_pk_bf16_f32 v67, v48, v49
	s_waitcnt vmcnt(0)
	v_lshlrev_b32_e32 v48, 16, v68
	v_and_b32_e32 v49, 0xffff0000, v68
	v_pk_fma_f32 v[48:49], v[48:49], s[6:7], v[52:53] op_sel_hi:[1,0,1]
	s_nop 0
	v_cvt_pk_bf16_f32 v68, v48, v49
	v_lshlrev_b32_e32 v48, 16, v69
	v_and_b32_e32 v49, 0xffff0000, v69
	v_pk_fma_f32 v[48:49], v[48:49], s[6:7], v[54:55] op_sel_hi:[1,0,1]
	v_permlane32_swap_b32_e32 v66, v68
	v_cvt_pk_bf16_f32 v69, v48, v49
	s_nop 1
	v_permlane32_swap_b32_e32 v67, v69
	v_lshl_add_u64 v[48:49], v[70:71], 0, v[134:135]
	global_store_dwordx4 v[48:49], v[66:69], off
	global_load_dwordx2 v[50:51], v[64:65], off offset:32
	global_load_dwordx2 v[52:53], v[64:65], off offset:48
	s_waitcnt vmcnt(1)
	v_lshlrev_b32_e32 v54, 16, v50
	v_and_b32_e32 v55, 0xffff0000, v50
	v_pk_fma_f32 v[54:55], v[54:55], s[6:7], v[56:57] op_sel_hi:[1,0,1]
	s_nop 0
	v_cvt_pk_bf16_f32 v50, v54, v55
	v_lshlrev_b32_e32 v54, 16, v51
	v_and_b32_e32 v55, 0xffff0000, v51
	v_pk_fma_f32 v[54:55], v[54:55], s[6:7], v[58:59] op_sel_hi:[1,0,1]
	s_nop 0
	v_cvt_pk_bf16_f32 v51, v54, v55
	s_waitcnt vmcnt(0)
	v_lshlrev_b32_e32 v54, 16, v52
	v_and_b32_e32 v55, 0xffff0000, v52
	v_pk_fma_f32 v[54:55], v[54:55], s[6:7], v[60:61] op_sel_hi:[1,0,1]
	s_nop 0
	v_cvt_pk_bf16_f32 v52, v54, v55
	v_lshlrev_b32_e32 v54, 16, v53
	v_and_b32_e32 v55, 0xffff0000, v53
	v_pk_fma_f32 v[54:55], v[54:55], s[6:7], v[62:63] op_sel_hi:[1,0,1]
	v_permlane32_swap_b32_e32 v50, v52
	v_cvt_pk_bf16_f32 v53, v54, v55
	s_nop 1
	v_permlane32_swap_b32_e32 v51, v53
	global_store_dwordx4 v[48:49], v[50:53], off offset:32
	global_load_dwordx2 v[50:51], v[64:65], off offset:64
	s_nop 0
	global_load_dwordx2 v[52:53], v[64:65], off offset:80
	s_waitcnt vmcnt(1)
;     ...
;         for (int mi = 0; mi < 2; ++mi) {
;           const size_t m = (size_t)mt * 256 + wm * 64 + mi * 32 + r;
; #pragma unroll
;           for (int ni = 0; ni < 4; ++ni) {
;             __builtin_amdgcn_sched_barrier(0);
;             if (MODE == 0) {
; #pragma unroll
;               for (int gp = 0; gp < 2; ++gp) {
;                 const int g0 = 2 * gp;
;                 uint2 pa, pb;
;                 pa.x = pack2(acc[mi][ni][4 * g0], acc[mi][ni][4 * g0 + 1]); pa.y = pack2(acc[mi][ni][4 * g0 + 2], acc[mi][ni][4 * g0 + 3]);
;                 pb.x = pack2(acc[mi][ni][4 * g0 + 4], acc[mi][ni][4 * g0 + 5]); pb.y = pack2(acc[mi][ni][4 * g0 + 6], acc[mi][ni][4 * g0 + 7]);
;                 { auto rx = __builtin_amdgcn_permlane32_swap(pa.x, pb.x, false, false); pa.x = rx[0]; pb.x = rx[1]; }
;                 { auto ry = __builtin_amdgcn_permlane32_swap(pa.y, pb.y, false, false); pa.y = ry[0]; pb.y = ry[1]; }
;                 const int col = nt * 256 + wn * 128 + ni * 32 + 8 * g0 + 8 * hh;
;                 const uint4 v4 = make_uint4(pa.x, pa.y, pb.x, pb.y);
;                 if (outp != nullptr && nt >= 32) *(uint4*)(outp + m * 2048 + (col - 8192)) = v4;
;                 else if (col < nvalid) *(uint4*)(C + m * ldc + col) = v4;
;               }
;             } else if (MODE == 1) {
; #pragma unroll
;               for (int gp = 0; gp < 2; ++gp) {
;                 const int g0 = 2 * gp;
;                 const int nb_ = nt * 256 + wn * 128 + ni * 32 + 8 * g0;
;                 const uint2 ra = *(const uint2*)(res + m * 1024 + nb_ + 4 * hh), rb = *(const uint2*)(res + m * 1024 + nb_ + 8 + 4 * hh);
;                 uint2 pa, pb;
;                 pa.x = pack2(alpha * lo2f(ra.x) + acc[mi][ni][4 * g0], alpha * hi2f(ra.x) + acc[mi][ni][4 * g0 + 1]);
;                 pa.y = pack2(alpha * lo2f(ra.y) + acc[mi][ni][4 * g0 + 2], alpha * hi2f(ra.y) + acc[mi][ni][4 * g0 + 3]);
;                 pb.x = pack2(alpha * lo2f(rb.x) + acc[mi][ni][4 * g0 + 4], alpha * hi2f(rb.x) + acc[mi][ni][4 * g0 + 5]);
;                 pb.y = pack2(alpha * lo2f(rb.y) + acc[mi][ni][4 * g0 + 6], alpha * hi2f(rb.y) + acc[mi][ni][4 * g0 + 7]);
;                 { auto rx = __builtin_amdgcn_permlane32_swap(pa.x, pb.x, false, false); pa.x = rx[0]; pb.x = rx[1]; }
;                 { auto ry = __builtin_amdgcn_permlane32_swap(pa.y, pb.y, false, false); pa.y = ry[0]; pb.y = ry[1]; }
	v_lshlrev_b32_e32 v54, 16, v50
	v_and_b32_e32 v55, 0xffff0000, v50
	v_lshlrev_b32_e32 v50, 16, v51
	v_and_b32_e32 v51, 0xffff0000, v51
	v_pk_fma_f32 v[32:33], v[54:55], s[6:7], v[32:33] op_sel_hi:[1,0,1]
	v_pk_fma_f32 v[34:35], v[50:51], s[6:7], v[34:35] op_sel_hi:[1,0,1]
	v_cvt_pk_bf16_f32 v32, v32, v33
	v_cvt_pk_bf16_f32 v33, v34, v35
	s_waitcnt vmcnt(0)
	v_lshlrev_b32_e32 v34, 16, v52
	v_and_b32_e32 v35, 0xffff0000, v52
	v_pk_fma_f32 v[34:35], v[34:35], s[6:7], v[36:37] op_sel_hi:[1,0,1]
	v_lshlrev_b32_e32 v36, 16, v53
	v_and_b32_e32 v37, 0xffff0000, v53
	v_pk_fma_f32 v[36:37], v[36:37], s[6:7], v[38:39] op_sel_hi:[1,0,1]
	v_cvt_pk_bf16_f32 v34, v34, v35
	v_cvt_pk_bf16_f32 v35, v36, v37
	s_nop 0
	v_permlane32_swap_b32_e32 v32, v34
	v_permlane32_swap_b32_e32 v33, v35
	global_store_dwordx4 v[48:49], v[32:35], off offset:64
	global_load_dwordx2 v[32:33], v[64:65], off offset:96
	s_nop 0
	global_load_dwordx2 v[34:35], v[64:65], off offset:112
	s_waitcnt vmcnt(1)
	v_lshlrev_b32_e32 v36, 16, v32
	v_and_b32_e32 v37, 0xffff0000, v32
	v_pk_fma_f32 v[36:37], v[36:37], s[6:7], v[40:41] op_sel_hi:[1,0,1]
	s_nop 0
	v_cvt_pk_bf16_f32 v32, v36, v37
	v_lshlrev_b32_e32 v36, 16, v33
	v_and_b32_e32 v37, 0xffff0000, v33
	v_pk_fma_f32 v[36:37], v[36:37], s[6:7], v[42:43] op_sel_hi:[1,0,1]
	s_nop 0
	v_cvt_pk_bf16_f32 v33, v36, v37
	s_waitcnt vmcnt(0)
	v_lshlrev_b32_e32 v36, 16, v34
	v_and_b32_e32 v37, 0xffff0000, v34
	v_pk_fma_f32 v[36:37], v[36:37], s[6:7], v[44:45] op_sel_hi:[1,0,1]
	s_nop 0
	v_cvt_pk_bf16_f32 v34, v36, v37
	v_lshlrev_b32_e32 v36, 16, v35
	v_and_b32_e32 v37, 0xffff0000, v35
	v_pk_fma_f32 v[36:37], v[36:37], s[6:7], v[46:47] op_sel_hi:[1,0,1]
	v_permlane32_swap_b32_e32 v32, v34
	v_cvt_pk_bf16_f32 v35, v36, v37
	s_nop 1
	v_permlane32_swap_b32_e32 v33, v35
	global_store_dwordx4 v[48:49], v[32:35], off offset:96
	global_load_dwordx2 v[32:33], v[64:65], off offset:128
	s_nop 0
	global_load_dwordx2 v[34:35], v[64:65], off offset:144
	s_waitcnt vmcnt(1)
	v_lshlrev_b32_e32 v36, 16, v32
	v_and_b32_e32 v37, 0xffff0000, v32
	v_lshlrev_b32_e32 v32, 16, v33
	v_and_b32_e32 v33, 0xffff0000, v33
	v_pk_fma_f32 v[16:17], v[36:37], s[6:7], v[16:17] op_sel_hi:[1,0,1]
	v_pk_fma_f32 v[18:19], v[32:33], s[6:7], v[18:19] op_sel_hi:[1,0,1]
	v_cvt_pk_bf16_f32 v16, v16, v17
	v_cvt_pk_bf16_f32 v17, v18, v19
	s_waitcnt vmcnt(0)
	v_lshlrev_b32_e32 v18, 16, v34
	v_and_b32_e32 v19, 0xffff0000, v34
	v_pk_fma_f32 v[18:19], v[18:19], s[6:7], v[20:21] op_sel_hi:[1,0,1]
	v_lshlrev_b32_e32 v20, 16, v35
	v_and_b32_e32 v21, 0xffff0000, v35
	v_pk_fma_f32 v[20:21], v[20:21], s[6:7], v[22:23] op_sel_hi:[1,0,1]
	v_cvt_pk_bf16_f32 v18, v18, v19
	v_cvt_pk_bf16_f32 v19, v20, v21
	s_nop 0
	v_permlane32_swap_b32_e32 v16, v18
	v_permlane32_swap_b32_e32 v17, v19
	global_store_dwordx4 v[48:49], v[16:19], off offset:128
	global_load_dwordx2 v[16:17], v[64:65], off offset:160
	s_nop 0
	global_load_dwordx2 v[18:19], v[64:65], off offset:176
	s_waitcnt vmcnt(1)
	v_lshlrev_b32_e32 v20, 16, v16
	v_and_b32_e32 v21, 0xffff0000, v16
	v_pk_fma_f32 v[20:21], v[20:21], s[6:7], v[24:25] op_sel_hi:[1,0,1]
	s_nop 0
	v_cvt_pk_bf16_f32 v16, v20, v21
	v_lshlrev_b32_e32 v20, 16, v17
	v_and_b32_e32 v21, 0xffff0000, v17
	v_pk_fma_f32 v[20:21], v[20:21], s[6:7], v[26:27] op_sel_hi:[1,0,1]
	s_nop 0
	v_cvt_pk_bf16_f32 v17, v20, v21
	s_waitcnt vmcnt(0)
	v_lshlrev_b32_e32 v20, 16, v18
	v_and_b32_e32 v21, 0xffff0000, v18
	v_pk_fma_f32 v[20:21], v[20:21], s[6:7], v[28:29] op_sel_hi:[1,0,1]
	s_nop 0
	v_cvt_pk_bf16_f32 v18, v20, v21
	v_lshlrev_b32_e32 v20, 16, v19
	v_and_b32_e32 v21, 0xffff0000, v19
	v_pk_fma_f32 v[20:21], v[20:21], s[6:7], v[30:31] op_sel_hi:[1,0,1]
	v_permlane32_swap_b32_e32 v16, v18
	v_cvt_pk_bf16_f32 v19, v20, v21
	s_nop 1
	v_permlane32_swap_b32_e32 v17, v19
	global_store_dwordx4 v[48:49], v[16:19], off offset:160
	global_load_dwordx2 v[16:17], v[64:65], off offset:192
	s_nop 0
	global_load_dwordx2 v[18:19], v[64:65], off offset:208
	s_waitcnt vmcnt(1)
	v_lshlrev_b32_e32 v20, 16, v16
	v_and_b32_e32 v21, 0xffff0000, v16
	v_lshlrev_b32_e32 v16, 16, v17
	v_and_b32_e32 v17, 0xffff0000, v17
	v_pk_fma_f32 v[0:1], v[20:21], s[6:7], v[0:1] op_sel_hi:[1,0,1]
	v_pk_fma_f32 v[2:3], v[16:17], s[6:7], v[2:3] op_sel_hi:[1,0,1]
	v_cvt_pk_bf16_f32 v0, v0, v1
	v_cvt_pk_bf16_f32 v1, v2, v3
	s_waitcnt vmcnt(0)
	v_lshlrev_b32_e32 v2, 16, v18
	v_and_b32_e32 v3, 0xffff0000, v18
	v_pk_fma_f32 v[2:3], v[2:3], s[6:7], v[4:5] op_sel_hi:[1,0,1]
	v_lshlrev_b32_e32 v4, 16, v19
	v_and_b32_e32 v5, 0xffff0000, v19
	v_pk_fma_f32 v[4:5], v[4:5], s[6:7], v[6:7] op_sel_hi:[1,0,1]
	v_cvt_pk_bf16_f32 v2, v2, v3
	v_cvt_pk_bf16_f32 v3, v4, v5
	s_nop 0
	v_permlane32_swap_b32_e32 v0, v2
	v_permlane32_swap_b32_e32 v1, v3
	global_store_dwordx4 v[48:49], v[0:3], off offset:192
	global_load_dwordx2 v[0:1], v[64:65], off offset:224
	s_nop 0
	global_load_dwordx2 v[2:3], v[64:65], off offset:240
	s_waitcnt vmcnt(1)
	v_lshlrev_b32_e32 v4, 16, v0
	v_and_b32_e32 v5, 0xffff0000, v0
	v_pk_fma_f32 v[4:5], v[4:5], s[6:7], v[8:9] op_sel_hi:[1,0,1]
	s_nop 0
	v_cvt_pk_bf16_f32 v0, v4, v5
	v_lshlrev_b32_e32 v4, 16, v1
	v_and_b32_e32 v5, 0xffff0000, v1
	v_pk_fma_f32 v[4:5], v[4:5], s[6:7], v[10:11] op_sel_hi:[1,0,1]
	s_nop 0
	v_cvt_pk_bf16_f32 v1, v4, v5
	s_waitcnt vmcnt(0)
	v_lshlrev_b32_e32 v4, 16, v2
	v_and_b32_e32 v5, 0xffff0000, v2
	v_pk_fma_f32 v[4:5], v[4:5], s[6:7], v[12:13] op_sel_hi:[1,0,1]
	s_nop 0
	v_cvt_pk_bf16_f32 v2, v4, v5
	v_lshlrev_b32_e32 v4, 16, v3
	v_and_b32_e32 v5, 0xffff0000, v3
	v_pk_fma_f32 v[4:5], v[4:5], s[6:7], v[14:15] op_sel_hi:[1,0,1]
	v_permlane32_swap_b32_e32 v0, v2
	v_cvt_pk_bf16_f32 v3, v4, v5
	s_nop 1
	v_permlane32_swap_b32_e32 v1, v3
	global_store_dwordx4 v[48:49], v[0:3], off offset:224
	s_waitcnt lgkmcnt(0)
	s_barrier
	s_waitcnt vmcnt(0)
	s_barrier

; #define MFMA(a, b, c) __builtin_amdgcn_mfma_f32_32x32x16_bf16((a), (b), (c), 0, 0, 0)
;     ...
;   const int fP = r * 128, fsw = (r >> 1) & 7;
;   const int fA = wm * 8192 + fP, fB = 32768 + wn * 16384 + fP;
;   f32x16 acc[2][4];
; #pragma unroll
;   for (int i = 0; i < 2; ++i)
; #pragma unroll
;     for (int j = 0; j < 4; ++j) acc[i][j] = zero16();
;   __syncthreads();
;   G_DMA(0, 0);
;   asm volatile("s_waitcnt vmcnt(0)" ::: "memory");
;   asm volatile("s_waitcnt lgkmcnt(0)" ::: "memory"); __builtin_amdgcn_s_barrier(); asm volatile("" ::: "memory");
;   int cur = 0;
;   for (int s = 0; s < S; ++s) {
;     G_DMA(s + 1, cur ^ BUFB);
;     {
;       const char* Ab = smem + cur + fA;
;       const char* Bb = smem + cur + fB;
;       __builtin_amdgcn_sched_barrier(0);
; #pragma unroll
;       for (int kk = 0; kk < 4; ++kk) {
;         const int ko = (((kk * 2 + hh) ^ fsw) << 4);
;         bf16x8 af[2], wf[4];
;         af[0] = *(const bf16x8*)(Ab + ko); af[1] = *(const bf16x8*)(Ab + 4096 + ko);
; #pragma unroll
;         for (int ni = 0; ni < 4; ++ni) wf[ni] = *(const bf16x8*)(Bb + ni * 4096 + ko);
; #pragma unroll
;         for (int mi = 0; mi < 2; ++mi)
; #pragma unroll
;           for (int ni = 0; ni < 4; ++ni) acc[mi][ni] = MFMA(wf[ni], af[mi], acc[mi][ni]);
;         if (kk == 1) __builtin_amdgcn_sched_barrier(0);
;       }
;       __builtin_amdgcn_sched_barrier(0);
;     }
;     asm volatile("s_waitcnt vmcnt(0)" ::: "memory");
;     ...
;                 const int g0 = 2 * gp;
;                 uint2 pa, pb;
;                 pa.x = pack2(acc[mi][ni][4 * g0], acc[mi][ni][4 * g0 + 1]); pa.y = pack2(acc[mi][ni][4 * g0 + 2], acc[mi][ni][4 * g0 + 3]);
;                 pb.x = pack2(acc[mi][ni][4 * g0 + 4], acc[mi][ni][4 * g0 + 5]); pb.y = pack2(acc[mi][ni][4 * g0 + 6], acc[mi][ni][4 * g0 + 7]);
;                 { auto rx = __builtin_amdgcn_permlane32_swap(pa.x, pb.x, false, false); pa.x = rx[0]; pb.x = rx[1]; }
;                 { auto ry = __builtin_amdgcn_permlane32_swap(pa.y, pb.y, false, false); pa.y = ry[0]; pb.y = ry[1]; }
;                 const int col = nt * 256 + wn * 128 + ni * 32 + 8 * g0 + 8 * hh;
;                 const uint4 v4 = make_uint4(pa.x, pa.y, pb.x, pb.y);
;                 if (outp != nullptr && nt >= 32) *(uint4*)(outp + m * 2048 + (col - 8192)) = v4;
;                 else if (col < nvalid) *(uint4*)(C + m * ldc + col) = v4;
.LBB0_741:
	v_add3_u32 v187, s6, v131, v140
	v_add3_u32 v208, s6, v141, v140
	v_add_u32_e32 v182, v208, v144
	v_add_u32_e32 v183, v187, v144
	ds_read_b128 v[192:195], v182 offset:32768
	ds_read_b128 v[216:219], v183
	ds_read_b128 v[196:199], v182 offset:36864
	ds_read_b128 v[200:203], v182 offset:40960
	ds_read_b128 v[204:207], v182 offset:45056
	ds_read_b128 v[220:223], v183 offset:4096
	v_add_u32_e32 v184, v208, v145
	v_add_u32_e32 v185, v187, v145
	ds_read_b128 v[224:227], v184 offset:32768
	ds_read_b128 v[240:243], v185
	ds_read_b128 v[228:231], v184 offset:36864
	ds_read_b128 v[232:235], v184 offset:40960
	ds_read_b128 v[236:239], v184 offset:45056
	ds_read_b128 v[244:247], v185 offset:4096
	s_add_i32 s7, s8, 1
	s_mov_b32 s9, s6
	s_cmp_lt_u32 s7, s22
	v_readlane_b32 s6, v251, 36
	s_cselect_b32 s24, s7, s6
	s_lshl_b32 s6, s24, 1
	s_and_b32 s6, s6, 0x7ffffe0
	s_add_i32 s6, s6, s33
	s_lshl_b32 s6, s6, 5
	s_and_b32 s22, s6, 0xffffff00
	s_ashr_i32 s23, s22, 31
	s_lshl_b64 s[22:23], s[22:23], 11
	s_add_u32 s22, s62, s22
	s_addc_u32 s23, s63, s23
	s_xor_b32 s6, s9, 0x10000
	v_add_u32_e32 v128, s6, v142
	s_lshl_b32 s24, s24, 7
	s_and_b32 s28, s24, 0x780
	v_readfirstlane_b32 s24, v128
	v_add_u32_e32 v152, 0x2000, v128
	v_lshl_add_u64 v[148:149], v[134:135], 0, s[28:29]
	s_mov_b32 m0, s24
	s_mov_b64 s[44:45], 0x20000
	v_readfirstlane_b32 s24, v152
	v_add_u32_e32 v152, 0x4000, v128
	global_load_lds_dwordx4 v[148:149], off
	s_waitcnt lgkmcnt(10)
	v_mfma_f32_32x32x16_bf16 v[112:127], v[192:195], v[216:219], v[112:127]
	s_waitcnt lgkmcnt(9)
	v_mfma_f32_32x32x16_bf16 v[96:111], v[196:199], v[216:219], v[96:111]
	v_lshl_add_u64 v[150:151], v[148:149], 0, s[44:45]
	s_mov_b32 m0, s24
	s_mov_b64 s[42:43], 0x40000
	v_readfirstlane_b32 s24, v152
	global_load_lds_dwordx4 v[150:151], off
	s_waitcnt lgkmcnt(8)
	v_mfma_f32_32x32x16_bf16 v[80:95], v[200:203], v[216:219], v[80:95]
	s_waitcnt lgkmcnt(7)
	v_mfma_f32_32x32x16_bf16 v[64:79], v[204:207], v[216:219], v[64:79]
	v_lshl_add_u64 v[150:151], v[148:149], 0, s[42:43]
	s_mov_b32 m0, s24
	s_mov_b64 s[46:47], 0x60000
	global_load_lds_dwordx4 v[150:151], off
	s_waitcnt lgkmcnt(6)
	v_mfma_f32_32x32x16_bf16 v[48:63], v[192:195], v[220:223], v[48:63]
	v_mfma_f32_32x32x16_bf16 v[32:47], v[196:199], v[220:223], v[32:47]
	v_add_u32_e32 v150, 0x6000, v128
	s_add_u32 s22, s22, s28
	v_readfirstlane_b32 s24, v150
	v_lshl_add_u64 v[148:149], v[148:149], 0, s[46:47]
	s_mov_b32 m0, s24
	s_addc_u32 s23, s23, 0
	v_add_u32_e32 v150, 0x8000, v128
	global_load_lds_dwordx4 v[148:149], off
	v_mfma_f32_32x32x16_bf16 v[16:31], v[200:203], v[220:223], v[16:31]
	v_mfma_f32_32x32x16_bf16 v[0:15], v[204:207], v[220:223], v[0:15]
	v_lshl_add_u64 v[148:149], s[22:23], 0, v[132:133]
	v_readfirstlane_b32 s22, v150
	v_add_u32_e32 v152, 0xa000, v128
	s_mov_b32 m0, s22
	v_readfirstlane_b32 s22, v152
	v_add_u32_e32 v152, 0xc000, v128
	global_load_lds_dwordx4 v[148:149], off
	v_add_u32_e32 v182, v208, v146
	v_add_u32_e32 v183, v187, v146
	ds_read_b128 v[192:195], v182 offset:32768
	ds_read_b128 v[216:219], v183
	ds_read_b128 v[196:199], v182 offset:36864
	ds_read_b128 v[200:203], v182 offset:40960
	ds_read_b128 v[204:207], v182 offset:45056
	ds_read_b128 v[220:223], v183 offset:4096
	s_waitcnt lgkmcnt(10)
	v_mfma_f32_32x32x16_bf16 v[112:127], v[224:227], v[240:243], v[112:127]
	s_waitcnt lgkmcnt(9)
	v_mfma_f32_32x32x16_bf16 v[96:111], v[228:231], v[240:243], v[96:111]
	v_lshl_add_u64 v[150:151], v[148:149], 0, s[44:45]
	s_mov_b32 m0, s22
	v_readfirstlane_b32 s22, v152
	v_add_u32_e32 v128, 0xe000, v128
	global_load_lds_dwordx4 v[150:151], off
	s_waitcnt lgkmcnt(8)
	v_mfma_f32_32x32x16_bf16 v[80:95], v[232:235], v[240:243], v[80:95]
	s_waitcnt lgkmcnt(7)
	v_mfma_f32_32x32x16_bf16 v[64:79], v[236:239], v[240:243], v[64:79]
	v_lshl_add_u64 v[150:151], v[148:149], 0, s[42:43]
	s_mov_b32 m0, s22
	v_readfirstlane_b32 s22, v128
	global_load_lds_dwordx4 v[150:151], off
	s_waitcnt lgkmcnt(6)
	v_mfma_f32_32x32x16_bf16 v[48:63], v[224:227], v[244:247], v[48:63]
	v_mfma_f32_32x32x16_bf16 v[32:47], v[228:231], v[244:247], v[32:47]
	v_lshl_add_u64 v[148:149], v[148:149], 0, s[46:47]
	s_mov_b32 m0, s22
	s_add_i32 s9, s9, 0
	global_load_lds_dwordx4 v[148:149], off
	v_mfma_f32_32x32x16_bf16 v[16:31], v[232:235], v[244:247], v[16:31]
	v_mfma_f32_32x32x16_bf16 v[0:15], v[236:239], v[244:247], v[0:15]
	v_add_u32_e32 v184, v208, v147
	v_add_u32_e32 v185, v187, v147
	ds_read_b128 v[224:227], v184 offset:32768
	ds_read_b128 v[240:243], v185
	ds_read_b128 v[228:231], v184 offset:36864
	ds_read_b128 v[232:235], v184 offset:40960
	ds_read_b128 v[236:239], v184 offset:45056
	ds_read_b128 v[244:247], v185 offset:4096
	s_waitcnt lgkmcnt(10)
	v_mfma_f32_32x32x16_bf16 v[112:127], v[192:195], v[216:219], v[112:127]
	s_waitcnt lgkmcnt(9)
	v_mfma_f32_32x32x16_bf16 v[96:111], v[196:199], v[216:219], v[96:111]
	s_waitcnt lgkmcnt(8)
	v_mfma_f32_32x32x16_bf16 v[80:95], v[200:203], v[216:219], v[80:95]
	s_waitcnt lgkmcnt(7)
	v_mfma_f32_32x32x16_bf16 v[64:79], v[204:207], v[216:219], v[64:79]
	s_waitcnt lgkmcnt(6)
	v_mfma_f32_32x32x16_bf16 v[48:63], v[192:195], v[220:223], v[48:63]
	v_mfma_f32_32x32x16_bf16 v[32:47], v[196:199], v[220:223], v[32:47]
	v_mfma_f32_32x32x16_bf16 v[16:31], v[200:203], v[220:223], v[16:31]
	v_mfma_f32_32x32x16_bf16 v[0:15], v[204:207], v[220:223], v[0:15]
	s_waitcnt lgkmcnt(4)
	v_mfma_f32_32x32x16_bf16 v[112:127], v[224:227], v[240:243], v[112:127]
	s_waitcnt lgkmcnt(3)
	v_mfma_f32_32x32x16_bf16 v[96:111], v[228:231], v[240:243], v[96:111]
	s_waitcnt lgkmcnt(2)
	v_mfma_f32_32x32x16_bf16 v[80:95], v[232:235], v[240:243], v[80:95]
	s_waitcnt lgkmcnt(1)
	v_mfma_f32_32x32x16_bf16 v[64:79], v[236:239], v[240:243], v[64:79]
	s_waitcnt lgkmcnt(0)
	v_mfma_f32_32x32x16_bf16 v[48:63], v[224:227], v[244:247], v[48:63]
	v_mfma_f32_32x32x16_bf16 v[32:47], v[228:231], v[244:247], v[32:47]
	v_mfma_f32_32x32x16_bf16 v[16:31], v[232:235], v[244:247], v[16:31]
	v_mfma_f32_32x32x16_bf16 v[0:15], v[236:239], v[244:247], v[0:15]
	s_waitcnt vmcnt(0)
	s_and_b32 s9, s8, 15
	s_cmp_lg_u32 s9, 15
	s_cbranch_scc1 .LBB0_740
	s_lshl_b32 s8, s8, 1
	s_and_b32 s8, s8, 0x3ffffe0
	s_add_i32 s8, s8, s33
	s_lshl_b32 s8, s8, 5
	s_and_b32 s8, s8, 0x7fffff00
	v_or_b32_e32 v148, s8, v143
	v_cvt_pk_bf16_f32 v112, v112, v113
	v_cvt_pk_bf16_f32 v113, v114, v115
	v_cvt_pk_bf16_f32 v114, v116, v117
	v_cvt_pk_bf16_f32 v115, v118, v119
	s_movk_i32 s8, 0x1480
	v_permlane32_swap_b32_e32 v112, v114
	v_permlane32_swap_b32_e32 v113, v115
	v_cmp_gt_u32_e32 vcc, s8, v148
	v_lshlrev_b32_e32 v128, 1, v148
	s_and_saveexec_b64 s[22:23], vcc
	s_cbranch_execz .LBB0_744
	v_lshl_add_u64 v[116:117], v[136:137], 0, v[128:129]
	global_store_dwordx4 v[116:117], v[112:115], off

; #define MFMA(a, b, c) __builtin_amdgcn_mfma_f32_32x32x16_bf16((a), (b), (c), 0, 0, 0)
; DI f32x16 zero16() { f32x16 z; for (int i = 0; i < 16; ++i) z[i] = 0.f; return z; }
;     ...
;   const int fP = r * 128, fsw = (r >> 1) & 7;
;   const int fA = wm * 8192 + fP, fB = 32768 + wn * 16384 + fP;
;   f32x16 acc[2][4];
; #pragma unroll
;   for (int i = 0; i < 2; ++i)
; #pragma unroll
;     for (int j = 0; j < 4; ++j) acc[i][j] = zero16();
;   __syncthreads();
;   G_DMA(0, 0);
;   asm volatile("s_waitcnt vmcnt(0)" ::: "memory");
;   asm volatile("s_waitcnt lgkmcnt(0)" ::: "memory"); __builtin_amdgcn_s_barrier(); asm volatile("" ::: "memory");
;   int cur = 0;
;   for (int s = 0; s < S; ++s) {
;     G_DMA(s + 1, cur ^ BUFB);
;     {
;       const char* Ab = smem + cur + fA;
;       const char* Bb = smem + cur + fB;
;       __builtin_amdgcn_sched_barrier(0);
; #pragma unroll
;       for (int kk = 0; kk < 4; ++kk) {
;         const int ko = (((kk * 2 + hh) ^ fsw) << 4);
;         bf16x8 af[2], wf[4];
;         af[0] = *(const bf16x8*)(Ab + ko); af[1] = *(const bf16x8*)(Ab + 4096 + ko);
; #pragma unroll
;         for (int ni = 0; ni < 4; ++ni) wf[ni] = *(const bf16x8*)(Bb + ni * 4096 + ko);
; #pragma unroll
;         for (int mi = 0; mi < 2; ++mi)
; #pragma unroll
;           for (int ni = 0; ni < 4; ++ni) acc[mi][ni] = MFMA(wf[ni], af[mi], acc[mi][ni]);
;         if (kk == 1) __builtin_amdgcn_sched_barrier(0);
;       }
;       __builtin_amdgcn_sched_barrier(0);
;     }
;     asm volatile("s_waitcnt vmcnt(0)" ::: "memory");
.LBB0_1108:
	v_add3_u32 v215, s6, v187, v189
	v_add3_u32 v244, s6, v188, v189
	v_add_u32_e32 v182, v244, v190
	v_add_u32_e32 v183, v215, v190
	ds_read_b128 v[170:173], v182 offset:32768
	ds_read_b128 v[194:197], v183
	ds_read_b128 v[198:201], v182 offset:36864
	ds_read_b128 v[202:205], v182 offset:40960
	ds_read_b128 v[206:209], v182 offset:45056
	ds_read_b128 v[216:219], v183 offset:4096
	v_add_u32_e32 v184, v244, v191
	v_add_u32_e32 v185, v215, v191
	ds_read_b128 v[220:223], v184 offset:32768
	ds_read_b128 v[236:239], v185
	ds_read_b128 v[224:227], v184 offset:36864
	ds_read_b128 v[228:231], v184 offset:40960
	ds_read_b128 v[232:235], v184 offset:45056
	ds_read_b128 v[240:243], v185 offset:4096
	s_add_i32 s7, s8, 1
	s_mov_b32 s9, s6
	s_cmp_lt_u32 s7, s60
	v_readlane_b32 s6, v253, 59
	s_cselect_b32 s6, s7, s6
	s_lshl_b32 s22, s6, 1
	s_andn2_b32 s22, s22, 31
	s_add_i32 s22, s22, s33
	s_lshr_b32 s23, s22, 4
	s_lshr_b32 s22, s22, 3
	s_and_b32 s22, s22, 12
	v_readlane_b32 s46, v252, 41
	s_and_b32 s23, s23, 0xfffff8
	s_or_b32 s22, s22, s46
	s_or_b32 s24, s23, s74
	s_lshl_b32 s22, s22, 19
	v_readlane_b32 s40, v253, 39
	v_readlane_b32 s41, v253, 40
	s_add_u32 s22, s40, s22
	s_addc_u32 s23, s41, 0
	s_lshl_b32 s6, s6, 7
	s_and_b32 s28, s6, 0x780
	s_add_u32 s22, s22, s28
	s_addc_u32 s23, s23, 0
	s_lshl_b32 s24, s24, 8
	s_ashr_i32 s25, s24, 31
	s_lshl_b64 s[24:25], s[24:25], 11
	s_add_u32 s24, s62, s24
	s_addc_u32 s25, s63, s25
	s_xor_b32 s6, s9, 0x10000
	v_add_u32_e32 v245, s6, v131
	v_lshl_add_u64 v[246:247], s[22:23], 0, v[132:133]
	v_readfirstlane_b32 s22, v245
	v_add_u32_e32 v250, 0x2000, v245
	s_mov_b32 m0, s22
	s_mov_b64 s[42:43], 0x20000
	v_readfirstlane_b32 s22, v250
	v_add_u32_e32 v250, 0x4000, v245
	global_load_lds_dwordx4 v[246:247], off
	s_waitcnt lgkmcnt(10)
	v_mfma_f32_32x32x16_bf16 v[112:127], v[170:173], v[194:197], v[112:127]
	s_waitcnt lgkmcnt(9)
	v_mfma_f32_32x32x16_bf16 v[96:111], v[198:201], v[194:197], v[96:111]
	v_lshl_add_u64 v[248:249], v[246:247], 0, s[42:43]
	s_mov_b32 m0, s22
	s_mov_b64 s[40:41], 0x40000
	v_readfirstlane_b32 s22, v250
	v_add_u32_e32 v250, 0x6000, v245
	global_load_lds_dwordx4 v[248:249], off
	s_waitcnt lgkmcnt(8)
	v_mfma_f32_32x32x16_bf16 v[80:95], v[202:205], v[194:197], v[80:95]
	s_waitcnt lgkmcnt(7)
	v_mfma_f32_32x32x16_bf16 v[64:79], v[206:209], v[194:197], v[64:79]
	v_lshl_add_u64 v[248:249], v[246:247], 0, s[40:41]
	s_mov_b32 m0, s22
	v_readfirstlane_b32 s22, v250
	global_load_lds_dwordx4 v[248:249], off
	s_waitcnt lgkmcnt(6)
	v_mfma_f32_32x32x16_bf16 v[48:63], v[170:173], v[216:219], v[48:63]
	v_mfma_f32_32x32x16_bf16 v[32:47], v[198:201], v[216:219], v[32:47]
	s_mov_b64 s[44:45], 0x60000
	s_mov_b32 m0, s22
	s_add_u32 s22, s24, s28
	v_lshl_add_u64 v[246:247], v[246:247], 0, s[44:45]
	s_addc_u32 s23, s25, 0
	v_add_u32_e32 v250, 0x8000, v245
	global_load_lds_dwordx4 v[246:247], off
	v_mfma_f32_32x32x16_bf16 v[16:31], v[202:205], v[216:219], v[16:31]
	v_mfma_f32_32x32x16_bf16 v[0:15], v[206:209], v[216:219], v[0:15]
	v_lshl_add_u64 v[246:247], s[22:23], 0, v[132:133]
	v_readfirstlane_b32 s22, v250
	v_add_u32_e32 v250, 0xa000, v245
	s_mov_b32 m0, s22
	v_readfirstlane_b32 s22, v250
	v_add_u32_e32 v250, 0xc000, v245
	global_load_lds_dwordx4 v[246:247], off
	v_add_u32_e32 v182, v244, v192
	v_add_u32_e32 v183, v215, v192
	ds_read_b128 v[170:173], v182 offset:32768
	ds_read_b128 v[194:197], v183
	ds_read_b128 v[198:201], v182 offset:36864
	ds_read_b128 v[202:205], v182 offset:40960
	ds_read_b128 v[206:209], v182 offset:45056
	ds_read_b128 v[216:219], v183 offset:4096
	s_waitcnt lgkmcnt(10)
	v_mfma_f32_32x32x16_bf16 v[112:127], v[220:223], v[236:239], v[112:127]
	s_waitcnt lgkmcnt(9)
	v_mfma_f32_32x32x16_bf16 v[96:111], v[224:227], v[236:239], v[96:111]
	v_lshl_add_u64 v[248:249], v[246:247], 0, s[42:43]
	s_mov_b32 m0, s22
	v_readfirstlane_b32 s22, v250
	v_add_u32_e32 v245, 0xe000, v245
	global_load_lds_dwordx4 v[248:249], off
	s_waitcnt lgkmcnt(8)
	v_mfma_f32_32x32x16_bf16 v[80:95], v[228:231], v[236:239], v[80:95]
	s_waitcnt lgkmcnt(7)
	v_mfma_f32_32x32x16_bf16 v[64:79], v[232:235], v[236:239], v[64:79]
	v_lshl_add_u64 v[248:249], v[246:247], 0, s[40:41]
	s_mov_b32 m0, s22
	v_readfirstlane_b32 s22, v245
	global_load_lds_dwordx4 v[248:249], off
	s_waitcnt lgkmcnt(6)
	v_mfma_f32_32x32x16_bf16 v[48:63], v[220:223], v[240:243], v[48:63]
	v_mfma_f32_32x32x16_bf16 v[32:47], v[224:227], v[240:243], v[32:47]
	v_lshl_add_u64 v[246:247], v[246:247], 0, s[44:45]
	s_mov_b32 m0, s22
	s_add_i32 s9, s9, 0
	global_load_lds_dwordx4 v[246:247], off
	v_mfma_f32_32x32x16_bf16 v[16:31], v[228:231], v[240:243], v[16:31]
	v_mfma_f32_32x32x16_bf16 v[0:15], v[232:235], v[240:243], v[0:15]
	v_add_u32_e32 v184, v244, v193
	v_add_u32_e32 v185, v215, v193
	ds_read_b128 v[220:223], v184 offset:32768
	ds_read_b128 v[236:239], v185
	ds_read_b128 v[224:227], v184 offset:36864
	ds_read_b128 v[228:231], v184 offset:40960
	ds_read_b128 v[232:235], v184 offset:45056
	ds_read_b128 v[240:243], v185 offset:4096
	s_waitcnt lgkmcnt(10)
	v_mfma_f32_32x32x16_bf16 v[112:127], v[170:173], v[194:197], v[112:127]
	s_waitcnt lgkmcnt(9)
	v_mfma_f32_32x32x16_bf16 v[96:111], v[198:201], v[194:197], v[96:111]
	s_waitcnt lgkmcnt(8)
	v_mfma_f32_32x32x16_bf16 v[80:95], v[202:205], v[194:197], v[80:95]
	s_waitcnt lgkmcnt(7)
	v_mfma_f32_32x32x16_bf16 v[64:79], v[206:209], v[194:197], v[64:79]
	s_waitcnt lgkmcnt(6)
	v_mfma_f32_32x32x16_bf16 v[48:63], v[170:173], v[216:219], v[48:63]
	v_mfma_f32_32x32x16_bf16 v[32:47], v[198:201], v[216:219], v[32:47]
	v_mfma_f32_32x32x16_bf16 v[16:31], v[202:205], v[216:219], v[16:31]
	v_mfma_f32_32x32x16_bf16 v[0:15], v[206:209], v[216:219], v[0:15]
	s_waitcnt lgkmcnt(4)
	v_mfma_f32_32x32x16_bf16 v[112:127], v[220:223], v[236:239], v[112:127]
	s_waitcnt lgkmcnt(3)
	v_mfma_f32_32x32x16_bf16 v[96:111], v[224:227], v[236:239], v[96:111]
	s_waitcnt lgkmcnt(2)
	v_mfma_f32_32x32x16_bf16 v[80:95], v[228:231], v[236:239], v[80:95]
	s_waitcnt lgkmcnt(1)
	v_mfma_f32_32x32x16_bf16 v[64:79], v[232:235], v[236:239], v[64:79]
	s_waitcnt lgkmcnt(0)
	v_mfma_f32_32x32x16_bf16 v[48:63], v[220:223], v[240:243], v[48:63]
	v_mfma_f32_32x32x16_bf16 v[32:47], v[224:227], v[240:243], v[32:47]
	v_mfma_f32_32x32x16_bf16 v[16:31], v[228:231], v[240:243], v[16:31]
	v_mfma_f32_32x32x16_bf16 v[0:15], v[232:235], v[240:243], v[0:15]
	s_waitcnt vmcnt(0)
	s_and_b32 s9, s8, 15
	s_cmp_lg_u32 s9, 15
	s_cbranch_scc1 .LBB0_1107
; DI unsigned pack2(float a, float b) { f32x2_t v = {a, b}; return __builtin_bit_cast(unsigned, __builtin_convertvector(v, bf16x2_t)); }
;     ...
;             for (int g = 0; g < 4; ++g) {
;               const int n = nt * 256 + wn * 128 + ni * 32 + 8 * g + 4 * hh;
;               const float a0 = acc[mi][ni][4 * g], a1 = acc[mi][ni][4 * g + 1], a2 = acc[mi][ni][4 * g + 2], a3 = acc[mi][ni][4 * g + 3];
;               if (MODE == 0) {
;                 uint2 pk; pk.x = pack2(a0, a1); pk.y = pack2(a2, a3);
;                 if (outp != nullptr && nt >= 32) *(uint2*)(outp + m * 2048 + (n - 8192)) = pk;
;                 else if (n < nvalid) *(uint2*)(C + m * ldc + n) = pk;
;               } else if (MODE == 2) {
;                 const unsigned p01 = pack2(a0, a1), p23 = pack2(a2, a3);
;                 bf16_t* dst = ((nt < 8) ? C : outp) + ((size_t)(n & 2047) * 8 + (m >> 12)) * SEQ + (m & 4095);
;                 dst[0] = (bf16_t)(p01 & 0xffffu); dst[(size_t)8 * SEQ] = (bf16_t)(p01 >> 16);
;                 dst[(size_t)16 * SEQ] = (bf16_t)(p23 & 0xffffu); dst[(size_t)24 * SEQ] = (bf16_t)(p23 >> 16);
	s_lshl_b32 s8, s8, 1
	s_and_b32 s8, s8, 0x7fffffe0
	s_add_i32 s8, s8, s33
	s_lshr_b32 s9, s8, 3
	s_and_b32 s9, s9, 12
	s_or_b32 s9, s9, s46
	s_lshl_b32 s28, s9, 8
	s_cmpk_lt_u32 s8, 0x80
	v_lshl_add_u64 v[170:171], s[28:29], 0, v[134:135]
	s_cselect_b32 s8, s11, s31
	s_cselect_b32 s9, s10, s30
	v_mov_b32_e32 v172, s9
	v_mov_b32_e32 v173, s8
	v_and_b32_e32 v175, 0x7fffffff, v171
	v_and_b32_e32 v174, 0xfffff000, v170
	v_and_b32_e32 v128, 0xfc0, v170
	v_lshl_add_u64 v[172:173], v[174:175], 1, v[172:173]
	v_lshlrev_b32_e32 v128, 1, v128
	v_lshl_add_u64 v[170:171], v[172:173], 0, v[128:129]
	v_mov_b32_e32 v169, v129
	v_lshl_add_u64 v[170:171], v[170:171], 0, v[168:169]
	v_cvt_pk_bf16_f32 v128, v112, v113
	v_lshl_add_u64 v[112:113], v[170:171], 0, v[136:137]
	s_mov_b32 s8, 0x10000
	v_cvt_pk_bf16_f32 v169, v114, v115
	v_add_co_u32_e32 v114, vcc, s8, v112
	s_mov_b32 s9, 0x20000
	s_nop 0
	v_addc_co_u32_e32 v115, vcc, 0, v113, vcc
	v_add_co_u32_e32 v172, vcc, s9, v112
	s_mov_b32 s22, 0x30000
	s_nop 0
	v_addc_co_u32_e32 v173, vcc, 0, v113, vcc
	v_add_co_u32_e32 v174, vcc, s22, v112
	global_store_short v[112:113], v128, off
	global_store_short_d16_hi v[114:115], v128, off
	v_addc_co_u32_e32 v175, vcc, 0, v113, vcc
	v_cvt_pk_bf16_f32 v128, v116, v117
	v_lshl_add_u64 v[116:117], v[170:171], 0, v[138:139]
	global_store_short v[172:173], v169, off
	global_store_short_d16_hi v[174:175], v169, off
	v_cvt_pk_bf16_f32 v169, v118, v119
	v_add_co_u32_e32 v118, vcc, s8, v116
	global_store_short v[116:117], v128, off
	s_nop 0
	v_addc_co_u32_e32 v119, vcc, 0, v117, vcc
	global_store_short_d16_hi v[118:119], v128, off
	v_add_co_u32_e32 v118, vcc, s9, v116
	v_cvt_pk_bf16_f32 v120, v120, v121
	s_nop 0
	v_addc_co_u32_e32 v119, vcc, 0, v117, vcc
	v_add_co_u32_e32 v116, vcc, s22, v116
	global_store_short v[118:119], v169, off
	s_nop 0
	v_addc_co_u32_e32 v117, vcc, 0, v117, vcc
	global_store_short_d16_hi v[116:117], v169, off
	v_lshl_add_u64 v[116:117], v[170:171], 0, v[140:141]
	v_add_co_u32_e32 v118, vcc, s8, v116
	global_store_short v[116:117], v120, off
	s_nop 0
	v_addc_co_u32_e32 v119, vcc, 0, v117, vcc
	global_store_short_d16_hi v[118:119], v120, off
	v_add_co_u32_e32 v118, vcc, s9, v116
	v_cvt_pk_bf16_f32 v121, v122, v123
	s_nop 0
	v_addc_co_u32_e32 v119, vcc, 0, v117, vcc
	v_add_co_u32_e32 v116, vcc, s22, v116
	global_store_short v[118:119], v121, off
	s_nop 0
	v_addc_co_u32_e32 v117, vcc, 0, v117, vcc
	global_store_short_d16_hi v[116:117], v121, off
	v_lshl_add_u64 v[116:117], v[170:171], 0, v[142:143]
	v_add_co_u32_e32 v118, vcc, s8, v116
	v_cvt_pk_bf16_f32 v120, v124, v125
	s_nop 0
	v_addc_co_u32_e32 v119, vcc, 0, v117, vcc
	global_store_short_d16_hi v[118:119], v120, off
	v_add_co_u32_e32 v118, vcc, s9, v116
	global_store_short v[116:117], v120, off
	s_nop 0
	v_addc_co_u32_e32 v119, vcc, 0, v117, vcc
	v_add_co_u32_e32 v116, vcc, s22, v116
	v_cvt_pk_bf16_f32 v121, v126, v127
	s_nop 0
	v_addc_co_u32_e32 v117, vcc, 0, v117, vcc
	global_store_short v[118:119], v121, off
	global_store_short_d16_hi v[116:117], v121, off
	v_cvt_pk_bf16_f32 v116, v96, v97
	v_lshl_add_u64 v[96:97], v[170:171], 0, v[144:145]
	v_cvt_pk_bf16_f32 v117, v98, v99
	v_add_co_u32_e32 v98, vcc, s8, v96
	global_store_short v[96:97], v116, off
	s_nop 0
	v_addc_co_u32_e32 v99, vcc, 0, v97, vcc
	global_store_short_d16_hi v[98:99], v116, off
	v_add_co_u32_e32 v98, vcc, s9, v96
	v_cvt_pk_bf16_f32 v100, v100, v101
	s_nop 0
	v_addc_co_u32_e32 v99, vcc, 0, v97, vcc
	v_add_co_u32_e32 v96, vcc, s22, v96
	global_store_short v[98:99], v117, off
	s_nop 0
	v_addc_co_u32_e32 v97, vcc, 0, v97, vcc
	global_store_short_d16_hi v[96:97], v117, off
	v_lshl_add_u64 v[96:97], v[170:171], 0, v[146:147]
	v_add_co_u32_e32 v98, vcc, s8, v96
	global_store_short v[96:97], v100, off
	s_nop 0
	v_addc_co_u32_e32 v99, vcc, 0, v97, vcc
	global_store_short_d16_hi v[98:99], v100, off
	v_add_co_u32_e32 v98, vcc, s9, v96
	v_cvt_pk_bf16_f32 v101, v102, v103
	s_nop 0
	v_addc_co_u32_e32 v99, vcc, 0, v97, vcc
	v_add_co_u32_e32 v96, vcc, s22, v96
	global_store_short v[98:99], v101, off
	s_nop 0
	v_addc_co_u32_e32 v97, vcc, 0, v97, vcc
	global_store_short_d16_hi v[96:97], v101, off
	v_lshl_add_u64 v[96:97], v[170:171], 0, v[148:149]
	v_add_co_u32_e32 v98, vcc, s8, v96
	v_cvt_pk_bf16_f32 v100, v104, v105
	s_nop 0
	v_addc_co_u32_e32 v99, vcc, 0, v97, vcc
	global_store_short_d16_hi v[98:99], v100, off
	v_add_co_u32_e32 v98, vcc, s9, v96
	global_store_short v[96:97], v100, off
	s_nop 0
	v_addc_co_u32_e32 v99, vcc, 0, v97, vcc
	v_add_co_u32_e32 v96, vcc, s22, v96
	v_cvt_pk_bf16_f32 v101, v106, v107
	s_nop 0
	v_addc_co_u32_e32 v97, vcc, 0, v97, vcc
	global_store_short_d16_hi v[96:97], v101, off
	v_lshl_add_u64 v[96:97], v[170:171], 0, v[150:151]
	global_store_short v[98:99], v101, off
	v_add_co_u32_e32 v98, vcc, s8, v96
	v_cvt_pk_bf16_f32 v100, v108, v109
	s_nop 0
	v_addc_co_u32_e32 v99, vcc, 0, v97, vcc
	global_store_short_d16_hi v[98:99], v100, off
	v_add_co_u32_e32 v98, vcc, s9, v96
	global_store_short v[96:97], v100, off
	s_nop 0
	v_addc_co_u32_e32 v99, vcc, 0, v97, vcc
	v_add_co_u32_e32 v96, vcc, s22, v96
	v_cvt_pk_bf16_f32 v101, v110, v111
	s_nop 0
	v_addc_co_u32_e32 v97, vcc, 0, v97, vcc
	global_store_short v[98:99], v101, off
	global_store_short_d16_hi v[96:97], v101, off
	v_cvt_pk_bf16_f32 v96, v80, v81
	v_lshl_add_u64 v[80:81], v[170:171], 0, v[152:153]
	v_cvt_pk_bf16_f32 v97, v82, v83
	v_add_co_u32_e32 v82, vcc, s8, v80
	global_store_short v[80:81], v96, off
	s_nop 0
	v_addc_co_u32_e32 v83, vcc, 0, v81, vcc
	global_store_short_d16_hi v[82:83], v96, off
	v_add_co_u32_e32 v82, vcc, s9, v80
	v_cvt_pk_bf16_f32 v84, v84, v85
	s_nop 0
; DI unsigned pack2(float a, float b) { f32x2_t v = {a, b}; return __builtin_bit_cast(unsigned, __builtin_convertvector(v, bf16x2_t)); }
;     ...
;             for (int g = 0; g < 4; ++g) {
;               const int n = nt * 256 + wn * 128 + ni * 32 + 8 * g + 4 * hh;
;               const float a0 = acc[mi][ni][4 * g], a1 = acc[mi][ni][4 * g + 1], a2 = acc[mi][ni][4 * g + 2], a3 = acc[mi][ni][4 * g + 3];
;               if (MODE == 0) {
;                 uint2 pk; pk.x = pack2(a0, a1); pk.y = pack2(a2, a3);
;                 if (outp != nullptr && nt >= 32) *(uint2*)(outp + m * 2048 + (n - 8192)) = pk;
;                 else if (n < nvalid) *(uint2*)(C + m * ldc + n) = pk;
;               } else if (MODE == 2) {
;                 const unsigned p01 = pack2(a0, a1), p23 = pack2(a2, a3);
;                 bf16_t* dst = ((nt < 8) ? C : outp) + ((size_t)(n & 2047) * 8 + (m >> 12)) * SEQ + (m & 4095);
;                 dst[0] = (bf16_t)(p01 & 0xffffu); dst[(size_t)8 * SEQ] = (bf16_t)(p01 >> 16);
;                 dst[(size_t)16 * SEQ] = (bf16_t)(p23 & 0xffffu); dst[(size_t)24 * SEQ] = (bf16_t)(p23 >> 16);
	v_addc_co_u32_e32 v83, vcc, 0, v81, vcc
	v_add_co_u32_e32 v80, vcc, s22, v80
	global_store_short v[82:83], v97, off
	s_nop 0
	v_addc_co_u32_e32 v81, vcc, 0, v81, vcc
	global_store_short_d16_hi v[80:81], v97, off
	v_lshl_add_u64 v[80:81], v[170:171], 0, v[154:155]
	v_add_co_u32_e32 v82, vcc, s8, v80
	global_store_short v[80:81], v84, off
	s_nop 0
	v_addc_co_u32_e32 v83, vcc, 0, v81, vcc
	global_store_short_d16_hi v[82:83], v84, off
	v_add_co_u32_e32 v82, vcc, s9, v80
	v_cvt_pk_bf16_f32 v85, v86, v87
	s_nop 0
	v_addc_co_u32_e32 v83, vcc, 0, v81, vcc
	v_add_co_u32_e32 v80, vcc, s22, v80
	global_store_short v[82:83], v85, off
	s_nop 0
	v_addc_co_u32_e32 v81, vcc, 0, v81, vcc
	global_store_short_d16_hi v[80:81], v85, off
	v_lshl_add_u64 v[80:81], v[170:171], 0, v[156:157]
	v_add_co_u32_e32 v82, vcc, s8, v80
	v_cvt_pk_bf16_f32 v84, v88, v89
	s_nop 0
	v_addc_co_u32_e32 v83, vcc, 0, v81, vcc
	global_store_short_d16_hi v[82:83], v84, off
	v_add_co_u32_e32 v82, vcc, s9, v80
	global_store_short v[80:81], v84, off
	s_nop 0
	v_addc_co_u32_e32 v83, vcc, 0, v81, vcc
	v_add_co_u32_e32 v80, vcc, s22, v80
	v_cvt_pk_bf16_f32 v85, v90, v91
	s_nop 0
	v_addc_co_u32_e32 v81, vcc, 0, v81, vcc
	global_store_short_d16_hi v[80:81], v85, off
	v_lshl_add_u64 v[80:81], v[170:171], 0, v[158:159]
	global_store_short v[82:83], v85, off
	v_add_co_u32_e32 v82, vcc, s8, v80
	v_cvt_pk_bf16_f32 v84, v92, v93
	s_nop 0
	v_addc_co_u32_e32 v83, vcc, 0, v81, vcc
	global_store_short_d16_hi v[82:83], v84, off
	v_add_co_u32_e32 v82, vcc, s9, v80
	global_store_short v[80:81], v84, off
	s_nop 0
	v_addc_co_u32_e32 v83, vcc, 0, v81, vcc
	v_add_co_u32_e32 v80, vcc, s22, v80
	v_cvt_pk_bf16_f32 v85, v94, v95
	s_nop 0
	v_addc_co_u32_e32 v81, vcc, 0, v81, vcc
	global_store_short v[82:83], v85, off
	global_store_short_d16_hi v[80:81], v85, off
	v_cvt_pk_bf16_f32 v80, v64, v65
	v_lshl_add_u64 v[64:65], v[170:171], 0, v[160:161]
	v_cvt_pk_bf16_f32 v81, v66, v67
	v_add_co_u32_e32 v66, vcc, s8, v64
	global_store_short v[64:65], v80, off
	s_nop 0
	v_addc_co_u32_e32 v67, vcc, 0, v65, vcc
	global_store_short_d16_hi v[66:67], v80, off
	v_add_co_u32_e32 v66, vcc, s9, v64
	v_cvt_pk_bf16_f32 v68, v68, v69
	s_nop 0
	v_addc_co_u32_e32 v67, vcc, 0, v65, vcc
	v_add_co_u32_e32 v64, vcc, s22, v64
	global_store_short v[66:67], v81, off
	s_nop 0
	v_addc_co_u32_e32 v65, vcc, 0, v65, vcc
	global_store_short_d16_hi v[64:65], v81, off
	v_lshl_add_u64 v[64:65], v[170:171], 0, v[162:163]
	v_add_co_u32_e32 v66, vcc, s8, v64
	global_store_short v[64:65], v68, off
	s_nop 0
	v_addc_co_u32_e32 v67, vcc, 0, v65, vcc
	global_store_short_d16_hi v[66:67], v68, off
	v_add_co_u32_e32 v66, vcc, s9, v64
	v_cvt_pk_bf16_f32 v69, v70, v71
	s_nop 0
	v_addc_co_u32_e32 v67, vcc, 0, v65, vcc
	v_add_co_u32_e32 v64, vcc, s22, v64
	global_store_short v[66:67], v69, off
	s_nop 0
	v_addc_co_u32_e32 v65, vcc, 0, v65, vcc
	global_store_short_d16_hi v[64:65], v69, off
	v_lshl_add_u64 v[64:65], v[170:171], 0, v[164:165]
	v_add_co_u32_e32 v66, vcc, s8, v64
	v_cvt_pk_bf16_f32 v68, v72, v73
	s_nop 0
	v_addc_co_u32_e32 v67, vcc, 0, v65, vcc
	global_store_short_d16_hi v[66:67], v68, off
	v_add_co_u32_e32 v66, vcc, s9, v64
	global_store_short v[64:65], v68, off
	s_nop 0
	v_addc_co_u32_e32 v67, vcc, 0, v65, vcc
	v_add_co_u32_e32 v64, vcc, s22, v64
	v_cvt_pk_bf16_f32 v69, v74, v75
	s_nop 0
	v_addc_co_u32_e32 v65, vcc, 0, v65, vcc
	global_store_short_d16_hi v[64:65], v69, off
	v_lshl_add_u64 v[64:65], v[170:171], 0, v[166:167]
	global_store_short v[66:67], v69, off
	v_add_co_u32_e32 v66, vcc, s8, v64
	v_cvt_pk_bf16_f32 v68, v76, v77
	s_nop 0
	v_addc_co_u32_e32 v67, vcc, 0, v65, vcc
	global_store_short_d16_hi v[66:67], v68, off
	v_add_co_u32_e32 v66, vcc, s9, v64
	global_store_short v[64:65], v68, off
	s_nop 0
	v_addc_co_u32_e32 v67, vcc, 0, v65, vcc
	v_add_co_u32_e32 v64, vcc, s22, v64
	v_cvt_pk_bf16_f32 v69, v78, v79
	s_nop 0
	v_addc_co_u32_e32 v65, vcc, 0, v65, vcc
	global_store_short_d16_hi v[64:65], v69, off
	v_lshl_add_u64 v[64:65], v[170:171], 0, 64
	global_store_short v[66:67], v69, off
	v_cvt_pk_bf16_f32 v48, v48, v49
	v_cvt_pk_bf16_f32 v49, v50, v51
	global_store_short v[112:113], v48, off offset:64
	global_store_short_d16_hi v[114:115], v48, off offset:64
	global_store_short v[172:173], v49, off offset:64
	global_store_short_d16_hi v[174:175], v49, off offset:64
	v_lshl_add_u64 v[48:49], v[64:65], 0, v[138:139]
	v_add_co_u32_e32 v50, vcc, s8, v48
	v_cvt_pk_bf16_f32 v52, v52, v53
	s_nop 0
	v_addc_co_u32_e32 v51, vcc, 0, v49, vcc
	global_store_short_d16_hi v[50:51], v52, off
	v_add_co_u32_e32 v50, vcc, s9, v48
	global_store_short v[48:49], v52, off
	s_nop 0
	v_addc_co_u32_e32 v51, vcc, 0, v49, vcc
	v_add_co_u32_e32 v48, vcc, s22, v48
	v_cvt_pk_bf16_f32 v53, v54, v55
	s_nop 0
	v_addc_co_u32_e32 v49, vcc, 0, v49, vcc
	global_store_short_d16_hi v[48:49], v53, off
	v_lshl_add_u64 v[48:49], v[64:65], 0, v[140:141]
	global_store_short v[50:51], v53, off
	v_add_co_u32_e32 v50, vcc, s8, v48
	v_cvt_pk_bf16_f32 v52, v56, v57
	s_nop 0
	v_addc_co_u32_e32 v51, vcc, 0, v49, vcc
	global_store_short_d16_hi v[50:51], v52, off
	v_add_co_u32_e32 v50, vcc, s9, v48
	global_store_short v[48:49], v52, off
	s_nop 0
	v_addc_co_u32_e32 v51, vcc, 0, v49, vcc
	v_add_co_u32_e32 v48, vcc, s22, v48
	v_cvt_pk_bf16_f32 v53, v58, v59
	s_nop 0
	v_addc_co_u32_e32 v49, vcc, 0, v49, vcc
	global_store_short_d16_hi v[48:49], v53, off
	v_lshl_add_u64 v[48:49], v[64:65], 0, v[142:143]
	global_store_short v[50:51], v53, off
	v_add_co_u32_e32 v50, vcc, s8, v48
	v_cvt_pk_bf16_f32 v52, v60, v61
	s_nop 0
	v_addc_co_u32_e32 v51, vcc, 0, v49, vcc
	global_store_short_d16_hi v[50:51], v52, off
; DI unsigned pack2(float a, float b) { f32x2_t v = {a, b}; return __builtin_bit_cast(unsigned, __builtin_convertvector(v, bf16x2_t)); }
;     ...
;             for (int g = 0; g < 4; ++g) {
;               const int n = nt * 256 + wn * 128 + ni * 32 + 8 * g + 4 * hh;
;               const float a0 = acc[mi][ni][4 * g], a1 = acc[mi][ni][4 * g + 1], a2 = acc[mi][ni][4 * g + 2], a3 = acc[mi][ni][4 * g + 3];
;               if (MODE == 0) {
;                 uint2 pk; pk.x = pack2(a0, a1); pk.y = pack2(a2, a3);
;                 if (outp != nullptr && nt >= 32) *(uint2*)(outp + m * 2048 + (n - 8192)) = pk;
;                 else if (n < nvalid) *(uint2*)(C + m * ldc + n) = pk;
;               } else if (MODE == 2) {
;                 const unsigned p01 = pack2(a0, a1), p23 = pack2(a2, a3);
;                 bf16_t* dst = ((nt < 8) ? C : outp) + ((size_t)(n & 2047) * 8 + (m >> 12)) * SEQ + (m & 4095);
;                 dst[0] = (bf16_t)(p01 & 0xffffu); dst[(size_t)8 * SEQ] = (bf16_t)(p01 >> 16);
;                 dst[(size_t)16 * SEQ] = (bf16_t)(p23 & 0xffffu); dst[(size_t)24 * SEQ] = (bf16_t)(p23 >> 16);
	v_add_co_u32_e32 v50, vcc, s9, v48
	global_store_short v[48:49], v52, off
	s_nop 0
	v_addc_co_u32_e32 v51, vcc, 0, v49, vcc
	v_add_co_u32_e32 v48, vcc, s22, v48
	v_cvt_pk_bf16_f32 v53, v62, v63
	s_nop 0
	v_addc_co_u32_e32 v49, vcc, 0, v49, vcc
	global_store_short v[50:51], v53, off
	global_store_short_d16_hi v[48:49], v53, off
	v_cvt_pk_bf16_f32 v48, v32, v33
	v_lshl_add_u64 v[32:33], v[64:65], 0, v[144:145]
	v_cvt_pk_bf16_f32 v49, v34, v35
	v_add_co_u32_e32 v34, vcc, s8, v32
	global_store_short v[32:33], v48, off
	s_nop 0
	v_addc_co_u32_e32 v35, vcc, 0, v33, vcc
	global_store_short_d16_hi v[34:35], v48, off
	v_add_co_u32_e32 v34, vcc, s9, v32
	v_cvt_pk_bf16_f32 v36, v36, v37
	s_nop 0
	v_addc_co_u32_e32 v35, vcc, 0, v33, vcc
	v_add_co_u32_e32 v32, vcc, s22, v32
	global_store_short v[34:35], v49, off
	s_nop 0
	v_addc_co_u32_e32 v33, vcc, 0, v33, vcc
	global_store_short_d16_hi v[32:33], v49, off
	v_lshl_add_u64 v[32:33], v[64:65], 0, v[146:147]
	v_add_co_u32_e32 v34, vcc, s8, v32
	global_store_short v[32:33], v36, off
	s_nop 0
	v_addc_co_u32_e32 v35, vcc, 0, v33, vcc
	global_store_short_d16_hi v[34:35], v36, off
	v_add_co_u32_e32 v34, vcc, s9, v32
	v_cvt_pk_bf16_f32 v37, v38, v39
	s_nop 0
	v_addc_co_u32_e32 v35, vcc, 0, v33, vcc
	v_add_co_u32_e32 v32, vcc, s22, v32
	global_store_short v[34:35], v37, off
	s_nop 0
	v_addc_co_u32_e32 v33, vcc, 0, v33, vcc
	global_store_short_d16_hi v[32:33], v37, off
	v_lshl_add_u64 v[32:33], v[64:65], 0, v[148:149]
	v_add_co_u32_e32 v34, vcc, s8, v32
	v_cvt_pk_bf16_f32 v36, v40, v41
	s_nop 0
	v_addc_co_u32_e32 v35, vcc, 0, v33, vcc
	global_store_short_d16_hi v[34:35], v36, off
	v_add_co_u32_e32 v34, vcc, s9, v32
	global_store_short v[32:33], v36, off
	s_nop 0
	v_addc_co_u32_e32 v35, vcc, 0, v33, vcc
	v_add_co_u32_e32 v32, vcc, s22, v32
	v_cvt_pk_bf16_f32 v37, v42, v43
	s_nop 0
	v_addc_co_u32_e32 v33, vcc, 0, v33, vcc
	global_store_short_d16_hi v[32:33], v37, off
	v_lshl_add_u64 v[32:33], v[64:65], 0, v[150:151]
	global_store_short v[34:35], v37, off
	v_add_co_u32_e32 v34, vcc, s8, v32
	v_cvt_pk_bf16_f32 v36, v44, v45
	s_nop 0
	v_addc_co_u32_e32 v35, vcc, 0, v33, vcc
	global_store_short_d16_hi v[34:35], v36, off
	v_add_co_u32_e32 v34, vcc, s9, v32
	global_store_short v[32:33], v36, off
	s_nop 0
	v_addc_co_u32_e32 v35, vcc, 0, v33, vcc
	v_add_co_u32_e32 v32, vcc, s22, v32
	v_cvt_pk_bf16_f32 v37, v46, v47
	s_nop 0
	v_addc_co_u32_e32 v33, vcc, 0, v33, vcc
	global_store_short v[34:35], v37, off
	global_store_short_d16_hi v[32:33], v37, off
	v_cvt_pk_bf16_f32 v32, v16, v17
	v_lshl_add_u64 v[16:17], v[64:65], 0, v[152:153]
	v_cvt_pk_bf16_f32 v33, v18, v19
	v_add_co_u32_e32 v18, vcc, s8, v16
	global_store_short v[16:17], v32, off
	s_nop 0
	v_addc_co_u32_e32 v19, vcc, 0, v17, vcc
	global_store_short_d16_hi v[18:19], v32, off
	v_add_co_u32_e32 v18, vcc, s9, v16
	v_cvt_pk_bf16_f32 v20, v20, v21
	s_nop 0
	v_addc_co_u32_e32 v19, vcc, 0, v17, vcc
	v_add_co_u32_e32 v16, vcc, s22, v16
	global_store_short v[18:19], v33, off
	s_nop 0
	v_addc_co_u32_e32 v17, vcc, 0, v17, vcc
	global_store_short_d16_hi v[16:17], v33, off
	v_lshl_add_u64 v[16:17], v[64:65], 0, v[154:155]
	v_add_co_u32_e32 v18, vcc, s8, v16
	global_store_short v[16:17], v20, off
	s_nop 0
	v_addc_co_u32_e32 v19, vcc, 0, v17, vcc
	global_store_short_d16_hi v[18:19], v20, off
	v_add_co_u32_e32 v18, vcc, s9, v16
	v_cvt_pk_bf16_f32 v21, v22, v23
	s_nop 0
	v_addc_co_u32_e32 v19, vcc, 0, v17, vcc
	v_add_co_u32_e32 v16, vcc, s22, v16
	global_store_short v[18:19], v21, off
	s_nop 0
	v_addc_co_u32_e32 v17, vcc, 0, v17, vcc
	global_store_short_d16_hi v[16:17], v21, off
	v_lshl_add_u64 v[16:17], v[64:65], 0, v[156:157]
	v_add_co_u32_e32 v18, vcc, s8, v16
	v_cvt_pk_bf16_f32 v20, v24, v25
	s_nop 0
	v_addc_co_u32_e32 v19, vcc, 0, v17, vcc
	global_store_short_d16_hi v[18:19], v20, off
	v_add_co_u32_e32 v18, vcc, s9, v16
	global_store_short v[16:17], v20, off
	s_nop 0
	v_addc_co_u32_e32 v19, vcc, 0, v17, vcc
	v_add_co_u32_e32 v16, vcc, s22, v16
	v_cvt_pk_bf16_f32 v21, v26, v27
	s_nop 0
	v_addc_co_u32_e32 v17, vcc, 0, v17, vcc
	global_store_short_d16_hi v[16:17], v21, off
	v_lshl_add_u64 v[16:17], v[64:65], 0, v[158:159]
	global_store_short v[18:19], v21, off
	v_add_co_u32_e32 v18, vcc, s8, v16
	v_cvt_pk_bf16_f32 v20, v28, v29
	s_nop 0
	v_addc_co_u32_e32 v19, vcc, 0, v17, vcc
	global_store_short_d16_hi v[18:19], v20, off
	v_add_co_u32_e32 v18, vcc, s9, v16
	global_store_short v[16:17], v20, off
	s_nop 0
	v_addc_co_u32_e32 v19, vcc, 0, v17, vcc
	v_add_co_u32_e32 v16, vcc, s22, v16
	v_cvt_pk_bf16_f32 v21, v30, v31
	s_nop 0
	v_addc_co_u32_e32 v17, vcc, 0, v17, vcc
	global_store_short v[18:19], v21, off
	global_store_short_d16_hi v[16:17], v21, off
	v_cvt_pk_bf16_f32 v16, v0, v1
	v_lshl_add_u64 v[0:1], v[64:65], 0, v[160:161]
	v_cvt_pk_bf16_f32 v17, v2, v3
	v_add_co_u32_e32 v2, vcc, s8, v0
	global_store_short v[0:1], v16, off
	s_nop 0
; DI unsigned pack2(float a, float b) { f32x2_t v = {a, b}; return __builtin_bit_cast(unsigned, __builtin_convertvector(v, bf16x2_t)); }
; DI f32x16 zero16() { f32x16 z; for (int i = 0; i < 16; ++i) z[i] = 0.f; return z; }
;     ...
;             for (int g = 0; g < 4; ++g) {
;               const int n = nt * 256 + wn * 128 + ni * 32 + 8 * g + 4 * hh;
;               const float a0 = acc[mi][ni][4 * g], a1 = acc[mi][ni][4 * g + 1], a2 = acc[mi][ni][4 * g + 2], a3 = acc[mi][ni][4 * g + 3];
;               if (MODE == 0) {
;                 uint2 pk; pk.x = pack2(a0, a1); pk.y = pack2(a2, a3);
;                 if (outp != nullptr && nt >= 32) *(uint2*)(outp + m * 2048 + (n - 8192)) = pk;
;                 else if (n < nvalid) *(uint2*)(C + m * ldc + n) = pk;
;               } else if (MODE == 2) {
;                 const unsigned p01 = pack2(a0, a1), p23 = pack2(a2, a3);
;                 bf16_t* dst = ((nt < 8) ? C : outp) + ((size_t)(n & 2047) * 8 + (m >> 12)) * SEQ + (m & 4095);
;                 dst[0] = (bf16_t)(p01 & 0xffffu); dst[(size_t)8 * SEQ] = (bf16_t)(p01 >> 16);
;                 dst[(size_t)16 * SEQ] = (bf16_t)(p23 & 0xffffu); dst[(size_t)24 * SEQ] = (bf16_t)(p23 >> 16);
;     ...
; #pragma unroll
;       for (int i = 0; i < 2; ++i)
; #pragma unroll
;         for (int j = 0; j < 4; ++j) acc[i][j] = zero16();
;     }
;     asm volatile("s_waitcnt lgkmcnt(0)" ::: "memory"); __builtin_amdgcn_s_barrier(); asm volatile("" ::: "memory");
;     cur ^= BUFB;
	v_addc_co_u32_e32 v3, vcc, 0, v1, vcc
	global_store_short_d16_hi v[2:3], v16, off
	v_add_co_u32_e32 v2, vcc, s9, v0
	v_cvt_pk_bf16_f32 v4, v4, v5
	s_nop 0
	v_addc_co_u32_e32 v3, vcc, 0, v1, vcc
	v_add_co_u32_e32 v0, vcc, s22, v0
	global_store_short v[2:3], v17, off
	s_nop 0
	v_addc_co_u32_e32 v1, vcc, 0, v1, vcc
	global_store_short_d16_hi v[0:1], v17, off
	v_lshl_add_u64 v[0:1], v[64:65], 0, v[162:163]
	v_add_co_u32_e32 v2, vcc, s8, v0
	global_store_short v[0:1], v4, off
	s_nop 0
	v_addc_co_u32_e32 v3, vcc, 0, v1, vcc
	global_store_short_d16_hi v[2:3], v4, off
	v_add_co_u32_e32 v2, vcc, s9, v0
	v_cvt_pk_bf16_f32 v5, v6, v7
	s_nop 0
	v_addc_co_u32_e32 v3, vcc, 0, v1, vcc
	v_add_co_u32_e32 v0, vcc, s22, v0
	global_store_short v[2:3], v5, off
	s_nop 0
	v_addc_co_u32_e32 v1, vcc, 0, v1, vcc
	global_store_short_d16_hi v[0:1], v5, off
	v_lshl_add_u64 v[0:1], v[64:65], 0, v[164:165]
	v_add_co_u32_e32 v2, vcc, s8, v0
	v_cvt_pk_bf16_f32 v4, v8, v9
	s_nop 0
	v_addc_co_u32_e32 v3, vcc, 0, v1, vcc
	global_store_short_d16_hi v[2:3], v4, off
	v_add_co_u32_e32 v2, vcc, s9, v0
	global_store_short v[0:1], v4, off
	s_nop 0
	v_addc_co_u32_e32 v3, vcc, 0, v1, vcc
	v_add_co_u32_e32 v0, vcc, 0x30000, v0
	v_cvt_pk_bf16_f32 v5, v10, v11
	s_nop 0
	v_addc_co_u32_e32 v1, vcc, 0, v1, vcc
	global_store_short_d16_hi v[0:1], v5, off
	v_lshl_add_u64 v[0:1], v[64:65], 0, v[166:167]
	global_store_short v[2:3], v5, off
	v_add_co_u32_e32 v2, vcc, 0x10000, v0
	v_cvt_pk_bf16_f32 v4, v12, v13
	s_nop 0
	v_addc_co_u32_e32 v3, vcc, 0, v1, vcc
	global_store_short_d16_hi v[2:3], v4, off
	v_add_co_u32_e32 v2, vcc, 0x20000, v0
	global_store_short v[0:1], v4, off
	s_nop 0
	v_addc_co_u32_e32 v3, vcc, 0, v1, vcc
	v_add_co_u32_e32 v0, vcc, 0x30000, v0
	v_cvt_pk_bf16_f32 v5, v14, v15
	s_nop 0
	v_addc_co_u32_e32 v1, vcc, 0, v1, vcc
	global_store_short_d16_hi v[0:1], v5, off
	v_mov_b32_e32 v0, 0
	global_store_short v[2:3], v5, off
	v_mov_b32_e32 v1, v0
	v_mov_b32_e32 v2, v0
	v_mov_b32_e32 v3, v0
	v_mov_b32_e32 v4, v0
	v_mov_b32_e32 v5, v0
	v_mov_b32_e32 v6, v0
	v_mov_b32_e32 v7, v0
	v_mov_b32_e32 v8, v0
	v_mov_b32_e32 v9, v0
	v_mov_b32_e32 v10, v0
	v_mov_b32_e32 v11, v0
	v_mov_b32_e32 v12, v0
	v_mov_b32_e32 v13, v0
	v_mov_b32_e32 v14, v0
	v_mov_b32_e32 v15, v0
	v_mov_b32_e32 v16, v0
	v_mov_b32_e32 v17, v0
	v_mov_b32_e32 v18, v0
	v_mov_b32_e32 v19, v0
	v_mov_b32_e32 v20, v0
	v_mov_b32_e32 v21, v0
	v_mov_b32_e32 v22, v0
	v_mov_b32_e32 v23, v0
	v_mov_b32_e32 v24, v0
	v_mov_b32_e32 v25, v0
	v_mov_b32_e32 v26, v0
	v_mov_b32_e32 v27, v0
	v_mov_b32_e32 v28, v0
	v_mov_b32_e32 v29, v0
	v_mov_b32_e32 v30, v0
	v_mov_b32_e32 v31, v0
	v_mov_b32_e32 v32, v0
	v_mov_b32_e32 v33, v0
	v_mov_b32_e32 v34, v0
	v_mov_b32_e32 v35, v0
	v_mov_b32_e32 v36, v0
	v_mov_b32_e32 v37, v0
	v_mov_b32_e32 v38, v0
	v_mov_b32_e32 v39, v0
	v_mov_b32_e32 v40, v0
	v_mov_b32_e32 v41, v0
	v_mov_b32_e32 v42, v0
	v_mov_b32_e32 v43, v0
	v_mov_b32_e32 v44, v0
	v_mov_b32_e32 v45, v0
	v_mov_b32_e32 v46, v0
	v_mov_b32_e32 v47, v0
	v_mov_b32_e32 v48, v0
	v_mov_b32_e32 v49, v0
	v_mov_b32_e32 v50, v0
	v_mov_b32_e32 v51, v0
	v_mov_b32_e32 v52, v0
	v_mov_b32_e32 v53, v0
	v_mov_b32_e32 v54, v0
	v_mov_b32_e32 v55, v0
	v_mov_b32_e32 v56, v0
	v_mov_b32_e32 v57, v0
	v_mov_b32_e32 v58, v0
	v_mov_b32_e32 v59, v0
	v_mov_b32_e32 v60, v0
	v_mov_b32_e32 v61, v0
	v_mov_b32_e32 v62, v0
	v_mov_b32_e32 v63, v0
	v_mov_b32_e32 v64, v0
	v_mov_b32_e32 v65, v0
	v_mov_b32_e32 v66, v0
	v_mov_b32_e32 v67, v0
	v_mov_b32_e32 v68, v0
	v_mov_b32_e32 v69, v0
	v_mov_b32_e32 v70, v0
	v_mov_b32_e32 v71, v0
	v_mov_b32_e32 v72, v0
	v_mov_b32_e32 v73, v0
	v_mov_b32_e32 v74, v0
	v_mov_b32_e32 v75, v0
	v_mov_b32_e32 v76, v0
	v_mov_b32_e32 v77, v0
	v_mov_b32_e32 v78, v0
	v_mov_b32_e32 v79, v0
	v_mov_b32_e32 v80, v0
	v_mov_b32_e32 v81, v0
	v_mov_b32_e32 v82, v0
	v_mov_b32_e32 v83, v0
	v_mov_b32_e32 v84, v0
	v_mov_b32_e32 v85, v0
	v_mov_b32_e32 v86, v0
	v_mov_b32_e32 v87, v0
	v_mov_b32_e32 v88, v0
	v_mov_b32_e32 v89, v0
	v_mov_b32_e32 v90, v0
	v_mov_b32_e32 v91, v0
	v_mov_b32_e32 v92, v0
	v_mov_b32_e32 v93, v0
	v_mov_b32_e32 v94, v0
	v_mov_b32_e32 v95, v0
	v_mov_b32_e32 v96, v0
	v_mov_b32_e32 v97, v0
	v_mov_b32_e32 v98, v0
	v_mov_b32_e32 v99, v0
	v_mov_b32_e32 v100, v0
	v_mov_b32_e32 v101, v0
	v_mov_b32_e32 v102, v0
	v_mov_b32_e32 v103, v0
	v_mov_b32_e32 v104, v0
	v_mov_b32_e32 v105, v0
	v_mov_b32_e32 v106, v0
	v_mov_b32_e32 v107, v0
	v_mov_b32_e32 v108, v0
	v_mov_b32_e32 v109, v0
	v_mov_b32_e32 v110, v0
	v_mov_b32_e32 v111, v0
	v_mov_b32_e32 v112, v0
	v_mov_b32_e32 v113, v0
	v_mov_b32_e32 v114, v0
	v_mov_b32_e32 v115, v0
	v_mov_b32_e32 v116, v0
	v_mov_b32_e32 v117, v0
	v_mov_b32_e32 v118, v0
	v_mov_b32_e32 v119, v0
	v_mov_b32_e32 v120, v0
	v_mov_b32_e32 v121, v0
	v_mov_b32_e32 v122, v0
	v_mov_b32_e32 v123, v0
	v_mov_b32_e32 v124, v0
	v_mov_b32_e32 v125, v0
	v_mov_b32_e32 v126, v0
	v_mov_b32_e32 v127, v0
	s_branch .LBB0_1107

; #define MFMA(a, b, c) __builtin_amdgcn_mfma_f32_32x32x16_bf16((a), (b), (c), 0, 0, 0)
; DI f32x16 zero16() { f32x16 z; for (int i = 0; i < 16; ++i) z[i] = 0.f; return z; }
;     ...
;   const int fP = r * 128, fsw = (r >> 1) & 7;
;   const int fA = wm * 8192 + fP, fB = 32768 + wn * 16384 + fP;
;   f32x16 acc[2][4];
; #pragma unroll
;   for (int i = 0; i < 2; ++i)
; #pragma unroll
;     for (int j = 0; j < 4; ++j) acc[i][j] = zero16();
;   __syncthreads();
;   G_DMA(0, 0);
;   asm volatile("s_waitcnt vmcnt(0)" ::: "memory");
;   asm volatile("s_waitcnt lgkmcnt(0)" ::: "memory"); __builtin_amdgcn_s_barrier(); asm volatile("" ::: "memory");
;   int cur = 0;
;   for (int s = 0; s < S; ++s) {
;     G_DMA(s + 1, cur ^ BUFB);
;     {
;       const char* Ab = smem + cur + fA;
;       const char* Bb = smem + cur + fB;
;       __builtin_amdgcn_sched_barrier(0);
; #pragma unroll
;       for (int kk = 0; kk < 4; ++kk) {
;         const int ko = (((kk * 2 + hh) ^ fsw) << 4);
;         bf16x8 af[2], wf[4];
;         af[0] = *(const bf16x8*)(Ab + ko); af[1] = *(const bf16x8*)(Ab + 4096 + ko);
; #pragma unroll
;         for (int ni = 0; ni < 4; ++ni) wf[ni] = *(const bf16x8*)(Bb + ni * 4096 + ko);
; #pragma unroll
;         for (int mi = 0; mi < 2; ++mi)
; #pragma unroll
;           for (int ni = 0; ni < 4; ++ni) acc[mi][ni] = MFMA(wf[ni], af[mi], acc[mi][ni]);
;         if (kk == 1) __builtin_amdgcn_sched_barrier(0);
;       }
;       __builtin_amdgcn_sched_barrier(0);
;     }
;     asm volatile("s_waitcnt vmcnt(0)" ::: "memory");
.LBB0_1286:
	v_add3_u32 v187, s8, v144, v147
	v_add3_u32 v208, s8, v149, v147
	v_add_u32_e32 v182, v208, v148
	v_add_u32_e32 v183, v187, v148
	ds_read_b128 v[192:195], v182 offset:32768
	ds_read_b128 v[216:219], v183
	ds_read_b128 v[196:199], v182 offset:36864
	ds_read_b128 v[200:203], v182 offset:40960
	ds_read_b128 v[204:207], v182 offset:45056
	ds_read_b128 v[220:223], v183 offset:4096
	v_add_u32_e32 v184, v208, v145
	v_add_u32_e32 v185, v187, v145
	ds_read_b128 v[224:227], v184 offset:32768
	ds_read_b128 v[240:243], v185
	ds_read_b128 v[228:231], v184 offset:36864
	ds_read_b128 v[232:235], v184 offset:40960
	ds_read_b128 v[236:239], v184 offset:45056
	ds_read_b128 v[244:247], v185 offset:4096
	s_lshl_b32 s9, s7, 16
	s_and_b32 s9, s9, 0x200000
	s_add_i32 s9, s93, s9
	s_lshl_b32 s9, s9, 1
	s_and_b32 s28, s9, 0x700000
	s_xor_b32 s9, s8, 0x10000
	v_add_u32_e32 v128, s9, v150
	v_lshl_add_u64 v[160:161], v[136:137], 0, s[40:41]
	v_readfirstlane_b32 s22, v128
	v_add_u32_e32 v164, 0x2000, v128
	v_lshl_add_u64 v[162:163], v[160:161], 0, s[24:25]
	s_mov_b32 m0, s22
	v_readfirstlane_b32 s22, v164
	v_add_u32_e32 v164, 0x4000, v128
	global_load_lds_dwordx4 v[162:163], off
	s_waitcnt lgkmcnt(10)
	v_mfma_f32_32x32x16_bf16 v[112:127], v[192:195], v[216:219], v[112:127]
	s_waitcnt lgkmcnt(9)
	v_mfma_f32_32x32x16_bf16 v[96:111], v[196:199], v[216:219], v[96:111]
	v_lshl_add_u64 v[162:163], v[160:161], 0, s[42:43]
	s_mov_b32 m0, s22
	v_readfirstlane_b32 s22, v164
	global_load_lds_dwordx4 v[162:163], off
	s_waitcnt lgkmcnt(8)
	v_mfma_f32_32x32x16_bf16 v[80:95], v[200:203], v[216:219], v[80:95]
	s_waitcnt lgkmcnt(7)
	v_mfma_f32_32x32x16_bf16 v[64:79], v[204:207], v[216:219], v[64:79]
	v_lshl_add_u64 v[162:163], v[160:161], 0, s[44:45]
	s_mov_b32 m0, s22
	v_lshl_add_u64 v[158:159], v[138:139], 0, s[28:29]
	global_load_lds_dwordx4 v[162:163], off
	s_waitcnt lgkmcnt(6)
	v_mfma_f32_32x32x16_bf16 v[48:63], v[192:195], v[220:223], v[48:63]
	v_mfma_f32_32x32x16_bf16 v[32:47], v[196:199], v[220:223], v[32:47]
	v_add_u32_e32 v162, 0x6000, v128
	v_lshl_add_u64 v[160:161], v[160:161], 0, s[46:47]
	v_readfirstlane_b32 s22, v162
	v_add_u32_e32 v162, 0x8000, v128
	s_mov_b32 m0, s22
	v_lshl_add_u64 v[158:159], v[158:159], 0, s[40:41]
	v_readfirstlane_b32 s22, v162
	v_add_u32_e32 v162, 0xa000, v128
	global_load_lds_dwordx4 v[160:161], off
	v_mfma_f32_32x32x16_bf16 v[16:31], v[200:203], v[220:223], v[16:31]
	v_mfma_f32_32x32x16_bf16 v[0:15], v[204:207], v[220:223], v[0:15]
	v_lshl_add_u64 v[160:161], v[158:159], 0, s[48:49]
	s_mov_b32 m0, s22
	v_readfirstlane_b32 s22, v162
	v_add_u32_e32 v162, 0xc000, v128
	global_load_lds_dwordx4 v[160:161], off
	v_add_u32_e32 v182, v208, v141
	v_add_u32_e32 v183, v187, v141
	ds_read_b128 v[192:195], v182 offset:32768
	ds_read_b128 v[216:219], v183
	ds_read_b128 v[196:199], v182 offset:36864
	ds_read_b128 v[200:203], v182 offset:40960
	ds_read_b128 v[204:207], v182 offset:45056
	ds_read_b128 v[220:223], v183 offset:4096
	s_waitcnt lgkmcnt(10)
	v_mfma_f32_32x32x16_bf16 v[112:127], v[224:227], v[240:243], v[112:127]
	s_waitcnt lgkmcnt(9)
	v_mfma_f32_32x32x16_bf16 v[96:111], v[228:231], v[240:243], v[96:111]
	v_lshl_add_u64 v[160:161], v[158:159], 0, s[50:51]
	s_mov_b32 m0, s22
	v_readfirstlane_b32 s22, v162
	v_add_u32_e32 v128, 0xe000, v128
	global_load_lds_dwordx4 v[160:161], off
	s_waitcnt lgkmcnt(8)
	v_mfma_f32_32x32x16_bf16 v[80:95], v[232:235], v[240:243], v[80:95]
	s_waitcnt lgkmcnt(7)
	v_mfma_f32_32x32x16_bf16 v[64:79], v[236:239], v[240:243], v[64:79]
	v_lshl_add_u64 v[160:161], v[158:159], 0, s[52:53]
	s_mov_b32 m0, s22
	v_readfirstlane_b32 s22, v128
	global_load_lds_dwordx4 v[160:161], off
	s_waitcnt lgkmcnt(6)
	v_mfma_f32_32x32x16_bf16 v[48:63], v[224:227], v[244:247], v[48:63]
	v_mfma_f32_32x32x16_bf16 v[32:47], v[228:231], v[244:247], v[32:47]
	v_lshl_add_u64 v[158:159], v[158:159], 0, s[56:57]
	s_mov_b32 m0, s22
	s_add_i32 s8, s8, 0
	global_load_lds_dwordx4 v[158:159], off
	v_mfma_f32_32x32x16_bf16 v[16:31], v[232:235], v[244:247], v[16:31]
	v_mfma_f32_32x32x16_bf16 v[0:15], v[236:239], v[244:247], v[0:15]
	v_add_u32_e32 v184, v208, v140
	v_add_u32_e32 v185, v187, v140
	ds_read_b128 v[224:227], v184 offset:32768
	ds_read_b128 v[240:243], v185
	ds_read_b128 v[228:231], v184 offset:36864
	ds_read_b128 v[232:235], v184 offset:40960
	ds_read_b128 v[236:239], v184 offset:45056
	ds_read_b128 v[244:247], v185 offset:4096
	s_waitcnt lgkmcnt(10)
	v_mfma_f32_32x32x16_bf16 v[112:127], v[192:195], v[216:219], v[112:127]
	s_waitcnt lgkmcnt(9)
	v_mfma_f32_32x32x16_bf16 v[96:111], v[196:199], v[216:219], v[96:111]
	s_waitcnt lgkmcnt(8)
	v_mfma_f32_32x32x16_bf16 v[80:95], v[200:203], v[216:219], v[80:95]
	s_waitcnt lgkmcnt(7)
	v_mfma_f32_32x32x16_bf16 v[64:79], v[204:207], v[216:219], v[64:79]
	s_waitcnt lgkmcnt(6)
	v_mfma_f32_32x32x16_bf16 v[48:63], v[192:195], v[220:223], v[48:63]
	v_mfma_f32_32x32x16_bf16 v[32:47], v[196:199], v[220:223], v[32:47]
	v_mfma_f32_32x32x16_bf16 v[16:31], v[200:203], v[220:223], v[16:31]
	v_mfma_f32_32x32x16_bf16 v[0:15], v[204:207], v[220:223], v[0:15]
	s_waitcnt lgkmcnt(4)
	v_mfma_f32_32x32x16_bf16 v[112:127], v[224:227], v[240:243], v[112:127]
	s_waitcnt lgkmcnt(3)
	v_mfma_f32_32x32x16_bf16 v[96:111], v[228:231], v[240:243], v[96:111]
	s_waitcnt lgkmcnt(2)
	v_mfma_f32_32x32x16_bf16 v[80:95], v[232:235], v[240:243], v[80:95]
	s_waitcnt lgkmcnt(1)
	v_mfma_f32_32x32x16_bf16 v[64:79], v[236:239], v[240:243], v[64:79]
	s_waitcnt lgkmcnt(0)
	v_mfma_f32_32x32x16_bf16 v[48:63], v[224:227], v[244:247], v[48:63]
	v_mfma_f32_32x32x16_bf16 v[32:47], v[228:231], v[244:247], v[32:47]
	v_mfma_f32_32x32x16_bf16 v[16:31], v[232:235], v[244:247], v[16:31]
	v_mfma_f32_32x32x16_bf16 v[0:15], v[236:239], v[244:247], v[0:15]
	s_waitcnt vmcnt(0)
	s_waitcnt lgkmcnt(0)
	s_barrier
; #define MFMA(a, b, c) __builtin_amdgcn_mfma_f32_32x32x16_bf16((a), (b), (c), 0, 0, 0)
;     ...
;   G_DMA(0, 0);
;   asm volatile("s_waitcnt vmcnt(0)" ::: "memory");
;   asm volatile("s_waitcnt lgkmcnt(0)" ::: "memory"); __builtin_amdgcn_s_barrier(); asm volatile("" ::: "memory");
;   int cur = 0;
;   for (int s = 0; s < S; ++s) {
;     G_DMA(s + 1, cur ^ BUFB);
;     {
;       const char* Ab = smem + cur + fA;
;       const char* Bb = smem + cur + fB;
;       __builtin_amdgcn_sched_barrier(0);
; #pragma unroll
;       for (int kk = 0; kk < 4; ++kk) {
;         const int ko = (((kk * 2 + hh) ^ fsw) << 4);
;         bf16x8 af[2], wf[4];
;         af[0] = *(const bf16x8*)(Ab + ko); af[1] = *(const bf16x8*)(Ab + 4096 + ko);
; #pragma unroll
;         for (int ni = 0; ni < 4; ++ni) wf[ni] = *(const bf16x8*)(Bb + ni * 4096 + ko);
; #pragma unroll
;         for (int mi = 0; mi < 2; ++mi)
; #pragma unroll
;           for (int ni = 0; ni < 4; ++ni) acc[mi][ni] = MFMA(wf[ni], af[mi], acc[mi][ni]);
;         if (kk == 1) __builtin_amdgcn_sched_barrier(0);
;       }
;       __builtin_amdgcn_sched_barrier(0);
;     }
;     asm volatile("s_waitcnt vmcnt(0)" ::: "memory");
	s_add_u32 s40, s40, 0x80
	s_addc_u32 s41, s41, 0
	s_add_i32 s7, s7, 1
	s_cmpk_eq_i32 s40, 0xf80
	s_mov_b32 s8, s9
	s_cbranch_scc0 .LBB0_1286
	s_mov_b64 s[8:9], 0xf80
	v_readfirstlane_b32 s7, v150
	v_lshl_add_u64 v[136:137], v[132:133], 0, s[8:9]
	s_mov_b32 m0, s7
	s_mov_b64 s[22:23], 0x40f80
	v_readfirstlane_b32 s7, v151
	global_load_lds_dwordx4 v[136:137], off
	v_lshl_add_u64 v[136:137], v[132:133], 0, s[22:23]
	s_mov_b32 m0, s7
	s_mov_b64 s[24:25], 0x80f80
	v_readfirstlane_b32 s7, v152
	global_load_lds_dwordx4 v[136:137], off
	v_lshl_add_u64 v[136:137], v[132:133], 0, s[24:25]
	s_mov_b32 m0, s7
	s_mov_b64 s[40:41], 0xc0f80
	v_readfirstlane_b32 s7, v153
	global_load_lds_dwordx4 v[136:137], off
	v_lshl_add_u64 v[132:133], v[132:133], 0, s[40:41]
	s_mov_b32 m0, s7
	v_readfirstlane_b32 s7, v154
	global_load_lds_dwordx4 v[132:133], off
	v_lshl_add_u64 v[132:133], v[134:135], 0, s[8:9]
	s_mov_b32 m0, s7
	v_readfirstlane_b32 s7, v155
	global_load_lds_dwordx4 v[132:133], off
	v_lshl_add_u64 v[132:133], v[134:135], 0, s[22:23]
	s_mov_b32 m0, s7
	v_readfirstlane_b32 s7, v156
	global_load_lds_dwordx4 v[132:133], off
	v_lshl_add_u64 v[132:133], v[134:135], 0, s[24:25]
	s_mov_b32 m0, s7
	v_readfirstlane_b32 s7, v157
	global_load_lds_dwordx4 v[132:133], off
	v_lshl_add_u64 v[132:133], v[134:135], 0, s[40:41]
	s_mov_b32 m0, s7
	s_add_i32 s28, s6, -1
	global_load_lds_dwordx4 v[132:133], off
	s_lshl_b64 s[8:9], s[28:29], 25
	v_readlane_b32 s22, v253, 39
	v_readlane_b32 s23, v253, 40
	s_add_u32 s40, s22, s8
	v_lshlrev_b32_e32 v132, 6, v146
	s_addc_u32 s41, s23, s9
	v_readlane_b32 s8, v253, 27
	v_ashrrev_i32_e32 v133, 31, v132
	v_readlane_b32 s9, v253, 28
	s_add_i32 s7, 0, 0x10000
	v_lshlrev_b32_e32 v128, 3, v142
	v_lshl_add_u64 v[162:163], v[132:133], 0, s[8:9]
	v_lshlrev_b32_e32 v132, 4, v142
	v_mov_b32_e32 v133, v129
	v_or_b32_e32 v162, v162, v143
	v_lshl_add_u64 v[132:133], s[40:41], 0, v[132:133]
	v_add3_u32 v138, s7, v144, v147
	v_add3_u32 v139, s7, v149, v147
	v_add_u32_e32 v182, v139, v148
	v_add_u32_e32 v183, v138, v148
	ds_read_b128 v[134:137], v182 offset:32768
	ds_read_b128 v[146:149], v183
	ds_read_b128 v[150:153], v182 offset:36864
	ds_read_b128 v[154:157], v182 offset:40960
	ds_read_b128 v[158:161], v182 offset:45056
	ds_read_b128 v[192:195], v183 offset:4096
	v_add_u32_e32 v184, v139, v145
	v_add_u32_e32 v185, v138, v145
	ds_read_b128 v[196:199], v184 offset:32768
	ds_read_b128 v[220:223], v185
	ds_read_b128 v[200:203], v184 offset:36864
	ds_read_b128 v[204:207], v184 offset:40960
	ds_read_b128 v[216:219], v184 offset:45056
	ds_read_b128 v[224:227], v185 offset:4096
	s_waitcnt lgkmcnt(10)
	v_mfma_f32_32x32x16_bf16 v[112:127], v[134:137], v[146:149], v[112:127]
	s_waitcnt lgkmcnt(9)
	v_mfma_f32_32x32x16_bf16 v[96:111], v[150:153], v[146:149], v[96:111]
	s_waitcnt lgkmcnt(8)
	v_mfma_f32_32x32x16_bf16 v[80:95], v[154:157], v[146:149], v[80:95]
	s_waitcnt lgkmcnt(7)
	v_mfma_f32_32x32x16_bf16 v[64:79], v[158:161], v[146:149], v[64:79]
	s_waitcnt lgkmcnt(6)
	v_mfma_f32_32x32x16_bf16 v[48:63], v[134:137], v[192:195], v[48:63]
	v_mfma_f32_32x32x16_bf16 v[32:47], v[150:153], v[192:195], v[32:47]
	v_mfma_f32_32x32x16_bf16 v[16:31], v[154:157], v[192:195], v[16:31]
	v_mfma_f32_32x32x16_bf16 v[0:15], v[158:161], v[192:195], v[0:15]
	v_add_u32_e32 v182, v139, v141
	v_add_u32_e32 v183, v138, v141
	ds_read_b128 v[134:137], v182 offset:32768
	ds_read_b128 v[146:149], v183
	ds_read_b128 v[150:153], v182 offset:36864
	ds_read_b128 v[154:157], v182 offset:40960
	ds_read_b128 v[158:161], v182 offset:45056
	ds_read_b128 v[192:195], v183 offset:4096
	s_waitcnt lgkmcnt(10)
	v_mfma_f32_32x32x16_bf16 v[112:127], v[196:199], v[220:223], v[112:127]
	s_waitcnt lgkmcnt(9)
	v_mfma_f32_32x32x16_bf16 v[96:111], v[200:203], v[220:223], v[96:111]
	s_waitcnt lgkmcnt(8)
	v_mfma_f32_32x32x16_bf16 v[80:95], v[204:207], v[220:223], v[80:95]
	s_waitcnt lgkmcnt(7)
	v_mfma_f32_32x32x16_bf16 v[64:79], v[216:219], v[220:223], v[64:79]
	s_waitcnt lgkmcnt(6)
	v_mfma_f32_32x32x16_bf16 v[48:63], v[196:199], v[224:227], v[48:63]
	v_mfma_f32_32x32x16_bf16 v[32:47], v[200:203], v[224:227], v[32:47]
	v_mfma_f32_32x32x16_bf16 v[16:31], v[204:207], v[224:227], v[16:31]
	v_mfma_f32_32x32x16_bf16 v[0:15], v[216:219], v[224:227], v[0:15]
	v_add_u32_e32 v184, v139, v140
	v_add_u32_e32 v185, v138, v140
	ds_read_b128 v[196:199], v184 offset:32768
	ds_read_b128 v[220:223], v185
	ds_read_b128 v[200:203], v184 offset:36864
	ds_read_b128 v[204:207], v184 offset:40960
	ds_read_b128 v[216:219], v184 offset:45056
	ds_read_b128 v[224:227], v185 offset:4096
	s_waitcnt lgkmcnt(10)
	v_mfma_f32_32x32x16_bf16 v[112:127], v[134:137], v[146:149], v[112:127]
	s_waitcnt lgkmcnt(9)
	v_mfma_f32_32x32x16_bf16 v[96:111], v[150:153], v[146:149], v[96:111]
	s_waitcnt lgkmcnt(8)
	v_mfma_f32_32x32x16_bf16 v[80:95], v[154:157], v[146:149], v[80:95]
	s_waitcnt lgkmcnt(7)
	v_mfma_f32_32x32x16_bf16 v[64:79], v[158:161], v[146:149], v[64:79]
	s_waitcnt lgkmcnt(6)
	v_mfma_f32_32x32x16_bf16 v[48:63], v[134:137], v[192:195], v[48:63]
	v_mfma_f32_32x32x16_bf16 v[32:47], v[150:153], v[192:195], v[32:47]
	v_mfma_f32_32x32x16_bf16 v[16:31], v[154:157], v[192:195], v[16:31]
	v_mfma_f32_32x32x16_bf16 v[0:15], v[158:161], v[192:195], v[0:15]
	s_waitcnt lgkmcnt(4)
	v_mfma_f32_32x32x16_bf16 v[112:127], v[196:199], v[220:223], v[112:127]
	s_waitcnt lgkmcnt(3)
	v_mfma_f32_32x32x16_bf16 v[96:111], v[200:203], v[220:223], v[96:111]
	s_waitcnt lgkmcnt(2)
	v_mfma_f32_32x32x16_bf16 v[80:95], v[204:207], v[220:223], v[80:95]
	s_waitcnt lgkmcnt(1)
	v_mfma_f32_32x32x16_bf16 v[64:79], v[216:219], v[220:223], v[64:79]
	s_waitcnt lgkmcnt(0)
; DI float lo2f(unsigned v) { return __uint_as_float(v << 16); }
;     ...
;     if ((s & (nk - 1)) == nk - 1) {
;       const int q = slot + (s >> lnk) * nslots;
;       int mt, nt; G_TILEMAP(q, mt, nt);
;       if (dostore) {
; #pragma unroll
;         for (int mi = 0; mi < 2; ++mi) {
;           const size_t m = (size_t)mt * 256 + wm * 64 + mi * 32 + r;
; #pragma unroll
;           for (int ni = 0; ni < 4; ++ni) {
;             __builtin_amdgcn_sched_barrier(0);
;             if (MODE == 0) {
; #pragma unroll
;               for (int gp = 0; gp < 2; ++gp) {
;                 const int g0 = 2 * gp;
;                 uint2 pa, pb;
;                 pa.x = pack2(acc[mi][ni][4 * g0], acc[mi][ni][4 * g0 + 1]); pa.y = pack2(acc[mi][ni][4 * g0 + 2], acc[mi][ni][4 * g0 + 3]);
;                 pb.x = pack2(acc[mi][ni][4 * g0 + 4], acc[mi][ni][4 * g0 + 5]); pb.y = pack2(acc[mi][ni][4 * g0 + 6], acc[mi][ni][4 * g0 + 7]);
;                 { auto rx = __builtin_amdgcn_permlane32_swap(pa.x, pb.x, false, false); pa.x = rx[0]; pb.x = rx[1]; }
;                 { auto ry = __builtin_amdgcn_permlane32_swap(pa.y, pb.y, false, false); pa.y = ry[0]; pb.y = ry[1]; }
;                 const int col = nt * 256 + wn * 128 + ni * 32 + 8 * g0 + 8 * hh;
;                 const uint4 v4 = make_uint4(pa.x, pa.y, pb.x, pb.y);
;                 if (outp != nullptr && nt >= 32) *(uint4*)(outp + m * 2048 + (col - 8192)) = v4;
;                 else if (col < nvalid) *(uint4*)(C + m * ldc + col) = v4;
;               }
;             } else if (MODE == 1) {
; #pragma unroll
;               for (int gp = 0; gp < 2; ++gp) {
;                 const int g0 = 2 * gp;
;                 const int nb_ = nt * 256 + wn * 128 + ni * 32 + 8 * g0;
;                 const uint2 ra = *(const uint2*)(res + m * 1024 + nb_ + 4 * hh), rb = *(const uint2*)(res + m * 1024 + nb_ + 8 + 4 * hh);
;                 uint2 pa, pb;
;                 pa.x = pack2(alpha * lo2f(ra.x) + acc[mi][ni][4 * g0], alpha * hi2f(ra.x) + acc[mi][ni][4 * g0 + 1]);
;                 pa.y = pack2(alpha * lo2f(ra.y) + acc[mi][ni][4 * g0 + 2], alpha * hi2f(ra.y) + acc[mi][ni][4 * g0 + 3]);
;                 pb.x = pack2(alpha * lo2f(rb.x) + acc[mi][ni][4 * g0 + 4], alpha * hi2f(rb.x) + acc[mi][ni][4 * g0 + 5]);
;                 pb.y = pack2(alpha * lo2f(rb.y) + acc[mi][ni][4 * g0 + 6], alpha * hi2f(rb.y) + acc[mi][ni][4 * g0 + 7]);
	v_mfma_f32_32x32x16_bf16 v[48:63], v[196:199], v[224:227], v[48:63]
	v_mfma_f32_32x32x16_bf16 v[32:47], v[200:203], v[224:227], v[32:47]
	v_mfma_f32_32x32x16_bf16 v[16:31], v[204:207], v[224:227], v[16:31]
	v_mfma_f32_32x32x16_bf16 v[0:15], v[216:219], v[224:227], v[0:15]
	s_waitcnt vmcnt(0)
	v_lshlrev_b64 v[136:137], 11, v[162:163]
	v_lshl_add_u64 v[138:139], s[40:41], 0, v[136:137]
	v_lshl_add_u64 v[144:145], v[132:133], 0, v[136:137]
	v_readlane_b32 s7, v251, 32
	s_lshl_b32 s7, s7, 1
	v_mov_b32_e32 v135, v129
	v_lshl_or_b32 v134, v131, 8, s7
	v_lshl_add_u64 v[138:139], v[138:139], 0, v[134:135]
	v_lshl_add_u64 v[138:139], v[138:139], 0, v[128:129]
	global_load_dwordx2 v[140:141], v[138:139], off
	global_load_dwordx2 v[142:143], v[138:139], off offset:16
	s_mov_b32 s8, 0x3fd744fd
	s_waitcnt vmcnt(0)
	v_lshlrev_b32_e32 v146, 16, v140
	v_and_b32_e32 v147, 0xffff0000, v140
	v_pk_fma_f32 v[112:113], v[146:147], s[8:9], v[112:113] op_sel_hi:[1,0,1]
	s_nop 0
	v_cvt_pk_bf16_f32 v140, v112, v113
	v_lshlrev_b32_e32 v112, 16, v141
	v_and_b32_e32 v113, 0xffff0000, v141
	v_pk_fma_f32 v[112:113], v[112:113], s[8:9], v[114:115] op_sel_hi:[1,0,1]
	s_nop 0
	v_cvt_pk_bf16_f32 v141, v112, v113
	v_lshlrev_b32_e32 v112, 16, v142
	v_and_b32_e32 v113, 0xffff0000, v142
	v_pk_fma_f32 v[112:113], v[112:113], s[8:9], v[116:117] op_sel_hi:[1,0,1]
	s_nop 0
	v_cvt_pk_bf16_f32 v142, v112, v113
	v_lshlrev_b32_e32 v112, 16, v143
	v_and_b32_e32 v113, 0xffff0000, v143
	v_pk_fma_f32 v[112:113], v[112:113], s[8:9], v[118:119] op_sel_hi:[1,0,1]
	v_permlane32_swap_b32_e32 v140, v142
	v_cvt_pk_bf16_f32 v143, v112, v113
	s_nop 1
	v_permlane32_swap_b32_e32 v141, v143
	v_lshl_add_u64 v[112:113], v[144:145], 0, v[134:135]
	global_store_dwordx4 v[112:113], v[140:143], off
	global_load_dwordx2 v[114:115], v[138:139], off offset:32
	global_load_dwordx2 v[116:117], v[138:139], off offset:48
	s_waitcnt vmcnt(1)
	v_lshlrev_b32_e32 v118, 16, v114
	v_and_b32_e32 v119, 0xffff0000, v114
	v_pk_fma_f32 v[118:119], v[118:119], s[8:9], v[120:121] op_sel_hi:[1,0,1]
	s_nop 0
	v_cvt_pk_bf16_f32 v114, v118, v119
	v_lshlrev_b32_e32 v118, 16, v115
	v_and_b32_e32 v119, 0xffff0000, v115
	v_pk_fma_f32 v[118:119], v[118:119], s[8:9], v[122:123] op_sel_hi:[1,0,1]
	s_nop 0
	v_cvt_pk_bf16_f32 v115, v118, v119
	s_waitcnt vmcnt(0)
	v_lshlrev_b32_e32 v118, 16, v116
	v_and_b32_e32 v119, 0xffff0000, v116
	v_pk_fma_f32 v[118:119], v[118:119], s[8:9], v[124:125] op_sel_hi:[1,0,1]
	s_nop 0
	v_cvt_pk_bf16_f32 v116, v118, v119
	v_lshlrev_b32_e32 v118, 16, v117
	v_and_b32_e32 v119, 0xffff0000, v117
	v_pk_fma_f32 v[118:119], v[118:119], s[8:9], v[126:127] op_sel_hi:[1,0,1]
	v_permlane32_swap_b32_e32 v114, v116
	v_cvt_pk_bf16_f32 v117, v118, v119
	s_nop 1
	v_permlane32_swap_b32_e32 v115, v117
	global_store_dwordx4 v[112:113], v[114:117], off offset:32
	global_load_dwordx2 v[114:115], v[138:139], off offset:64
	s_nop 0
	global_load_dwordx2 v[116:117], v[138:139], off offset:80
	s_waitcnt vmcnt(1)
	v_lshlrev_b32_e32 v118, 16, v114
	v_and_b32_e32 v119, 0xffff0000, v114
	v_lshlrev_b32_e32 v114, 16, v115
	v_and_b32_e32 v115, 0xffff0000, v115
	v_pk_fma_f32 v[96:97], v[118:119], s[8:9], v[96:97] op_sel_hi:[1,0,1]
	v_pk_fma_f32 v[98:99], v[114:115], s[8:9], v[98:99] op_sel_hi:[1,0,1]
	v_cvt_pk_bf16_f32 v96, v96, v97
	v_cvt_pk_bf16_f32 v97, v98, v99
	s_waitcnt vmcnt(0)
	v_lshlrev_b32_e32 v98, 16, v116
	v_and_b32_e32 v99, 0xffff0000, v116
	v_pk_fma_f32 v[98:99], v[98:99], s[8:9], v[100:101] op_sel_hi:[1,0,1]
	v_lshlrev_b32_e32 v100, 16, v117
	v_and_b32_e32 v101, 0xffff0000, v117
	v_pk_fma_f32 v[100:101], v[100:101], s[8:9], v[102:103] op_sel_hi:[1,0,1]
	v_cvt_pk_bf16_f32 v98, v98, v99
	v_cvt_pk_bf16_f32 v99, v100, v101
	s_nop 0
	v_permlane32_swap_b32_e32 v96, v98
	v_permlane32_swap_b32_e32 v97, v99
	global_store_dwordx4 v[112:113], v[96:99], off offset:64
	global_load_dwordx2 v[96:97], v[138:139], off offset:96
	s_nop 0
	global_load_dwordx2 v[98:99], v[138:139], off offset:112
	s_waitcnt vmcnt(1)
	v_lshlrev_b32_e32 v100, 16, v96
	v_and_b32_e32 v101, 0xffff0000, v96
	v_pk_fma_f32 v[100:101], v[100:101], s[8:9], v[104:105] op_sel_hi:[1,0,1]
	s_nop 0
	v_cvt_pk_bf16_f32 v96, v100, v101
	v_lshlrev_b32_e32 v100, 16, v97
	v_and_b32_e32 v101, 0xffff0000, v97
	v_pk_fma_f32 v[100:101], v[100:101], s[8:9], v[106:107] op_sel_hi:[1,0,1]
	s_nop 0
	v_cvt_pk_bf16_f32 v97, v100, v101
	s_waitcnt vmcnt(0)
	v_lshlrev_b32_e32 v100, 16, v98
	v_and_b32_e32 v101, 0xffff0000, v98
	v_pk_fma_f32 v[100:101], v[100:101], s[8:9], v[108:109] op_sel_hi:[1,0,1]
	s_nop 0
	v_cvt_pk_bf16_f32 v98, v100, v101
	v_lshlrev_b32_e32 v100, 16, v99
	v_and_b32_e32 v101, 0xffff0000, v99
	v_pk_fma_f32 v[100:101], v[100:101], s[8:9], v[110:111] op_sel_hi:[1,0,1]
	v_permlane32_swap_b32_e32 v96, v98
	v_cvt_pk_bf16_f32 v99, v100, v101
	s_nop 1
	v_permlane32_swap_b32_e32 v97, v99
	global_store_dwordx4 v[112:113], v[96:99], off offset:96
	global_load_dwordx2 v[96:97], v[138:139], off offset:128
	s_nop 0
	global_load_dwordx2 v[98:99], v[138:139], off offset:144
	s_waitcnt vmcnt(1)
	v_lshlrev_b32_e32 v100, 16, v96
	v_and_b32_e32 v101, 0xffff0000, v96
	v_lshlrev_b32_e32 v96, 16, v97
	v_and_b32_e32 v97, 0xffff0000, v97
	v_pk_fma_f32 v[80:81], v[100:101], s[8:9], v[80:81] op_sel_hi:[1,0,1]
	v_pk_fma_f32 v[82:83], v[96:97], s[8:9], v[82:83] op_sel_hi:[1,0,1]
	v_cvt_pk_bf16_f32 v80, v80, v81
	v_cvt_pk_bf16_f32 v81, v82, v83
	s_waitcnt vmcnt(0)
;     ...
;         for (int mi = 0; mi < 2; ++mi) {
;           const size_t m = (size_t)mt * 256 + wm * 64 + mi * 32 + r;
; #pragma unroll
;           for (int ni = 0; ni < 4; ++ni) {
;             __builtin_amdgcn_sched_barrier(0);
;             if (MODE == 0) {
; #pragma unroll
;               for (int gp = 0; gp < 2; ++gp) {
;                 const int g0 = 2 * gp;
;                 uint2 pa, pb;
;                 pa.x = pack2(acc[mi][ni][4 * g0], acc[mi][ni][4 * g0 + 1]); pa.y = pack2(acc[mi][ni][4 * g0 + 2], acc[mi][ni][4 * g0 + 3]);
;                 pb.x = pack2(acc[mi][ni][4 * g0 + 4], acc[mi][ni][4 * g0 + 5]); pb.y = pack2(acc[mi][ni][4 * g0 + 6], acc[mi][ni][4 * g0 + 7]);
;                 { auto rx = __builtin_amdgcn_permlane32_swap(pa.x, pb.x, false, false); pa.x = rx[0]; pb.x = rx[1]; }
;                 { auto ry = __builtin_amdgcn_permlane32_swap(pa.y, pb.y, false, false); pa.y = ry[0]; pb.y = ry[1]; }
;                 const int col = nt * 256 + wn * 128 + ni * 32 + 8 * g0 + 8 * hh;
;                 const uint4 v4 = make_uint4(pa.x, pa.y, pb.x, pb.y);
;                 if (outp != nullptr && nt >= 32) *(uint4*)(outp + m * 2048 + (col - 8192)) = v4;
;                 else if (col < nvalid) *(uint4*)(C + m * ldc + col) = v4;
;               }
;             } else if (MODE == 1) {
; #pragma unroll
;               for (int gp = 0; gp < 2; ++gp) {
;                 const int g0 = 2 * gp;
;                 const int nb_ = nt * 256 + wn * 128 + ni * 32 + 8 * g0;
;                 const uint2 ra = *(const uint2*)(res + m * 1024 + nb_ + 4 * hh), rb = *(const uint2*)(res + m * 1024 + nb_ + 8 + 4 * hh);
;                 uint2 pa, pb;
;                 pa.x = pack2(alpha * lo2f(ra.x) + acc[mi][ni][4 * g0], alpha * hi2f(ra.x) + acc[mi][ni][4 * g0 + 1]);
;                 pa.y = pack2(alpha * lo2f(ra.y) + acc[mi][ni][4 * g0 + 2], alpha * hi2f(ra.y) + acc[mi][ni][4 * g0 + 3]);
;                 pb.x = pack2(alpha * lo2f(rb.x) + acc[mi][ni][4 * g0 + 4], alpha * hi2f(rb.x) + acc[mi][ni][4 * g0 + 5]);
;                 pb.y = pack2(alpha * lo2f(rb.y) + acc[mi][ni][4 * g0 + 6], alpha * hi2f(rb.y) + acc[mi][ni][4 * g0 + 7]);
;                 { auto rx = __builtin_amdgcn_permlane32_swap(pa.x, pb.x, false, false); pa.x = rx[0]; pb.x = rx[1]; }
;                 { auto ry = __builtin_amdgcn_permlane32_swap(pa.y, pb.y, false, false); pa.y = ry[0]; pb.y = ry[1]; }
	v_lshlrev_b32_e32 v82, 16, v98
	v_and_b32_e32 v83, 0xffff0000, v98
	v_pk_fma_f32 v[82:83], v[82:83], s[8:9], v[84:85] op_sel_hi:[1,0,1]
	v_lshlrev_b32_e32 v84, 16, v99
	v_and_b32_e32 v85, 0xffff0000, v99
	v_pk_fma_f32 v[84:85], v[84:85], s[8:9], v[86:87] op_sel_hi:[1,0,1]
	v_cvt_pk_bf16_f32 v82, v82, v83
	v_cvt_pk_bf16_f32 v83, v84, v85
	s_nop 0
	v_permlane32_swap_b32_e32 v80, v82
	v_permlane32_swap_b32_e32 v81, v83
	global_store_dwordx4 v[112:113], v[80:83], off offset:128
	global_load_dwordx2 v[80:81], v[138:139], off offset:160
	s_nop 0
	global_load_dwordx2 v[82:83], v[138:139], off offset:176
	s_waitcnt vmcnt(1)
	v_lshlrev_b32_e32 v84, 16, v80
	v_and_b32_e32 v85, 0xffff0000, v80
	v_pk_fma_f32 v[84:85], v[84:85], s[8:9], v[88:89] op_sel_hi:[1,0,1]
	s_nop 0
	v_cvt_pk_bf16_f32 v80, v84, v85
	v_lshlrev_b32_e32 v84, 16, v81
	v_and_b32_e32 v85, 0xffff0000, v81
	v_pk_fma_f32 v[84:85], v[84:85], s[8:9], v[90:91] op_sel_hi:[1,0,1]
	s_nop 0
	v_cvt_pk_bf16_f32 v81, v84, v85
	s_waitcnt vmcnt(0)
	v_lshlrev_b32_e32 v84, 16, v82
	v_and_b32_e32 v85, 0xffff0000, v82
	v_pk_fma_f32 v[84:85], v[84:85], s[8:9], v[92:93] op_sel_hi:[1,0,1]
	s_nop 0
	v_cvt_pk_bf16_f32 v82, v84, v85
	v_lshlrev_b32_e32 v84, 16, v83
	v_and_b32_e32 v85, 0xffff0000, v83
	v_pk_fma_f32 v[84:85], v[84:85], s[8:9], v[94:95] op_sel_hi:[1,0,1]
	v_permlane32_swap_b32_e32 v80, v82
	v_cvt_pk_bf16_f32 v83, v84, v85
	s_nop 1
	v_permlane32_swap_b32_e32 v81, v83
	global_store_dwordx4 v[112:113], v[80:83], off offset:160
	global_load_dwordx2 v[80:81], v[138:139], off offset:192
	s_nop 0
	global_load_dwordx2 v[82:83], v[138:139], off offset:208
	v_or_b32_e32 v136, 0x10000, v136
	s_waitcnt vmcnt(1)
	v_lshlrev_b32_e32 v84, 16, v80
	v_and_b32_e32 v85, 0xffff0000, v80
	v_lshlrev_b32_e32 v80, 16, v81
	v_and_b32_e32 v81, 0xffff0000, v81
	v_pk_fma_f32 v[64:65], v[84:85], s[8:9], v[64:65] op_sel_hi:[1,0,1]
	v_pk_fma_f32 v[66:67], v[80:81], s[8:9], v[66:67] op_sel_hi:[1,0,1]
	v_cvt_pk_bf16_f32 v64, v64, v65
	v_cvt_pk_bf16_f32 v65, v66, v67
	s_waitcnt vmcnt(0)
	v_lshlrev_b32_e32 v66, 16, v82
	v_and_b32_e32 v67, 0xffff0000, v82
	v_pk_fma_f32 v[66:67], v[66:67], s[8:9], v[68:69] op_sel_hi:[1,0,1]
	v_lshlrev_b32_e32 v68, 16, v83
	v_and_b32_e32 v69, 0xffff0000, v83
	v_pk_fma_f32 v[68:69], v[68:69], s[8:9], v[70:71] op_sel_hi:[1,0,1]
	v_cvt_pk_bf16_f32 v66, v66, v67
	v_cvt_pk_bf16_f32 v67, v68, v69
	s_nop 0
	v_permlane32_swap_b32_e32 v64, v66
	v_permlane32_swap_b32_e32 v65, v67
	global_store_dwordx4 v[112:113], v[64:67], off offset:192
	global_load_dwordx2 v[64:65], v[138:139], off offset:224
	s_nop 0
	global_load_dwordx2 v[66:67], v[138:139], off offset:240
	v_lshl_add_u64 v[70:71], v[132:133], 0, v[136:137]
	s_waitcnt vmcnt(1)
	v_lshlrev_b32_e32 v68, 16, v64
	v_and_b32_e32 v69, 0xffff0000, v64
	v_pk_fma_f32 v[68:69], v[68:69], s[8:9], v[72:73] op_sel_hi:[1,0,1]
	s_nop 0
	v_cvt_pk_bf16_f32 v64, v68, v69
	v_lshlrev_b32_e32 v68, 16, v65
	v_and_b32_e32 v69, 0xffff0000, v65
	v_pk_fma_f32 v[68:69], v[68:69], s[8:9], v[74:75] op_sel_hi:[1,0,1]
	s_nop 0
	v_cvt_pk_bf16_f32 v65, v68, v69
	s_waitcnt vmcnt(0)
	v_lshlrev_b32_e32 v68, 16, v66
	v_and_b32_e32 v69, 0xffff0000, v66
	v_pk_fma_f32 v[68:69], v[68:69], s[8:9], v[76:77] op_sel_hi:[1,0,1]
	s_nop 0
	v_cvt_pk_bf16_f32 v66, v68, v69
	v_lshlrev_b32_e32 v68, 16, v67
	v_and_b32_e32 v69, 0xffff0000, v67
	v_pk_fma_f32 v[68:69], v[68:69], s[8:9], v[78:79] op_sel_hi:[1,0,1]
	v_permlane32_swap_b32_e32 v64, v66
	v_cvt_pk_bf16_f32 v67, v68, v69
	s_nop 1
	v_permlane32_swap_b32_e32 v65, v67
	global_store_dwordx4 v[112:113], v[64:67], off offset:224
	s_nop 1
	v_lshl_add_u64 v[64:65], s[40:41], 0, v[136:137]
	v_lshl_add_u64 v[64:65], v[64:65], 0, v[134:135]
	v_lshl_add_u64 v[64:65], v[64:65], 0, v[128:129]
	global_load_dwordx2 v[66:67], v[64:65], off
	global_load_dwordx2 v[68:69], v[64:65], off offset:16
	s_waitcnt vmcnt(1)
	v_lshlrev_b32_e32 v72, 16, v66
	v_and_b32_e32 v73, 0xffff0000, v66
	v_pk_fma_f32 v[48:49], v[72:73], s[8:9], v[48:49] op_sel_hi:[1,0,1]
	s_nop 0
	v_cvt_pk_bf16_f32 v66, v48, v49
	v_lshlrev_b32_e32 v48, 16, v67
	v_and_b32_e32 v49, 0xffff0000, v67
	v_pk_fma_f32 v[48:49], v[48:49], s[8:9], v[50:51] op_sel_hi:[1,0,1]
	s_nop 0
	v_cvt_pk_bf16_f32 v67, v48, v49
	s_waitcnt vmcnt(0)
	v_lshlrev_b32_e32 v48, 16, v68
	v_and_b32_e32 v49, 0xffff0000, v68
	v_pk_fma_f32 v[48:49], v[48:49], s[8:9], v[52:53] op_sel_hi:[1,0,1]
	s_nop 0
	v_cvt_pk_bf16_f32 v68, v48, v49
	v_lshlrev_b32_e32 v48, 16, v69
	v_and_b32_e32 v49, 0xffff0000, v69
	v_pk_fma_f32 v[48:49], v[48:49], s[8:9], v[54:55] op_sel_hi:[1,0,1]
	v_permlane32_swap_b32_e32 v66, v68
	v_cvt_pk_bf16_f32 v69, v48, v49
	s_nop 1
	v_permlane32_swap_b32_e32 v67, v69
	v_lshl_add_u64 v[48:49], v[70:71], 0, v[134:135]
	global_store_dwordx4 v[48:49], v[66:69], off
	global_load_dwordx2 v[50:51], v[64:65], off offset:32
	global_load_dwordx2 v[52:53], v[64:65], off offset:48
	s_waitcnt vmcnt(1)
	v_lshlrev_b32_e32 v54, 16, v50
	v_and_b32_e32 v55, 0xffff0000, v50
	v_pk_fma_f32 v[54:55], v[54:55], s[8:9], v[56:57] op_sel_hi:[1,0,1]
	s_nop 0
	v_cvt_pk_bf16_f32 v50, v54, v55
	v_lshlrev_b32_e32 v54, 16, v51
	v_and_b32_e32 v55, 0xffff0000, v51
	v_pk_fma_f32 v[54:55], v[54:55], s[8:9], v[58:59] op_sel_hi:[1,0,1]
	s_nop 0
	v_cvt_pk_bf16_f32 v51, v54, v55
	s_waitcnt vmcnt(0)
	v_lshlrev_b32_e32 v54, 16, v52
	v_and_b32_e32 v55, 0xffff0000, v52
	v_pk_fma_f32 v[54:55], v[54:55], s[8:9], v[60:61] op_sel_hi:[1,0,1]
	s_nop 0
	v_cvt_pk_bf16_f32 v52, v54, v55
	v_lshlrev_b32_e32 v54, 16, v53
	v_and_b32_e32 v55, 0xffff0000, v53
	v_pk_fma_f32 v[54:55], v[54:55], s[8:9], v[62:63] op_sel_hi:[1,0,1]
	v_permlane32_swap_b32_e32 v50, v52
	v_cvt_pk_bf16_f32 v53, v54, v55
	s_nop 1
	v_permlane32_swap_b32_e32 v51, v53
	global_store_dwordx4 v[48:49], v[50:53], off offset:32
	global_load_dwordx2 v[50:51], v[64:65], off offset:64
	s_nop 0
	global_load_dwordx2 v[52:53], v[64:65], off offset:80
	s_waitcnt vmcnt(1)
;     ...
;         for (int mi = 0; mi < 2; ++mi) {
;           const size_t m = (size_t)mt * 256 + wm * 64 + mi * 32 + r;
; #pragma unroll
;           for (int ni = 0; ni < 4; ++ni) {
;             __builtin_amdgcn_sched_barrier(0);
;             if (MODE == 0) {
; #pragma unroll
;               for (int gp = 0; gp < 2; ++gp) {
;                 const int g0 = 2 * gp;
;                 uint2 pa, pb;
;                 pa.x = pack2(acc[mi][ni][4 * g0], acc[mi][ni][4 * g0 + 1]); pa.y = pack2(acc[mi][ni][4 * g0 + 2], acc[mi][ni][4 * g0 + 3]);
;                 pb.x = pack2(acc[mi][ni][4 * g0 + 4], acc[mi][ni][4 * g0 + 5]); pb.y = pack2(acc[mi][ni][4 * g0 + 6], acc[mi][ni][4 * g0 + 7]);
;                 { auto rx = __builtin_amdgcn_permlane32_swap(pa.x, pb.x, false, false); pa.x = rx[0]; pb.x = rx[1]; }
;                 { auto ry = __builtin_amdgcn_permlane32_swap(pa.y, pb.y, false, false); pa.y = ry[0]; pb.y = ry[1]; }
;                 const int col = nt * 256 + wn * 128 + ni * 32 + 8 * g0 + 8 * hh;
;                 const uint4 v4 = make_uint4(pa.x, pa.y, pb.x, pb.y);
;                 if (outp != nullptr && nt >= 32) *(uint4*)(outp + m * 2048 + (col - 8192)) = v4;
;                 else if (col < nvalid) *(uint4*)(C + m * ldc + col) = v4;
;               }
;             } else if (MODE == 1) {
; #pragma unroll
;               for (int gp = 0; gp < 2; ++gp) {
;                 const int g0 = 2 * gp;
;                 const int nb_ = nt * 256 + wn * 128 + ni * 32 + 8 * g0;
;                 const uint2 ra = *(const uint2*)(res + m * 1024 + nb_ + 4 * hh), rb = *(const uint2*)(res + m * 1024 + nb_ + 8 + 4 * hh);
;                 uint2 pa, pb;
;                 pa.x = pack2(alpha * lo2f(ra.x) + acc[mi][ni][4 * g0], alpha * hi2f(ra.x) + acc[mi][ni][4 * g0 + 1]);
;                 pa.y = pack2(alpha * lo2f(ra.y) + acc[mi][ni][4 * g0 + 2], alpha * hi2f(ra.y) + acc[mi][ni][4 * g0 + 3]);
;                 pb.x = pack2(alpha * lo2f(rb.x) + acc[mi][ni][4 * g0 + 4], alpha * hi2f(rb.x) + acc[mi][ni][4 * g0 + 5]);
;                 pb.y = pack2(alpha * lo2f(rb.y) + acc[mi][ni][4 * g0 + 6], alpha * hi2f(rb.y) + acc[mi][ni][4 * g0 + 7]);
;                 { auto rx = __builtin_amdgcn_permlane32_swap(pa.x, pb.x, false, false); pa.x = rx[0]; pb.x = rx[1]; }
;                 { auto ry = __builtin_amdgcn_permlane32_swap(pa.y, pb.y, false, false); pa.y = ry[0]; pb.y = ry[1]; }
	v_lshlrev_b32_e32 v54, 16, v50
	v_and_b32_e32 v55, 0xffff0000, v50
	v_lshlrev_b32_e32 v50, 16, v51
	v_and_b32_e32 v51, 0xffff0000, v51
	v_pk_fma_f32 v[32:33], v[54:55], s[8:9], v[32:33] op_sel_hi:[1,0,1]
	v_pk_fma_f32 v[34:35], v[50:51], s[8:9], v[34:35] op_sel_hi:[1,0,1]
	v_cvt_pk_bf16_f32 v32, v32, v33
	v_cvt_pk_bf16_f32 v33, v34, v35
	s_waitcnt vmcnt(0)
	v_lshlrev_b32_e32 v34, 16, v52
	v_and_b32_e32 v35, 0xffff0000, v52
	v_pk_fma_f32 v[34:35], v[34:35], s[8:9], v[36:37] op_sel_hi:[1,0,1]
	v_lshlrev_b32_e32 v36, 16, v53
	v_and_b32_e32 v37, 0xffff0000, v53
	v_pk_fma_f32 v[36:37], v[36:37], s[8:9], v[38:39] op_sel_hi:[1,0,1]
	v_cvt_pk_bf16_f32 v34, v34, v35
	v_cvt_pk_bf16_f32 v35, v36, v37
	s_nop 0
	v_permlane32_swap_b32_e32 v32, v34
	v_permlane32_swap_b32_e32 v33, v35
	global_store_dwordx4 v[48:49], v[32:35], off offset:64
	global_load_dwordx2 v[32:33], v[64:65], off offset:96
	s_nop 0
	global_load_dwordx2 v[34:35], v[64:65], off offset:112
	s_waitcnt vmcnt(1)
	v_lshlrev_b32_e32 v36, 16, v32
	v_and_b32_e32 v37, 0xffff0000, v32
	v_pk_fma_f32 v[36:37], v[36:37], s[8:9], v[40:41] op_sel_hi:[1,0,1]
	s_nop 0
	v_cvt_pk_bf16_f32 v32, v36, v37
	v_lshlrev_b32_e32 v36, 16, v33
	v_and_b32_e32 v37, 0xffff0000, v33
	v_pk_fma_f32 v[36:37], v[36:37], s[8:9], v[42:43] op_sel_hi:[1,0,1]
	s_nop 0
	v_cvt_pk_bf16_f32 v33, v36, v37
	s_waitcnt vmcnt(0)
	v_lshlrev_b32_e32 v36, 16, v34
	v_and_b32_e32 v37, 0xffff0000, v34
	v_pk_fma_f32 v[36:37], v[36:37], s[8:9], v[44:45] op_sel_hi:[1,0,1]
	s_nop 0
	v_cvt_pk_bf16_f32 v34, v36, v37
	v_lshlrev_b32_e32 v36, 16, v35
	v_and_b32_e32 v37, 0xffff0000, v35
	v_pk_fma_f32 v[36:37], v[36:37], s[8:9], v[46:47] op_sel_hi:[1,0,1]
	v_permlane32_swap_b32_e32 v32, v34
	v_cvt_pk_bf16_f32 v35, v36, v37
	s_nop 1
	v_permlane32_swap_b32_e32 v33, v35
	global_store_dwordx4 v[48:49], v[32:35], off offset:96
	global_load_dwordx2 v[32:33], v[64:65], off offset:128
	s_nop 0
	global_load_dwordx2 v[34:35], v[64:65], off offset:144
	s_waitcnt vmcnt(1)
	v_lshlrev_b32_e32 v36, 16, v32
	v_and_b32_e32 v37, 0xffff0000, v32
	v_lshlrev_b32_e32 v32, 16, v33
	v_and_b32_e32 v33, 0xffff0000, v33
	v_pk_fma_f32 v[16:17], v[36:37], s[8:9], v[16:17] op_sel_hi:[1,0,1]
	v_pk_fma_f32 v[18:19], v[32:33], s[8:9], v[18:19] op_sel_hi:[1,0,1]
	v_cvt_pk_bf16_f32 v16, v16, v17
	v_cvt_pk_bf16_f32 v17, v18, v19
	s_waitcnt vmcnt(0)
	v_lshlrev_b32_e32 v18, 16, v34
	v_and_b32_e32 v19, 0xffff0000, v34
	v_pk_fma_f32 v[18:19], v[18:19], s[8:9], v[20:21] op_sel_hi:[1,0,1]
	v_lshlrev_b32_e32 v20, 16, v35
	v_and_b32_e32 v21, 0xffff0000, v35
	v_pk_fma_f32 v[20:21], v[20:21], s[8:9], v[22:23] op_sel_hi:[1,0,1]
	v_cvt_pk_bf16_f32 v18, v18, v19
	v_cvt_pk_bf16_f32 v19, v20, v21
	s_nop 0
	v_permlane32_swap_b32_e32 v16, v18
	v_permlane32_swap_b32_e32 v17, v19
	global_store_dwordx4 v[48:49], v[16:19], off offset:128
	global_load_dwordx2 v[16:17], v[64:65], off offset:160
	s_nop 0
	global_load_dwordx2 v[18:19], v[64:65], off offset:176
	s_waitcnt vmcnt(1)
	v_lshlrev_b32_e32 v20, 16, v16
	v_and_b32_e32 v21, 0xffff0000, v16
	v_pk_fma_f32 v[20:21], v[20:21], s[8:9], v[24:25] op_sel_hi:[1,0,1]
	s_nop 0
	v_cvt_pk_bf16_f32 v16, v20, v21
	v_lshlrev_b32_e32 v20, 16, v17
	v_and_b32_e32 v21, 0xffff0000, v17
	v_pk_fma_f32 v[20:21], v[20:21], s[8:9], v[26:27] op_sel_hi:[1,0,1]
	s_nop 0
	v_cvt_pk_bf16_f32 v17, v20, v21
	s_waitcnt vmcnt(0)
	v_lshlrev_b32_e32 v20, 16, v18
	v_and_b32_e32 v21, 0xffff0000, v18
	v_pk_fma_f32 v[20:21], v[20:21], s[8:9], v[28:29] op_sel_hi:[1,0,1]
	s_nop 0
	v_cvt_pk_bf16_f32 v18, v20, v21
	v_lshlrev_b32_e32 v20, 16, v19
	v_and_b32_e32 v21, 0xffff0000, v19
	v_pk_fma_f32 v[20:21], v[20:21], s[8:9], v[30:31] op_sel_hi:[1,0,1]
	v_permlane32_swap_b32_e32 v16, v18
	v_cvt_pk_bf16_f32 v19, v20, v21
	s_nop 1
	v_permlane32_swap_b32_e32 v17, v19
	global_store_dwordx4 v[48:49], v[16:19], off offset:160
	global_load_dwordx2 v[16:17], v[64:65], off offset:192
	s_nop 0
	global_load_dwordx2 v[18:19], v[64:65], off offset:208
	s_waitcnt vmcnt(1)
	v_lshlrev_b32_e32 v20, 16, v16
	v_and_b32_e32 v21, 0xffff0000, v16
	v_lshlrev_b32_e32 v16, 16, v17
	v_and_b32_e32 v17, 0xffff0000, v17
	v_pk_fma_f32 v[0:1], v[20:21], s[8:9], v[0:1] op_sel_hi:[1,0,1]
	v_pk_fma_f32 v[2:3], v[16:17], s[8:9], v[2:3] op_sel_hi:[1,0,1]
	v_cvt_pk_bf16_f32 v0, v0, v1
	v_cvt_pk_bf16_f32 v1, v2, v3
	s_waitcnt vmcnt(0)
	v_lshlrev_b32_e32 v2, 16, v18
	v_and_b32_e32 v3, 0xffff0000, v18
	v_pk_fma_f32 v[2:3], v[2:3], s[8:9], v[4:5] op_sel_hi:[1,0,1]
	v_lshlrev_b32_e32 v4, 16, v19
	v_and_b32_e32 v5, 0xffff0000, v19
	v_pk_fma_f32 v[4:5], v[4:5], s[8:9], v[6:7] op_sel_hi:[1,0,1]
	v_cvt_pk_bf16_f32 v2, v2, v3
	v_cvt_pk_bf16_f32 v3, v4, v5
	s_nop 0
	v_permlane32_swap_b32_e32 v0, v2
	v_permlane32_swap_b32_e32 v1, v3
	global_store_dwordx4 v[48:49], v[0:3], off offset:192
	global_load_dwordx2 v[0:1], v[64:65], off offset:224
	s_nop 0
	global_load_dwordx2 v[2:3], v[64:65], off offset:240
	s_waitcnt vmcnt(1)
	v_lshlrev_b32_e32 v4, 16, v0
	v_and_b32_e32 v5, 0xffff0000, v0
	v_pk_fma_f32 v[4:5], v[4:5], s[8:9], v[8:9] op_sel_hi:[1,0,1]
	s_nop 0
	v_cvt_pk_bf16_f32 v0, v4, v5
	v_lshlrev_b32_e32 v4, 16, v1
	v_and_b32_e32 v5, 0xffff0000, v1
	v_pk_fma_f32 v[4:5], v[4:5], s[8:9], v[10:11] op_sel_hi:[1,0,1]
	s_nop 0
	v_cvt_pk_bf16_f32 v1, v4, v5
	s_waitcnt vmcnt(0)
	v_lshlrev_b32_e32 v4, 16, v2
	v_and_b32_e32 v5, 0xffff0000, v2
	v_pk_fma_f32 v[4:5], v[4:5], s[8:9], v[12:13] op_sel_hi:[1,0,1]
	s_nop 0
	v_cvt_pk_bf16_f32 v2, v4, v5
	v_lshlrev_b32_e32 v4, 16, v3
	v_and_b32_e32 v5, 0xffff0000, v3
	v_pk_fma_f32 v[4:5], v[4:5], s[8:9], v[14:15] op_sel_hi:[1,0,1]
	v_permlane32_swap_b32_e32 v0, v2
	v_cvt_pk_bf16_f32 v3, v4, v5
	s_nop 1
	v_permlane32_swap_b32_e32 v1, v3
	global_store_dwordx4 v[48:49], v[0:3], off offset:224
	s_waitcnt lgkmcnt(0)
	s_barrier
	s_waitcnt vmcnt(0)
	s_barrier

; #define MFMA(a, b, c) __builtin_amdgcn_mfma_f32_32x32x16_bf16((a), (b), (c), 0, 0, 0)
; DI f32x16 zero16() { f32x16 z; for (int i = 0; i < 16; ++i) z[i] = 0.f; return z; }
;     ...
;   const int fP = r * 128, fsw = (r >> 1) & 7;
;   const int fA = wm * 8192 + fP, fB = 32768 + wn * 16384 + fP;
;   f32x16 acc[2][4];
; #pragma unroll
;   for (int i = 0; i < 2; ++i)
; #pragma unroll
;     for (int j = 0; j < 4; ++j) acc[i][j] = zero16();
;   __syncthreads();
;   G_DMA(0, 0);
;   asm volatile("s_waitcnt vmcnt(0)" ::: "memory");
;   asm volatile("s_waitcnt lgkmcnt(0)" ::: "memory"); __builtin_amdgcn_s_barrier(); asm volatile("" ::: "memory");
;   int cur = 0;
;   for (int s = 0; s < S; ++s) {
;     G_DMA(s + 1, cur ^ BUFB);
;     {
;       const char* Ab = smem + cur + fA;
;       const char* Bb = smem + cur + fB;
;       __builtin_amdgcn_sched_barrier(0);
; #pragma unroll
;       for (int kk = 0; kk < 4; ++kk) {
;         const int ko = (((kk * 2 + hh) ^ fsw) << 4);
;         bf16x8 af[2], wf[4];
;         af[0] = *(const bf16x8*)(Ab + ko); af[1] = *(const bf16x8*)(Ab + 4096 + ko);
; #pragma unroll
;         for (int ni = 0; ni < 4; ++ni) wf[ni] = *(const bf16x8*)(Bb + ni * 4096 + ko);
; #pragma unroll
;         for (int mi = 0; mi < 2; ++mi)
; #pragma unroll
;           for (int ni = 0; ni < 4; ++ni) acc[mi][ni] = MFMA(wf[ni], af[mi], acc[mi][ni]);
;         if (kk == 1) __builtin_amdgcn_sched_barrier(0);
;       }
;       __builtin_amdgcn_sched_barrier(0);
;     }
;     asm volatile("s_waitcnt vmcnt(0)" ::: "memory");
;     if ((s & (nk - 1)) == nk - 1) {
.LBB0_1293:
	v_add3_u32 v187, s23, v131, v138
	v_add3_u32 v208, s23, v139, v138
	v_add_u32_e32 v182, v208, v142
	v_add_u32_e32 v183, v187, v142
	ds_read_b128 v[192:195], v182 offset:32768
	ds_read_b128 v[216:219], v183
	ds_read_b128 v[196:199], v182 offset:36864
	ds_read_b128 v[200:203], v182 offset:40960
	ds_read_b128 v[204:207], v182 offset:45056
	ds_read_b128 v[220:223], v183 offset:4096
	v_add_u32_e32 v184, v208, v143
	v_add_u32_e32 v185, v187, v143
	ds_read_b128 v[224:227], v184 offset:32768
	ds_read_b128 v[240:243], v185
	ds_read_b128 v[228:231], v184 offset:36864
	ds_read_b128 v[232:235], v184 offset:40960
	ds_read_b128 v[236:239], v184 offset:45056
	ds_read_b128 v[244:247], v185 offset:4096
	s_add_i32 s44, s8, 1
	s_mov_b32 s9, s23
	s_cmp_lt_u32 s44, s46
	v_readlane_b32 s23, v252, 57
	s_cselect_b32 s23, s44, s23
	s_lshl_b32 s24, s23, 1
	s_andn2_b32 s24, s24, 31
	s_add_i32 s24, s24, s33
	s_lshr_b32 s24, s24, 3
	s_and_b32 s25, s24, 4
	s_or_b32 s25, s25, s47
	s_and_b32 s24, s24, 0xfffff8
	s_or_b32 s28, s24, s74
	s_lshl_b32 s24, s25, 19
	s_add_u32 s24, s7, s24
	s_addc_u32 s25, s22, 0
	s_lshl_b32 s23, s23, 7
	s_and_b32 s45, s23, 0x780
	s_add_u32 s24, s24, s45
	s_addc_u32 s25, s25, 0
	s_lshl_b32 s40, s28, 8
	s_ashr_i32 s41, s40, 31
	s_lshl_b64 s[40:41], s[40:41], 11
	s_add_u32 s28, s72, s40
	s_addc_u32 s40, s73, s41
	s_xor_b32 s23, s9, 0x10000
	v_add_u32_e32 v128, s23, v140
	v_lshl_add_u64 v[136:137], s[24:25], 0, v[132:133]
	v_readfirstlane_b32 s24, v128
	v_add_u32_e32 v148, 0x2000, v128
	s_mov_b32 m0, s24
	s_mov_b64 s[48:49], 0x20000
	v_readfirstlane_b32 s24, v148
	v_add_u32_e32 v148, 0x4000, v128
	global_load_lds_dwordx4 v[136:137], off
	s_add_i32 s9, s9, 0
	s_waitcnt lgkmcnt(10)
	v_mfma_f32_32x32x16_bf16 v[112:127], v[192:195], v[216:219], v[112:127]
	s_waitcnt lgkmcnt(9)
	v_mfma_f32_32x32x16_bf16 v[96:111], v[196:199], v[216:219], v[96:111]
	v_lshl_add_u64 v[146:147], v[136:137], 0, s[48:49]
	s_mov_b32 m0, s24
	s_mov_b64 s[50:51], 0x40000
	v_readfirstlane_b32 s24, v148
	global_load_lds_dwordx4 v[146:147], off
	s_waitcnt lgkmcnt(8)
	v_mfma_f32_32x32x16_bf16 v[80:95], v[200:203], v[216:219], v[80:95]
	s_waitcnt lgkmcnt(7)
	v_mfma_f32_32x32x16_bf16 v[64:79], v[204:207], v[216:219], v[64:79]
	v_lshl_add_u64 v[146:147], v[136:137], 0, s[50:51]
	s_mov_b32 m0, s24
	s_mov_b64 s[52:53], 0x60000
	global_load_lds_dwordx4 v[146:147], off
	s_waitcnt lgkmcnt(6)
	v_mfma_f32_32x32x16_bf16 v[48:63], v[192:195], v[220:223], v[48:63]
	v_mfma_f32_32x32x16_bf16 v[32:47], v[196:199], v[220:223], v[32:47]
	v_add_u32_e32 v146, 0x6000, v128
	v_lshl_add_u64 v[136:137], v[136:137], 0, s[52:53]
	v_readfirstlane_b32 s24, v146
	s_mov_b32 m0, s24
	s_add_u32 s24, s28, s45
	s_addc_u32 s25, s40, 0
	v_add_u32_e32 v146, 0x8000, v128
	global_load_lds_dwordx4 v[136:137], off
	v_mfma_f32_32x32x16_bf16 v[16:31], v[200:203], v[220:223], v[16:31]
	v_mfma_f32_32x32x16_bf16 v[0:15], v[204:207], v[220:223], v[0:15]
	v_lshl_add_u64 v[136:137], s[24:25], 0, v[132:133]
	v_readfirstlane_b32 s24, v146
	v_add_u32_e32 v148, 0xa000, v128
	s_mov_b32 m0, s24
	v_readfirstlane_b32 s24, v148
	v_add_u32_e32 v148, 0xc000, v128
	global_load_lds_dwordx4 v[136:137], off
	v_add_u32_e32 v182, v208, v144
	v_add_u32_e32 v183, v187, v144
	ds_read_b128 v[192:195], v182 offset:32768
	ds_read_b128 v[216:219], v183
	ds_read_b128 v[196:199], v182 offset:36864
	ds_read_b128 v[200:203], v182 offset:40960
	ds_read_b128 v[204:207], v182 offset:45056
	ds_read_b128 v[220:223], v183 offset:4096
	s_waitcnt lgkmcnt(10)
	v_mfma_f32_32x32x16_bf16 v[112:127], v[224:227], v[240:243], v[112:127]
	s_waitcnt lgkmcnt(9)
	v_mfma_f32_32x32x16_bf16 v[96:111], v[228:231], v[240:243], v[96:111]
	v_lshl_add_u64 v[146:147], v[136:137], 0, s[48:49]
	s_mov_b32 m0, s24
	v_readfirstlane_b32 s24, v148
	v_add_u32_e32 v128, 0xe000, v128
	global_load_lds_dwordx4 v[146:147], off
	s_waitcnt lgkmcnt(8)
	v_mfma_f32_32x32x16_bf16 v[80:95], v[232:235], v[240:243], v[80:95]
	s_waitcnt lgkmcnt(7)
	v_mfma_f32_32x32x16_bf16 v[64:79], v[236:239], v[240:243], v[64:79]
	v_lshl_add_u64 v[146:147], v[136:137], 0, s[50:51]
	s_mov_b32 m0, s24
	v_readfirstlane_b32 s24, v128
	global_load_lds_dwordx4 v[146:147], off
	s_waitcnt lgkmcnt(6)
	v_mfma_f32_32x32x16_bf16 v[48:63], v[224:227], v[244:247], v[48:63]
	v_mfma_f32_32x32x16_bf16 v[32:47], v[228:231], v[244:247], v[32:47]
	v_lshl_add_u64 v[136:137], v[136:137], 0, s[52:53]
	s_mov_b32 m0, s24
	s_mov_b64 s[48:49], 0x40000
	global_load_lds_dwordx4 v[136:137], off
	v_mfma_f32_32x32x16_bf16 v[16:31], v[232:235], v[244:247], v[16:31]
	v_mfma_f32_32x32x16_bf16 v[0:15], v[236:239], v[244:247], v[0:15]
	v_add_u32_e32 v184, v208, v145
	v_add_u32_e32 v185, v187, v145
	ds_read_b128 v[224:227], v184 offset:32768
	ds_read_b128 v[240:243], v185
	ds_read_b128 v[228:231], v184 offset:36864
	ds_read_b128 v[232:235], v184 offset:40960
	ds_read_b128 v[236:239], v184 offset:45056
	ds_read_b128 v[244:247], v185 offset:4096
	s_waitcnt lgkmcnt(10)
	v_mfma_f32_32x32x16_bf16 v[112:127], v[192:195], v[216:219], v[112:127]
	s_waitcnt lgkmcnt(9)
	v_mfma_f32_32x32x16_bf16 v[96:111], v[196:199], v[216:219], v[96:111]
	s_waitcnt lgkmcnt(8)
	v_mfma_f32_32x32x16_bf16 v[80:95], v[200:203], v[216:219], v[80:95]
	s_waitcnt lgkmcnt(7)
	v_mfma_f32_32x32x16_bf16 v[64:79], v[204:207], v[216:219], v[64:79]
	s_waitcnt lgkmcnt(6)
	v_mfma_f32_32x32x16_bf16 v[48:63], v[192:195], v[220:223], v[48:63]
	v_mfma_f32_32x32x16_bf16 v[32:47], v[196:199], v[220:223], v[32:47]
	v_mfma_f32_32x32x16_bf16 v[16:31], v[200:203], v[220:223], v[16:31]
	v_mfma_f32_32x32x16_bf16 v[0:15], v[204:207], v[220:223], v[0:15]
	s_waitcnt lgkmcnt(4)
	v_mfma_f32_32x32x16_bf16 v[112:127], v[224:227], v[240:243], v[112:127]
	s_waitcnt lgkmcnt(3)
	v_mfma_f32_32x32x16_bf16 v[96:111], v[228:231], v[240:243], v[96:111]
	s_waitcnt lgkmcnt(2)
	v_mfma_f32_32x32x16_bf16 v[80:95], v[232:235], v[240:243], v[80:95]
	s_waitcnt lgkmcnt(1)
	v_mfma_f32_32x32x16_bf16 v[64:79], v[236:239], v[240:243], v[64:79]
	s_waitcnt lgkmcnt(0)
	v_mfma_f32_32x32x16_bf16 v[48:63], v[224:227], v[244:247], v[48:63]
	v_mfma_f32_32x32x16_bf16 v[32:47], v[228:231], v[244:247], v[32:47]
	v_mfma_f32_32x32x16_bf16 v[16:31], v[232:235], v[244:247], v[16:31]
	v_mfma_f32_32x32x16_bf16 v[0:15], v[236:239], v[244:247], v[0:15]
	s_waitcnt vmcnt(0)
	s_and_b32 s9, s8, 15
	s_cmp_lg_u32 s9, 15
	s_cbranch_scc1 .LBB0_1292
; DI unsigned pack2(float a, float b) { f32x2_t v = {a, b}; return __builtin_bit_cast(unsigned, __builtin_convertvector(v, bf16x2_t)); }
; #define G_TILEMAP(q, MT, NT) do { if (sq) { const int grp_ = (q) >> 5, i_ = (q) & 31; \
;       MT = xcd * mpx + (grp_ & (mpx / 4 - 1)) * 4 + (i_ & 3); NT = (grp_ >> (LMPX - 2)) * 8 + (i_ >> 2); } \
;     else { MT = xcd * mpx + ((q) & (mpx - 1)); NT = (q) >> LMPX; } } while (0)
;     ...
;     if ((s & (nk - 1)) == nk - 1) {
;       const int q = slot + (s >> lnk) * nslots;
;       int mt, nt; G_TILEMAP(q, mt, nt);
;       if (dostore) {
; #pragma unroll
;         for (int mi = 0; mi < 2; ++mi) {
;           const size_t m = (size_t)mt * 256 + wm * 64 + mi * 32 + r;
; #pragma unroll
;           for (int ni = 0; ni < 4; ++ni) {
;             __builtin_amdgcn_sched_barrier(0);
;             if (MODE == 0) {
; #pragma unroll
;               for (int gp = 0; gp < 2; ++gp) {
;                 const int g0 = 2 * gp;
;                 uint2 pa, pb;
;                 pa.x = pack2(acc[mi][ni][4 * g0], acc[mi][ni][4 * g0 + 1]); pa.y = pack2(acc[mi][ni][4 * g0 + 2], acc[mi][ni][4 * g0 + 3]);
;                 pb.x = pack2(acc[mi][ni][4 * g0 + 4], acc[mi][ni][4 * g0 + 5]); pb.y = pack2(acc[mi][ni][4 * g0 + 6], acc[mi][ni][4 * g0 + 7]);
;                 { auto rx = __builtin_amdgcn_permlane32_swap(pa.x, pb.x, false, false); pa.x = rx[0]; pb.x = rx[1]; }
;                 { auto ry = __builtin_amdgcn_permlane32_swap(pa.y, pb.y, false, false); pa.y = ry[0]; pb.y = ry[1]; }
;                 const int col = nt * 256 + wn * 128 + ni * 32 + 8 * g0 + 8 * hh;
;                 const uint4 v4 = make_uint4(pa.x, pa.y, pb.x, pb.y);
;                 if (outp != nullptr && nt >= 32) *(uint4*)(outp + m * 2048 + (col - 8192)) = v4;
;                 else if (col < nvalid) *(uint4*)(C + m * ldc + col) = v4;
	s_lshl_b32 s8, s8, 1
	s_and_b32 s8, s8, 0x7fffffe0
	s_add_i32 s8, s8, s33
	s_lshr_b32 s8, s8, 3
	s_and_b32 s9, s8, 4
	s_or_b32 s9, s9, s47
	s_and_b32 s8, s8, 0xfffff8
	s_lshl_b32 s28, s9, 8
	s_or_b32 s8, s8, s74
	v_lshl_add_u64 v[136:137], v[134:135], 0, s[28:29]
	s_lshl_b32 s8, s8, 8
	v_lshlrev_b64 v[136:137], 13, v[136:137]
	v_or_b32_e32 v128, s8, v141
	v_lshl_add_u64 v[136:137], s[58:59], 0, v[136:137]
	v_cvt_pk_bf16_f32 v112, v112, v113
	v_cvt_pk_bf16_f32 v113, v114, v115
	v_cvt_pk_bf16_f32 v114, v116, v117
	v_cvt_pk_bf16_f32 v115, v118, v119
	s_cmp_lt_u32 s8, 2.0
	v_permlane32_swap_b32_e32 v112, v114
	s_cselect_b64 s[24:25], -1, 0
	s_cmp_gt_u32 s8, 0x3fffffff
	v_permlane32_swap_b32_e32 v113, v115
	s_cbranch_scc1 .LBB0_1296
	v_lshl_add_u64 v[116:117], v[128:129], 1, v[136:137]
	global_store_dwordx4 v[116:117], v[112:115], off
